# GEMM k-loops: all 16 LDS-DMA pieces per iteration in SGPR-base form (base+0x80 kept in a spare SGPR pair), no VALU address arithmetic left in the load stages
# speedup vs baseline: 1.0088x; 1.0010x over previous
; #define PG8_STAGE(bufoff, gbase, voff) do { _Pragma("unroll") for (int _i = 0; _i < 2; ++_i) \
;         __builtin_amdgcn_global_load_lds((const unsigned*)((const char*)(gbase) + (voff)[_i]), (PG8_LAS unsigned*)(lds + (bufoff) + ldsw + _i * 8192), 16, 0, 0); } while (0)
; #define PG8_LDA(dst, b, h) do { _Pragma("unroll") for (int m = 0; m < 4; ++m) _Pragma("unroll") for (int k = 0; k < 2; ++k) dst[m][k] = *(const PG8_LAS bf16x8*)(lds + PG8_SA(b, h) + aoff + m * 2048 + k * 1024); } while (0)
; #define PG8_LDB(dst, b, h) do { _Pragma("unroll") for (int n = 0; n < 2; ++n) _Pragma("unroll") for (int k = 0; k < 2; ++k) dst[n][k] = *(const PG8_LAS bf16x8*)(lds + PG8_SB(b, h) + boff + n * 2048 + k * 1024); } while (0)
; #define PG8_MMA(ai, bj, At, Bt) do { __builtin_amdgcn_s_setprio(1); _Pragma("unroll") for (int m = 0; m < 4; ++m) _Pragma("unroll") for (int n = 0; n < 2; ++n) _Pragma("unroll") for (int k = 0; k < 2; ++k) \
;         acc[ai][bj][m][n] = __builtin_amdgcn_mfma_f32_16x16x32_bf16(Bt[n][k], At[m][k], acc[ai][bj][m][n], 0, 0, 0); __builtin_amdgcn_s_setprio(0); } while (0)
; #define PG8_WAIT_V(n) asm volatile("s_waitcnt vmcnt(" #n ")" ::: "memory")
; #define PG8_BAR __builtin_amdgcn_s_barrier()
; template <class Epi, class Sched, bool ALIGN_EPI = false, bool SP2 = false>
; __device__ __forceinline__ void gemm_phase(PG8_LAS unsigned char* lds, const Gemm g, const Sched& S, const Epi& E) {
;     ...
;         for (int t = 0; t < nt; t += 2) {
;             const bool last = (t == nt - 2);
;             const char* a1 = cA + (size_t)(t + 1) * kstep;
;             const char* a2 = last ? nA : cA + (size_t)(t + 2) * kstep; const char* b2 = last ? nB : cB + (size_t)(t + 2) * kstep;
;             const char* a3 = a2 + kstep; const char* b3 = b2 + kstep;
;             if (last && has_next) S.a_ready(nxt);
;             if constexpr (SP2) {
;             PG8_LDB(B0, 0, 0); PG8_LDB(B1, 0, 1); PG8_SCHED; PG8_LDA(At, 0, 0); PG8_STAGE(PG8_SA(1, 1), a1 + hstep, voffA);
;             PG8_WAIT_V(8); PG8_WAIT_L(0); PG8_BAR; PG8_MMA(0, 0, At, B0); PG8_MMA(0, 1, At, B1); PG8_BAR; PG8_SCHED;
;             PG8_LDA(At, 0, 1); PG8_STAGE(PG8_SB(0, 0), b2, voffB); PG8_STAGE(PG8_SB(0, 1), b2 + hstep, voffB); PG8_STAGE(PG8_SA(0, 0), a2, voffA);
;             PG8_WAIT_V(8); PG8_WAIT_L(0); PG8_BAR; PG8_MMA(1, 0, At, B0); PG8_MMA(1, 1, At, B1); PG8_BAR; PG8_SCHED;
.LBB0_218:
	ds_read_b128 v[148:151], v157
	ds_read_b128 v[166:169], v157 offset:1024
	ds_read_b128 v[172:175], v157 offset:2048
	ds_read_b128 v[176:179], v157 offset:3072
	ds_read_b128 v[180:183], v158
	ds_read_b128 v[184:187], v158 offset:1024
	ds_read_b128 v[188:191], v158 offset:2048
	ds_read_b128 v[196:199], v158 offset:3072
	s_add_u32 s6, s52, 0xfffc0080
	s_addc_u32 s7, s53, -1
	s_cmp_eq_u32 s72, 12
	s_cselect_b32 s57, s4, s7
	s_cselect_b32 s56, s41, s6
	s_cselect_b32 s55, s39, s33
	s_cselect_b32 s54, s78, s79
	s_add_i32 m0, s37, 0xc000
	ds_read_b128 v[200:203], v159
	ds_read_b128 v[204:207], v159 offset:1024
	ds_read_b128 v[208:211], v159 offset:2048
	ds_read_b128 v[212:215], v159 offset:3072
	ds_read_b128 v[216:219], v159 offset:4096
	ds_read_b128 v[220:223], v159 offset:5120
	ds_read_b128 v[224:227], v159 offset:6144
	ds_read_b128 v[228:231], v159 offset:7168
	global_load_lds_dwordx4 v140, s[52:53]
	s_add_i32 m0, s37, 0xe000
	s_nop 0
	global_load_lds_dwordx4 v142, s[52:53]
	s_waitcnt vmcnt(8)
	s_waitcnt lgkmcnt(0)
	s_barrier
	s_waitcnt lgkmcnt(0)
	v_mfma_f32_16x16x32_bf16 v[124:127], v[148:151], v[200:203], v[124:127]
	v_mfma_f32_16x16x32_bf16 v[116:119], v[172:175], v[200:203], v[116:119]
	v_mfma_f32_16x16x32_bf16 v[108:111], v[148:151], v[208:211], v[108:111]
	v_mfma_f32_16x16x32_bf16 v[100:103], v[172:175], v[208:211], v[100:103]
	v_mfma_f32_16x16x32_bf16 v[92:95], v[148:151], v[216:219], v[92:95]
	v_mfma_f32_16x16x32_bf16 v[84:87], v[172:175], v[216:219], v[84:87]
	v_mfma_f32_16x16x32_bf16 v[76:79], v[148:151], v[224:227], v[76:79]
	v_mfma_f32_16x16x32_bf16 v[68:71], v[172:175], v[224:227], v[68:71]
	v_mfma_f32_16x16x32_bf16 v[124:127], v[166:169], v[204:207], v[124:127]
	v_mfma_f32_16x16x32_bf16 v[116:119], v[176:179], v[204:207], v[116:119]
	v_mfma_f32_16x16x32_bf16 v[108:111], v[166:169], v[212:215], v[108:111]
	v_mfma_f32_16x16x32_bf16 v[100:103], v[176:179], v[212:215], v[100:103]
	v_mfma_f32_16x16x32_bf16 v[92:95], v[166:169], v[220:223], v[92:95]
	v_mfma_f32_16x16x32_bf16 v[84:87], v[176:179], v[220:223], v[84:87]
	v_mfma_f32_16x16x32_bf16 v[76:79], v[166:169], v[228:231], v[76:79]
	v_mfma_f32_16x16x32_bf16 v[68:71], v[176:179], v[228:231], v[68:71]
	v_mfma_f32_16x16x32_bf16 v[120:123], v[180:183], v[200:203], v[120:123]
	v_mfma_f32_16x16x32_bf16 v[112:115], v[188:191], v[200:203], v[112:115]
	v_mfma_f32_16x16x32_bf16 v[104:107], v[180:183], v[208:211], v[104:107]
	v_mfma_f32_16x16x32_bf16 v[96:99], v[188:191], v[208:211], v[96:99]
	v_mfma_f32_16x16x32_bf16 v[88:91], v[180:183], v[216:219], v[88:91]
	v_mfma_f32_16x16x32_bf16 v[80:83], v[188:191], v[216:219], v[80:83]
	v_mfma_f32_16x16x32_bf16 v[72:75], v[180:183], v[224:227], v[72:75]
	v_mfma_f32_16x16x32_bf16 v[64:67], v[188:191], v[224:227], v[64:67]
	v_mfma_f32_16x16x32_bf16 v[120:123], v[184:187], v[204:207], v[120:123]
	v_mfma_f32_16x16x32_bf16 v[112:115], v[196:199], v[204:207], v[112:115]
	v_mfma_f32_16x16x32_bf16 v[104:107], v[184:187], v[212:215], v[104:107]
	v_mfma_f32_16x16x32_bf16 v[96:99], v[196:199], v[212:215], v[96:99]
	v_mfma_f32_16x16x32_bf16 v[88:91], v[184:187], v[220:223], v[88:91]
	v_mfma_f32_16x16x32_bf16 v[80:83], v[196:199], v[220:223], v[80:83]
	v_mfma_f32_16x16x32_bf16 v[72:75], v[184:187], v[228:231], v[72:75]
	v_mfma_f32_16x16x32_bf16 v[64:67], v[196:199], v[228:231], v[64:67]
	s_barrier
	s_add_i32 s6, s69, s36
	s_mov_b32 m0, s6
	ds_read_b128 v[200:203], v159 offset:16384
	ds_read_b128 v[204:207], v159 offset:17408
	ds_read_b128 v[208:211], v159 offset:18432
	ds_read_b128 v[212:215], v159 offset:19456
	ds_read_b128 v[216:219], v159 offset:20480
	ds_read_b128 v[220:223], v159 offset:21504
	ds_read_b128 v[224:227], v159 offset:22528
	ds_read_b128 v[228:231], v159 offset:23552
	global_load_lds_dwordx4 v136, s[54:55]
	s_add_i32 m0, s6, 0x2000
	s_add_u32 s6, s54, 0x40000
	s_addc_u32 s7, s55, 0
	s_add_i32 s73, s74, s36
	global_load_lds_dwordx4 v132, s[54:55]
	s_mov_b32 m0, s73
	global_load_lds_dwordx4 v136, s[6:7]
	s_add_i32 m0, s73, 0x2000
	s_nop 0
	global_load_lds_dwordx4 v132, s[6:7]
	s_mov_b32 m0, s37
	s_nop 0
	global_load_lds_dwordx4 v138, s[56:57]
	s_mov_b32 m0, s59
	s_nop 0
	global_load_lds_dwordx4 v134, s[56:57]
	s_waitcnt vmcnt(8)
	s_waitcnt lgkmcnt(0)
	s_barrier
	s_waitcnt lgkmcnt(0)
	v_mfma_f32_16x16x32_bf16 v[60:63], v[148:151], v[200:203], v[60:63]
	v_mfma_f32_16x16x32_bf16 v[52:55], v[172:175], v[200:203], v[52:55]
	v_mfma_f32_16x16x32_bf16 v[44:47], v[148:151], v[208:211], v[44:47]
	v_mfma_f32_16x16x32_bf16 v[36:39], v[172:175], v[208:211], v[36:39]
	v_mfma_f32_16x16x32_bf16 v[28:31], v[148:151], v[216:219], v[28:31]
	v_mfma_f32_16x16x32_bf16 v[20:23], v[172:175], v[216:219], v[20:23]
	v_mfma_f32_16x16x32_bf16 v[12:15], v[148:151], v[224:227], v[12:15]
	v_mfma_f32_16x16x32_bf16 v[4:7], v[172:175], v[224:227], v[4:7]
	v_mfma_f32_16x16x32_bf16 v[60:63], v[166:169], v[204:207], v[60:63]
	v_mfma_f32_16x16x32_bf16 v[52:55], v[176:179], v[204:207], v[52:55]
	v_mfma_f32_16x16x32_bf16 v[44:47], v[166:169], v[212:215], v[44:47]
	v_mfma_f32_16x16x32_bf16 v[36:39], v[176:179], v[212:215], v[36:39]
	v_mfma_f32_16x16x32_bf16 v[28:31], v[166:169], v[220:223], v[28:31]
	v_mfma_f32_16x16x32_bf16 v[20:23], v[176:179], v[220:223], v[20:23]
	v_mfma_f32_16x16x32_bf16 v[12:15], v[166:169], v[228:231], v[12:15]
	v_mfma_f32_16x16x32_bf16 v[4:7], v[176:179], v[228:231], v[4:7]
	v_mfma_f32_16x16x32_bf16 v[56:59], v[180:183], v[200:203], v[56:59]
	v_mfma_f32_16x16x32_bf16 v[48:51], v[188:191], v[200:203], v[48:51]
	v_mfma_f32_16x16x32_bf16 v[40:43], v[180:183], v[208:211], v[40:43]
	v_mfma_f32_16x16x32_bf16 v[32:35], v[188:191], v[208:211], v[32:35]
	v_mfma_f32_16x16x32_bf16 v[24:27], v[180:183], v[216:219], v[24:27]
	v_mfma_f32_16x16x32_bf16 v[16:19], v[188:191], v[216:219], v[16:19]
	v_mfma_f32_16x16x32_bf16 v[8:11], v[180:183], v[224:227], v[8:11]
	v_mfma_f32_16x16x32_bf16 v[0:3], v[188:191], v[224:227], v[0:3]
	v_mfma_f32_16x16x32_bf16 v[56:59], v[184:187], v[204:207], v[56:59]
	v_mfma_f32_16x16x32_bf16 v[48:51], v[196:199], v[204:207], v[48:51]
	v_mfma_f32_16x16x32_bf16 v[40:43], v[184:187], v[212:215], v[40:43]
	v_mfma_f32_16x16x32_bf16 v[32:35], v[196:199], v[212:215], v[32:35]
	v_mfma_f32_16x16x32_bf16 v[24:27], v[184:187], v[220:223], v[24:27]
	v_mfma_f32_16x16x32_bf16 v[16:19], v[196:199], v[220:223], v[16:19]
	v_mfma_f32_16x16x32_bf16 v[8:11], v[184:187], v[228:231], v[8:11]
	v_mfma_f32_16x16x32_bf16 v[0:3], v[196:199], v[228:231], v[0:3]
	s_barrier
; #define PG8_STAGE(bufoff, gbase, voff) do { _Pragma("unroll") for (int _i = 0; _i < 2; ++_i) \
;         __builtin_amdgcn_global_load_lds((const unsigned*)((const char*)(gbase) + (voff)[_i]), (PG8_LAS unsigned*)(lds + (bufoff) + ldsw + _i * 8192), 16, 0, 0); } while (0)
; #define PG8_LDA(dst, b, h) do { _Pragma("unroll") for (int m = 0; m < 4; ++m) _Pragma("unroll") for (int k = 0; k < 2; ++k) dst[m][k] = *(const PG8_LAS bf16x8*)(lds + PG8_SA(b, h) + aoff + m * 2048 + k * 1024); } while (0)
; #define PG8_LDB(dst, b, h) do { _Pragma("unroll") for (int n = 0; n < 2; ++n) _Pragma("unroll") for (int k = 0; k < 2; ++k) dst[n][k] = *(const PG8_LAS bf16x8*)(lds + PG8_SB(b, h) + boff + n * 2048 + k * 1024); } while (0)
; #define PG8_MMA(ai, bj, At, Bt) do { __builtin_amdgcn_s_setprio(1); _Pragma("unroll") for (int m = 0; m < 4; ++m) _Pragma("unroll") for (int n = 0; n < 2; ++n) _Pragma("unroll") for (int k = 0; k < 2; ++k) \
;         acc[ai][bj][m][n] = __builtin_amdgcn_mfma_f32_16x16x32_bf16(Bt[n][k], At[m][k], acc[ai][bj][m][n], 0, 0, 0); __builtin_amdgcn_s_setprio(0); } while (0)
; #define PG8_WAIT_V(n) asm volatile("s_waitcnt vmcnt(" #n ")" ::: "memory")
; #define PG8_WAIT_L(n) asm volatile("s_waitcnt lgkmcnt(" #n ")" ::: "memory")
; #define PG8_BAR __builtin_amdgcn_s_barrier()
; #define PG8_SCHED __builtin_amdgcn_sched_barrier(0)
; template <class Epi, class Sched, bool ALIGN_EPI = false, bool SP2 = false>
; __device__ __forceinline__ void gemm_phase(PG8_LAS unsigned char* lds, const Gemm g, const Sched& S, const Epi& E) {
;     ...
;         for (int t = 0; t < nt; t += 2) {
;             const bool last = (t == nt - 2);
;     ...
;             PG8_LDB(B0, 1, 0); PG8_LDB(B1, 1, 1); PG8_SCHED; PG8_LDA(At, 1, 0); PG8_STAGE(PG8_SA(0, 1), a2 + hstep, voffA);
;             PG8_WAIT_V(8); PG8_WAIT_L(0); PG8_BAR; PG8_MMA(0, 0, At, B0); PG8_MMA(0, 1, At, B1); PG8_BAR; PG8_SCHED;
;             PG8_LDA(At, 1, 1); PG8_STAGE(PG8_SB(1, 0), b3, voffB); PG8_STAGE(PG8_SB(1, 1), b3 + hstep, voffB); PG8_STAGE(PG8_SA(1, 0), a3, voffA);
;             PG8_WAIT_V(8); PG8_WAIT_L(0); PG8_BAR; PG8_MMA(1, 0, At, B0); PG8_MMA(1, 1, At, B1); PG8_BAR; PG8_SCHED;
	s_add_i32 s73, 0, 0x18000
	v_add_u32_e32 v161, s73, v154
	s_add_i32 s80, 0, 0x1c000
	ds_read_b128 v[148:151], v161
	ds_read_b128 v[166:169], v161 offset:1024
	ds_read_b128 v[172:175], v161 offset:2048
	ds_read_b128 v[176:179], v161 offset:3072
	v_add_u32_e32 v161, s80, v154
	ds_read_b128 v[180:183], v161
	ds_read_b128 v[184:187], v161 offset:1024
	ds_read_b128 v[188:191], v161 offset:2048
	ds_read_b128 v[196:199], v161 offset:3072
	s_add_u32 s6, s56, 0x40000
	s_addc_u32 s7, s57, 0
	s_mov_b32 m0, s60
	ds_read_b128 v[200:203], v159 offset:32768
	ds_read_b128 v[204:207], v159 offset:33792
	ds_read_b128 v[208:211], v159 offset:34816
	ds_read_b128 v[212:215], v159 offset:35840
	ds_read_b128 v[216:219], v159 offset:36864
	ds_read_b128 v[220:223], v159 offset:37888
	ds_read_b128 v[224:227], v159 offset:38912
	ds_read_b128 v[228:231], v159 offset:39936
	global_load_lds_dwordx4 v138, s[6:7]
	s_mov_b32 m0, s61
	s_nop 0
	global_load_lds_dwordx4 v134, s[6:7]
	s_waitcnt vmcnt(8)
	s_waitcnt lgkmcnt(0)
	s_barrier
	s_waitcnt lgkmcnt(0)
	v_mfma_f32_16x16x32_bf16 v[124:127], v[148:151], v[200:203], v[124:127]
	v_mfma_f32_16x16x32_bf16 v[116:119], v[172:175], v[200:203], v[116:119]
	v_mfma_f32_16x16x32_bf16 v[108:111], v[148:151], v[208:211], v[108:111]
	v_mfma_f32_16x16x32_bf16 v[100:103], v[172:175], v[208:211], v[100:103]
	v_mfma_f32_16x16x32_bf16 v[92:95], v[148:151], v[216:219], v[92:95]
	v_mfma_f32_16x16x32_bf16 v[84:87], v[172:175], v[216:219], v[84:87]
	v_mfma_f32_16x16x32_bf16 v[76:79], v[148:151], v[224:227], v[76:79]
	v_mfma_f32_16x16x32_bf16 v[68:71], v[172:175], v[224:227], v[68:71]
	v_mfma_f32_16x16x32_bf16 v[124:127], v[166:169], v[204:207], v[124:127]
	v_mfma_f32_16x16x32_bf16 v[116:119], v[176:179], v[204:207], v[116:119]
	v_mfma_f32_16x16x32_bf16 v[108:111], v[166:169], v[212:215], v[108:111]
	v_mfma_f32_16x16x32_bf16 v[100:103], v[176:179], v[212:215], v[100:103]
	v_mfma_f32_16x16x32_bf16 v[92:95], v[166:169], v[220:223], v[92:95]
	v_mfma_f32_16x16x32_bf16 v[84:87], v[176:179], v[220:223], v[84:87]
	v_mfma_f32_16x16x32_bf16 v[76:79], v[166:169], v[228:231], v[76:79]
	v_mfma_f32_16x16x32_bf16 v[68:71], v[176:179], v[228:231], v[68:71]
	v_mfma_f32_16x16x32_bf16 v[120:123], v[180:183], v[200:203], v[120:123]
	v_mfma_f32_16x16x32_bf16 v[112:115], v[188:191], v[200:203], v[112:115]
	v_mfma_f32_16x16x32_bf16 v[104:107], v[180:183], v[208:211], v[104:107]
	v_mfma_f32_16x16x32_bf16 v[96:99], v[188:191], v[208:211], v[96:99]
	v_mfma_f32_16x16x32_bf16 v[88:91], v[180:183], v[216:219], v[88:91]
	v_mfma_f32_16x16x32_bf16 v[80:83], v[188:191], v[216:219], v[80:83]
	v_mfma_f32_16x16x32_bf16 v[72:75], v[180:183], v[224:227], v[72:75]
	v_mfma_f32_16x16x32_bf16 v[64:67], v[188:191], v[224:227], v[64:67]
	v_mfma_f32_16x16x32_bf16 v[120:123], v[184:187], v[204:207], v[120:123]
	v_mfma_f32_16x16x32_bf16 v[112:115], v[196:199], v[204:207], v[112:115]
	v_mfma_f32_16x16x32_bf16 v[104:107], v[184:187], v[212:215], v[104:107]
	v_mfma_f32_16x16x32_bf16 v[96:99], v[196:199], v[212:215], v[96:99]
	v_mfma_f32_16x16x32_bf16 v[88:91], v[184:187], v[220:223], v[88:91]
	v_mfma_f32_16x16x32_bf16 v[80:83], v[196:199], v[220:223], v[80:83]
	v_mfma_f32_16x16x32_bf16 v[72:75], v[184:187], v[228:231], v[72:75]
	v_mfma_f32_16x16x32_bf16 v[64:67], v[196:199], v[228:231], v[64:67]
	s_barrier
	s_add_i32 s6, s73, s36
	s_add_u32 s98, s54, 0x80
	s_addc_u32 s99, s55, 0
	s_add_u32 s100, s56, 0x80
	s_addc_u32 s101, s57, 0
	s_mov_b32 m0, s6
	ds_read_b128 v[200:203], v159 offset:49152
	ds_read_b128 v[204:207], v159 offset:50176
	ds_read_b128 v[208:211], v159 offset:51200
	ds_read_b128 v[212:215], v159 offset:52224
	ds_read_b128 v[216:219], v159 offset:53248
	ds_read_b128 v[220:223], v159 offset:54272
	ds_read_b128 v[224:227], v159 offset:55296
	ds_read_b128 v[228:231], v159 offset:56320
	global_load_lds_dwordx4 v136, s[98:99]
	s_add_i32 m0, s6, 0x2000
	s_add_u32 s6, s54, 0x40080
	s_addc_u32 s7, s55, 0
	s_add_i32 s54, s80, s36
	global_load_lds_dwordx4 v132, s[98:99]
	s_mov_b32 m0, s54
	s_nop 0
	global_load_lds_dwordx4 v136, s[6:7]
	s_add_i32 m0, s54, 0x2000
	s_nop 0
	global_load_lds_dwordx4 v132, s[6:7]
	s_mov_b32 m0, s67
	s_nop 0
	global_load_lds_dwordx4 v138, s[100:101]
	s_mov_b32 m0, s68
	s_nop 0
	global_load_lds_dwordx4 v134, s[100:101]
	s_waitcnt vmcnt(8)
	s_waitcnt lgkmcnt(0)
	s_barrier
	s_waitcnt lgkmcnt(0)
	v_mfma_f32_16x16x32_bf16 v[60:63], v[148:151], v[200:203], v[60:63]
	v_mfma_f32_16x16x32_bf16 v[52:55], v[172:175], v[200:203], v[52:55]
	v_mfma_f32_16x16x32_bf16 v[44:47], v[148:151], v[208:211], v[44:47]
	v_mfma_f32_16x16x32_bf16 v[36:39], v[172:175], v[208:211], v[36:39]
	v_mfma_f32_16x16x32_bf16 v[28:31], v[148:151], v[216:219], v[28:31]
	v_mfma_f32_16x16x32_bf16 v[20:23], v[172:175], v[216:219], v[20:23]
	v_mfma_f32_16x16x32_bf16 v[12:15], v[148:151], v[224:227], v[12:15]
	v_mfma_f32_16x16x32_bf16 v[4:7], v[172:175], v[224:227], v[4:7]
	v_mfma_f32_16x16x32_bf16 v[60:63], v[166:169], v[204:207], v[60:63]
	v_mfma_f32_16x16x32_bf16 v[52:55], v[176:179], v[204:207], v[52:55]
	v_mfma_f32_16x16x32_bf16 v[44:47], v[166:169], v[212:215], v[44:47]
	v_mfma_f32_16x16x32_bf16 v[36:39], v[176:179], v[212:215], v[36:39]
	v_mfma_f32_16x16x32_bf16 v[28:31], v[166:169], v[220:223], v[28:31]
	v_mfma_f32_16x16x32_bf16 v[20:23], v[176:179], v[220:223], v[20:23]
	v_mfma_f32_16x16x32_bf16 v[12:15], v[166:169], v[228:231], v[12:15]
	v_mfma_f32_16x16x32_bf16 v[4:7], v[176:179], v[228:231], v[4:7]
	v_mfma_f32_16x16x32_bf16 v[56:59], v[180:183], v[200:203], v[56:59]
	v_mfma_f32_16x16x32_bf16 v[48:51], v[188:191], v[200:203], v[48:51]
	v_mfma_f32_16x16x32_bf16 v[40:43], v[180:183], v[208:211], v[40:43]
	v_mfma_f32_16x16x32_bf16 v[32:35], v[188:191], v[208:211], v[32:35]
	v_mfma_f32_16x16x32_bf16 v[24:27], v[180:183], v[216:219], v[24:27]
	v_mfma_f32_16x16x32_bf16 v[16:19], v[188:191], v[216:219], v[16:19]
	v_mfma_f32_16x16x32_bf16 v[8:11], v[180:183], v[224:227], v[8:11]
	v_mfma_f32_16x16x32_bf16 v[0:3], v[188:191], v[224:227], v[0:3]
	v_mfma_f32_16x16x32_bf16 v[56:59], v[184:187], v[204:207], v[56:59]
	v_mfma_f32_16x16x32_bf16 v[48:51], v[196:199], v[204:207], v[48:51]
	v_mfma_f32_16x16x32_bf16 v[40:43], v[184:187], v[212:215], v[40:43]
	v_mfma_f32_16x16x32_bf16 v[32:35], v[196:199], v[212:215], v[32:35]
	v_mfma_f32_16x16x32_bf16 v[24:27], v[184:187], v[220:223], v[24:27]
	v_mfma_f32_16x16x32_bf16 v[16:19], v[196:199], v[220:223], v[16:19]
	v_mfma_f32_16x16x32_bf16 v[8:11], v[184:187], v[228:231], v[8:11]
	v_mfma_f32_16x16x32_bf16 v[0:3], v[196:199], v[228:231], v[0:3]
	s_barrier
	s_add_i32 s72, s72, 2
	s_add_u32 s52, s52, 0x100
	s_addc_u32 s53, s53, 0
	s_add_u32 s79, s79, 0x100
	s_addc_u32 s33, s33, 0
	s_cmp_gt_u32 s72, 13
	s_cbranch_scc0 .LBB0_218
	s_and_b64 vcc, exec, s[34:35]
	s_cbranch_vccz .LBB0_221
	s_barrier

; #define PG8_STAGE(bufoff, gbase, voff) do { _Pragma("unroll") for (int _i = 0; _i < 2; ++_i) \
;         __builtin_amdgcn_global_load_lds((const unsigned*)((const char*)(gbase) + (voff)[_i]), (PG8_LAS unsigned*)(lds + (bufoff) + ldsw + _i * 8192), 16, 0, 0); } while (0)
; #define PG8_LDA(dst, b, h) do { _Pragma("unroll") for (int m = 0; m < 4; ++m) _Pragma("unroll") for (int k = 0; k < 2; ++k) dst[m][k] = *(const PG8_LAS bf16x8*)(lds + PG8_SA(b, h) + aoff + m * 2048 + k * 1024); } while (0)
; #define PG8_LDB(dst, b, h) do { _Pragma("unroll") for (int n = 0; n < 2; ++n) _Pragma("unroll") for (int k = 0; k < 2; ++k) dst[n][k] = *(const PG8_LAS bf16x8*)(lds + PG8_SB(b, h) + boff + n * 2048 + k * 1024); } while (0)
; #define PG8_MMA(ai, bj, At, Bt) do { __builtin_amdgcn_s_setprio(1); _Pragma("unroll") for (int m = 0; m < 4; ++m) _Pragma("unroll") for (int n = 0; n < 2; ++n) _Pragma("unroll") for (int k = 0; k < 2; ++k) \
;         acc[ai][bj][m][n] = __builtin_amdgcn_mfma_f32_16x16x32_bf16(Bt[n][k], At[m][k], acc[ai][bj][m][n], 0, 0, 0); __builtin_amdgcn_s_setprio(0); } while (0)
; #define PG8_WAIT_V(n) asm volatile("s_waitcnt vmcnt(" #n ")" ::: "memory")
; #define PG8_BAR __builtin_amdgcn_s_barrier()
; template <class Epi, class Sched, bool ALIGN_EPI = false, bool SP2 = false>
; __device__ __forceinline__ void gemm_phase(PG8_LAS unsigned char* lds, const Gemm g, const Sched& S, const Epi& E) {
;     ...
;         for (int t = 0; t < nt; t += 2) {
;             const bool last = (t == nt - 2);
;             const char* a1 = cA + (size_t)(t + 1) * kstep;
;             const char* a2 = last ? nA : cA + (size_t)(t + 2) * kstep; const char* b2 = last ? nB : cB + (size_t)(t + 2) * kstep;
;             const char* a3 = a2 + kstep; const char* b3 = b2 + kstep;
;             if (last && has_next) S.a_ready(nxt);
;             if constexpr (SP2) {
;             PG8_LDB(B0, 0, 0); PG8_LDB(B1, 0, 1); PG8_SCHED; PG8_LDA(At, 0, 0); PG8_STAGE(PG8_SA(1, 1), a1 + hstep, voffA);
;             PG8_WAIT_V(8); PG8_WAIT_L(0); PG8_BAR; PG8_MMA(0, 0, At, B0); PG8_MMA(0, 1, At, B1); PG8_BAR; PG8_SCHED;
;             PG8_LDA(At, 0, 1); PG8_STAGE(PG8_SB(0, 0), b2, voffB); PG8_STAGE(PG8_SB(0, 1), b2 + hstep, voffB); PG8_STAGE(PG8_SA(0, 0), a2, voffA);
;             PG8_WAIT_V(8); PG8_WAIT_L(0); PG8_BAR; PG8_MMA(1, 0, At, B0); PG8_MMA(1, 1, At, B1); PG8_BAR; PG8_SCHED;
.LBB0_323:
	ds_read_b128 v[148:151], v156
	ds_read_b128 v[166:169], v156 offset:1024
	ds_read_b128 v[172:175], v156 offset:2048
	ds_read_b128 v[176:179], v156 offset:3072
	ds_read_b128 v[180:183], v157
	ds_read_b128 v[184:187], v157 offset:1024
	ds_read_b128 v[188:191], v157 offset:2048
	ds_read_b128 v[196:199], v157 offset:3072
	s_add_u32 s56, s54, 0x100
	s_addc_u32 s57, s55, 0
	s_cmp_eq_u32 s69, 40
	s_cselect_b32 s61, s51, s57
	s_cselect_b32 s60, s50, s56
	s_cselect_b32 s59, s53, s33
	s_cselect_b32 s58, s52, s4
	s_add_i32 m0, s37, 0xc000
	ds_read_b128 v[200:203], v158
	ds_read_b128 v[204:207], v158 offset:1024
	ds_read_b128 v[208:211], v158 offset:2048
	ds_read_b128 v[212:215], v158 offset:3072
	ds_read_b128 v[216:219], v158 offset:4096
	ds_read_b128 v[220:223], v158 offset:5120
	ds_read_b128 v[224:227], v158 offset:6144
	ds_read_b128 v[228:231], v158 offset:7168
	global_load_lds_dwordx4 v140, s[54:55]
	s_add_i32 m0, s37, 0xe000
	s_nop 0
	global_load_lds_dwordx4 v142, s[54:55]
	s_waitcnt vmcnt(8)
	s_waitcnt lgkmcnt(0)
	s_barrier
	s_waitcnt lgkmcnt(0)
	v_mfma_f32_16x16x32_bf16 v[124:127], v[148:151], v[200:203], v[124:127]
	v_mfma_f32_16x16x32_bf16 v[120:123], v[172:175], v[200:203], v[120:123]
	v_mfma_f32_16x16x32_bf16 v[108:111], v[148:151], v[208:211], v[108:111]
	v_mfma_f32_16x16x32_bf16 v[104:107], v[172:175], v[208:211], v[104:107]
	v_mfma_f32_16x16x32_bf16 v[92:95], v[148:151], v[216:219], v[92:95]
	v_mfma_f32_16x16x32_bf16 v[88:91], v[172:175], v[216:219], v[88:91]
	v_mfma_f32_16x16x32_bf16 v[76:79], v[148:151], v[224:227], v[76:79]
	v_mfma_f32_16x16x32_bf16 v[72:75], v[172:175], v[224:227], v[72:75]
	v_mfma_f32_16x16x32_bf16 v[124:127], v[166:169], v[204:207], v[124:127]
	v_mfma_f32_16x16x32_bf16 v[120:123], v[176:179], v[204:207], v[120:123]
	v_mfma_f32_16x16x32_bf16 v[108:111], v[166:169], v[212:215], v[108:111]
	v_mfma_f32_16x16x32_bf16 v[104:107], v[176:179], v[212:215], v[104:107]
	v_mfma_f32_16x16x32_bf16 v[92:95], v[166:169], v[220:223], v[92:95]
	v_mfma_f32_16x16x32_bf16 v[88:91], v[176:179], v[220:223], v[88:91]
	v_mfma_f32_16x16x32_bf16 v[76:79], v[166:169], v[228:231], v[76:79]
	v_mfma_f32_16x16x32_bf16 v[72:75], v[176:179], v[228:231], v[72:75]
	v_mfma_f32_16x16x32_bf16 v[116:119], v[180:183], v[200:203], v[116:119]
	v_mfma_f32_16x16x32_bf16 v[112:115], v[188:191], v[200:203], v[112:115]
	v_mfma_f32_16x16x32_bf16 v[100:103], v[180:183], v[208:211], v[100:103]
	v_mfma_f32_16x16x32_bf16 v[96:99], v[188:191], v[208:211], v[96:99]
	v_mfma_f32_16x16x32_bf16 v[84:87], v[180:183], v[216:219], v[84:87]
	v_mfma_f32_16x16x32_bf16 v[80:83], v[188:191], v[216:219], v[80:83]
	v_mfma_f32_16x16x32_bf16 v[68:71], v[180:183], v[224:227], v[68:71]
	v_mfma_f32_16x16x32_bf16 v[64:67], v[188:191], v[224:227], v[64:67]
	v_mfma_f32_16x16x32_bf16 v[116:119], v[184:187], v[204:207], v[116:119]
	v_mfma_f32_16x16x32_bf16 v[112:115], v[196:199], v[204:207], v[112:115]
	v_mfma_f32_16x16x32_bf16 v[100:103], v[184:187], v[212:215], v[100:103]
	v_mfma_f32_16x16x32_bf16 v[96:99], v[196:199], v[212:215], v[96:99]
	v_mfma_f32_16x16x32_bf16 v[84:87], v[184:187], v[220:223], v[84:87]
	v_mfma_f32_16x16x32_bf16 v[80:83], v[196:199], v[220:223], v[80:83]
	v_mfma_f32_16x16x32_bf16 v[68:71], v[184:187], v[228:231], v[68:71]
	v_mfma_f32_16x16x32_bf16 v[64:67], v[196:199], v[228:231], v[64:67]
	s_barrier
	s_add_i32 s6, s74, s36
	s_mov_b32 m0, s6
	ds_read_b128 v[200:203], v158 offset:16384
	ds_read_b128 v[204:207], v158 offset:17408
	ds_read_b128 v[208:211], v158 offset:18432
	ds_read_b128 v[212:215], v158 offset:19456
	ds_read_b128 v[216:219], v158 offset:20480
	ds_read_b128 v[220:223], v158 offset:21504
	ds_read_b128 v[224:227], v158 offset:22528
	ds_read_b128 v[228:231], v158 offset:23552
	global_load_lds_dwordx4 v134, s[58:59]
	s_add_i32 m0, s6, 0x2000
	s_add_u32 s54, s58, 0xb0000
	s_addc_u32 s55, s59, 0
	s_add_i32 s6, s75, s36
	global_load_lds_dwordx4 v138, s[58:59]
	s_mov_b32 m0, s6
	global_load_lds_dwordx4 v134, s[54:55]
	s_add_i32 m0, s6, 0x2000
	s_nop 0
	global_load_lds_dwordx4 v138, s[54:55]
	s_mov_b32 m0, s37
	s_nop 0
	global_load_lds_dwordx4 v132, s[60:61]
	s_mov_b32 m0, s30
	s_nop 0
	global_load_lds_dwordx4 v136, s[60:61]
	s_waitcnt vmcnt(8)
	s_waitcnt lgkmcnt(0)
	s_barrier
	s_waitcnt lgkmcnt(0)
	v_mfma_f32_16x16x32_bf16 v[60:63], v[148:151], v[200:203], v[60:63]
	v_mfma_f32_16x16x32_bf16 v[56:59], v[172:175], v[200:203], v[56:59]
	v_mfma_f32_16x16x32_bf16 v[44:47], v[148:151], v[208:211], v[44:47]
	v_mfma_f32_16x16x32_bf16 v[40:43], v[172:175], v[208:211], v[40:43]
	v_mfma_f32_16x16x32_bf16 v[28:31], v[148:151], v[216:219], v[28:31]
	v_mfma_f32_16x16x32_bf16 v[24:27], v[172:175], v[216:219], v[24:27]
	v_mfma_f32_16x16x32_bf16 v[12:15], v[148:151], v[224:227], v[12:15]
	v_mfma_f32_16x16x32_bf16 v[8:11], v[172:175], v[224:227], v[8:11]
	v_mfma_f32_16x16x32_bf16 v[60:63], v[166:169], v[204:207], v[60:63]
	v_mfma_f32_16x16x32_bf16 v[56:59], v[176:179], v[204:207], v[56:59]
	v_mfma_f32_16x16x32_bf16 v[44:47], v[166:169], v[212:215], v[44:47]
	v_mfma_f32_16x16x32_bf16 v[40:43], v[176:179], v[212:215], v[40:43]
	v_mfma_f32_16x16x32_bf16 v[28:31], v[166:169], v[220:223], v[28:31]
	v_mfma_f32_16x16x32_bf16 v[24:27], v[176:179], v[220:223], v[24:27]
	v_mfma_f32_16x16x32_bf16 v[12:15], v[166:169], v[228:231], v[12:15]
	v_mfma_f32_16x16x32_bf16 v[8:11], v[176:179], v[228:231], v[8:11]
	v_mfma_f32_16x16x32_bf16 v[52:55], v[180:183], v[200:203], v[52:55]
	v_mfma_f32_16x16x32_bf16 v[48:51], v[188:191], v[200:203], v[48:51]
	v_mfma_f32_16x16x32_bf16 v[36:39], v[180:183], v[208:211], v[36:39]
	v_mfma_f32_16x16x32_bf16 v[32:35], v[188:191], v[208:211], v[32:35]
	v_mfma_f32_16x16x32_bf16 v[20:23], v[180:183], v[216:219], v[20:23]
	v_mfma_f32_16x16x32_bf16 v[16:19], v[188:191], v[216:219], v[16:19]
	v_mfma_f32_16x16x32_bf16 v[4:7], v[180:183], v[224:227], v[4:7]
	v_mfma_f32_16x16x32_bf16 v[0:3], v[188:191], v[224:227], v[0:3]
	v_mfma_f32_16x16x32_bf16 v[52:55], v[184:187], v[204:207], v[52:55]
	v_mfma_f32_16x16x32_bf16 v[48:51], v[196:199], v[204:207], v[48:51]
	v_mfma_f32_16x16x32_bf16 v[36:39], v[184:187], v[212:215], v[36:39]
	v_mfma_f32_16x16x32_bf16 v[32:35], v[196:199], v[212:215], v[32:35]
	v_mfma_f32_16x16x32_bf16 v[20:23], v[184:187], v[220:223], v[20:23]
	v_mfma_f32_16x16x32_bf16 v[16:19], v[196:199], v[220:223], v[16:19]
	v_mfma_f32_16x16x32_bf16 v[4:7], v[184:187], v[228:231], v[4:7]
	v_mfma_f32_16x16x32_bf16 v[0:3], v[196:199], v[228:231], v[0:3]
	s_barrier
; #define PG8_STAGE(bufoff, gbase, voff) do { _Pragma("unroll") for (int _i = 0; _i < 2; ++_i) \
;         __builtin_amdgcn_global_load_lds((const unsigned*)((const char*)(gbase) + (voff)[_i]), (PG8_LAS unsigned*)(lds + (bufoff) + ldsw + _i * 8192), 16, 0, 0); } while (0)
; #define PG8_LDA(dst, b, h) do { _Pragma("unroll") for (int m = 0; m < 4; ++m) _Pragma("unroll") for (int k = 0; k < 2; ++k) dst[m][k] = *(const PG8_LAS bf16x8*)(lds + PG8_SA(b, h) + aoff + m * 2048 + k * 1024); } while (0)
; #define PG8_LDB(dst, b, h) do { _Pragma("unroll") for (int n = 0; n < 2; ++n) _Pragma("unroll") for (int k = 0; k < 2; ++k) dst[n][k] = *(const PG8_LAS bf16x8*)(lds + PG8_SB(b, h) + boff + n * 2048 + k * 1024); } while (0)
; #define PG8_MMA(ai, bj, At, Bt) do { __builtin_amdgcn_s_setprio(1); _Pragma("unroll") for (int m = 0; m < 4; ++m) _Pragma("unroll") for (int n = 0; n < 2; ++n) _Pragma("unroll") for (int k = 0; k < 2; ++k) \
;         acc[ai][bj][m][n] = __builtin_amdgcn_mfma_f32_16x16x32_bf16(Bt[n][k], At[m][k], acc[ai][bj][m][n], 0, 0, 0); __builtin_amdgcn_s_setprio(0); } while (0)
; #define PG8_WAIT_V(n) asm volatile("s_waitcnt vmcnt(" #n ")" ::: "memory")
; #define PG8_WAIT_L(n) asm volatile("s_waitcnt lgkmcnt(" #n ")" ::: "memory")
; #define PG8_BAR __builtin_amdgcn_s_barrier()
; #define PG8_SCHED __builtin_amdgcn_sched_barrier(0)
; template <class Epi, class Sched, bool ALIGN_EPI = false, bool SP2 = false>
; __device__ __forceinline__ void gemm_phase(PG8_LAS unsigned char* lds, const Gemm g, const Sched& S, const Epi& E) {
;     ...
;         for (int t = 0; t < nt; t += 2) {
;             const bool last = (t == nt - 2);
;     ...
;             PG8_LDB(B0, 1, 0); PG8_LDB(B1, 1, 1); PG8_SCHED; PG8_LDA(At, 1, 0); PG8_STAGE(PG8_SA(0, 1), a2 + hstep, voffA);
;             PG8_WAIT_V(8); PG8_WAIT_L(0); PG8_BAR; PG8_MMA(0, 0, At, B0); PG8_MMA(0, 1, At, B1); PG8_BAR; PG8_SCHED;
;             PG8_LDA(At, 1, 1); PG8_STAGE(PG8_SB(1, 0), b3, voffB); PG8_STAGE(PG8_SB(1, 1), b3 + hstep, voffB); PG8_STAGE(PG8_SA(1, 0), a3, voffA);
;             PG8_WAIT_V(8); PG8_WAIT_L(0); PG8_BAR; PG8_MMA(1, 0, At, B0); PG8_MMA(1, 1, At, B1); PG8_BAR; PG8_SCHED;
	s_add_i32 s6, 0, 0x18000
	v_add_u32_e32 v161, s6, v154
	s_add_i32 s7, 0, 0x1c000
	ds_read_b128 v[148:151], v161
	ds_read_b128 v[166:169], v161 offset:1024
	ds_read_b128 v[172:175], v161 offset:2048
	ds_read_b128 v[176:179], v161 offset:3072
	v_add_u32_e32 v161, s7, v154
	ds_read_b128 v[180:183], v161
	ds_read_b128 v[184:187], v161 offset:1024
	ds_read_b128 v[188:191], v161 offset:2048
	ds_read_b128 v[196:199], v161 offset:3072
	s_add_u32 s54, s60, 0xb0000
	s_addc_u32 s55, s61, 0
	s_mov_b32 m0, s31
	ds_read_b128 v[200:203], v158 offset:32768
	ds_read_b128 v[204:207], v158 offset:33792
	ds_read_b128 v[208:211], v158 offset:34816
	ds_read_b128 v[212:215], v158 offset:35840
	ds_read_b128 v[216:219], v158 offset:36864
	ds_read_b128 v[220:223], v158 offset:37888
	ds_read_b128 v[224:227], v158 offset:38912
	ds_read_b128 v[228:231], v158 offset:39936
	global_load_lds_dwordx4 v132, s[54:55]
	s_mov_b32 m0, s76
	s_nop 0
	global_load_lds_dwordx4 v136, s[54:55]
	s_waitcnt vmcnt(8)
	s_waitcnt lgkmcnt(0)
	s_barrier
	s_waitcnt lgkmcnt(0)
	v_mfma_f32_16x16x32_bf16 v[124:127], v[148:151], v[200:203], v[124:127]
	v_mfma_f32_16x16x32_bf16 v[120:123], v[172:175], v[200:203], v[120:123]
	v_mfma_f32_16x16x32_bf16 v[108:111], v[148:151], v[208:211], v[108:111]
	v_mfma_f32_16x16x32_bf16 v[104:107], v[172:175], v[208:211], v[104:107]
	v_mfma_f32_16x16x32_bf16 v[92:95], v[148:151], v[216:219], v[92:95]
	v_mfma_f32_16x16x32_bf16 v[88:91], v[172:175], v[216:219], v[88:91]
	v_mfma_f32_16x16x32_bf16 v[76:79], v[148:151], v[224:227], v[76:79]
	v_mfma_f32_16x16x32_bf16 v[72:75], v[172:175], v[224:227], v[72:75]
	v_mfma_f32_16x16x32_bf16 v[124:127], v[166:169], v[204:207], v[124:127]
	v_mfma_f32_16x16x32_bf16 v[120:123], v[176:179], v[204:207], v[120:123]
	v_mfma_f32_16x16x32_bf16 v[108:111], v[166:169], v[212:215], v[108:111]
	v_mfma_f32_16x16x32_bf16 v[104:107], v[176:179], v[212:215], v[104:107]
	v_mfma_f32_16x16x32_bf16 v[92:95], v[166:169], v[220:223], v[92:95]
	v_mfma_f32_16x16x32_bf16 v[88:91], v[176:179], v[220:223], v[88:91]
	v_mfma_f32_16x16x32_bf16 v[76:79], v[166:169], v[228:231], v[76:79]
	v_mfma_f32_16x16x32_bf16 v[72:75], v[176:179], v[228:231], v[72:75]
	v_mfma_f32_16x16x32_bf16 v[116:119], v[180:183], v[200:203], v[116:119]
	v_mfma_f32_16x16x32_bf16 v[112:115], v[188:191], v[200:203], v[112:115]
	v_mfma_f32_16x16x32_bf16 v[100:103], v[180:183], v[208:211], v[100:103]
	v_mfma_f32_16x16x32_bf16 v[96:99], v[188:191], v[208:211], v[96:99]
	v_mfma_f32_16x16x32_bf16 v[84:87], v[180:183], v[216:219], v[84:87]
	v_mfma_f32_16x16x32_bf16 v[80:83], v[188:191], v[216:219], v[80:83]
	v_mfma_f32_16x16x32_bf16 v[68:71], v[180:183], v[224:227], v[68:71]
	v_mfma_f32_16x16x32_bf16 v[64:67], v[188:191], v[224:227], v[64:67]
	v_mfma_f32_16x16x32_bf16 v[116:119], v[184:187], v[204:207], v[116:119]
	v_mfma_f32_16x16x32_bf16 v[112:115], v[196:199], v[204:207], v[112:115]
	v_mfma_f32_16x16x32_bf16 v[100:103], v[184:187], v[212:215], v[100:103]
	v_mfma_f32_16x16x32_bf16 v[96:99], v[196:199], v[212:215], v[96:99]
	v_mfma_f32_16x16x32_bf16 v[84:87], v[184:187], v[220:223], v[84:87]
	v_mfma_f32_16x16x32_bf16 v[80:83], v[196:199], v[220:223], v[80:83]
	v_mfma_f32_16x16x32_bf16 v[68:71], v[184:187], v[228:231], v[68:71]
	v_mfma_f32_16x16x32_bf16 v[64:67], v[196:199], v[228:231], v[64:67]
	s_barrier
	s_add_i32 s6, s6, s36
	s_add_u32 s98, s58, 0x80
	s_addc_u32 s99, s59, 0
	s_add_u32 s100, s60, 0x80
	s_addc_u32 s101, s61, 0
	s_mov_b32 m0, s6
	ds_read_b128 v[200:203], v158 offset:49152
	ds_read_b128 v[204:207], v158 offset:50176
	ds_read_b128 v[208:211], v158 offset:51200
	ds_read_b128 v[212:215], v158 offset:52224
	ds_read_b128 v[216:219], v158 offset:53248
	ds_read_b128 v[220:223], v158 offset:54272
	ds_read_b128 v[224:227], v158 offset:55296
	ds_read_b128 v[228:231], v158 offset:56320
	global_load_lds_dwordx4 v134, s[98:99]
	s_add_i32 m0, s6, 0x2000
	s_add_u32 s54, s58, 0xb0080
	s_addc_u32 s55, s59, 0
	s_add_i32 s6, s7, s36
	global_load_lds_dwordx4 v138, s[98:99]
	s_mov_b32 m0, s6
	s_nop 0
	global_load_lds_dwordx4 v134, s[54:55]
	s_add_i32 m0, s6, 0x2000
	s_nop 0
	global_load_lds_dwordx4 v138, s[54:55]
	s_mov_b32 m0, s78
	s_nop 0
	global_load_lds_dwordx4 v132, s[100:101]
	s_mov_b32 m0, s79
	s_nop 0
	global_load_lds_dwordx4 v136, s[100:101]
	s_waitcnt vmcnt(8)
	s_waitcnt lgkmcnt(0)
	s_barrier
	s_waitcnt lgkmcnt(0)
	v_mfma_f32_16x16x32_bf16 v[60:63], v[148:151], v[200:203], v[60:63]
	v_mfma_f32_16x16x32_bf16 v[56:59], v[172:175], v[200:203], v[56:59]
	v_mfma_f32_16x16x32_bf16 v[44:47], v[148:151], v[208:211], v[44:47]
	v_mfma_f32_16x16x32_bf16 v[40:43], v[172:175], v[208:211], v[40:43]
	v_mfma_f32_16x16x32_bf16 v[28:31], v[148:151], v[216:219], v[28:31]
	v_mfma_f32_16x16x32_bf16 v[24:27], v[172:175], v[216:219], v[24:27]
	v_mfma_f32_16x16x32_bf16 v[12:15], v[148:151], v[224:227], v[12:15]
	v_mfma_f32_16x16x32_bf16 v[8:11], v[172:175], v[224:227], v[8:11]
	v_mfma_f32_16x16x32_bf16 v[60:63], v[166:169], v[204:207], v[60:63]
	v_mfma_f32_16x16x32_bf16 v[56:59], v[176:179], v[204:207], v[56:59]
	v_mfma_f32_16x16x32_bf16 v[44:47], v[166:169], v[212:215], v[44:47]
	v_mfma_f32_16x16x32_bf16 v[40:43], v[176:179], v[212:215], v[40:43]
	v_mfma_f32_16x16x32_bf16 v[28:31], v[166:169], v[220:223], v[28:31]
	v_mfma_f32_16x16x32_bf16 v[24:27], v[176:179], v[220:223], v[24:27]
	v_mfma_f32_16x16x32_bf16 v[12:15], v[166:169], v[228:231], v[12:15]
	v_mfma_f32_16x16x32_bf16 v[8:11], v[176:179], v[228:231], v[8:11]
	v_mfma_f32_16x16x32_bf16 v[52:55], v[180:183], v[200:203], v[52:55]
	v_mfma_f32_16x16x32_bf16 v[48:51], v[188:191], v[200:203], v[48:51]
	v_mfma_f32_16x16x32_bf16 v[36:39], v[180:183], v[208:211], v[36:39]
	v_mfma_f32_16x16x32_bf16 v[32:35], v[188:191], v[208:211], v[32:35]
	v_mfma_f32_16x16x32_bf16 v[20:23], v[180:183], v[216:219], v[20:23]
	v_mfma_f32_16x16x32_bf16 v[16:19], v[188:191], v[216:219], v[16:19]
	v_mfma_f32_16x16x32_bf16 v[4:7], v[180:183], v[224:227], v[4:7]
	v_mfma_f32_16x16x32_bf16 v[0:3], v[188:191], v[224:227], v[0:3]
	v_mfma_f32_16x16x32_bf16 v[52:55], v[184:187], v[204:207], v[52:55]
	v_mfma_f32_16x16x32_bf16 v[48:51], v[196:199], v[204:207], v[48:51]
	v_mfma_f32_16x16x32_bf16 v[36:39], v[184:187], v[212:215], v[36:39]
	v_mfma_f32_16x16x32_bf16 v[32:35], v[196:199], v[212:215], v[32:35]
	v_mfma_f32_16x16x32_bf16 v[20:23], v[184:187], v[220:223], v[20:23]
	v_mfma_f32_16x16x32_bf16 v[16:19], v[196:199], v[220:223], v[16:19]
	v_mfma_f32_16x16x32_bf16 v[4:7], v[184:187], v[228:231], v[4:7]
	v_mfma_f32_16x16x32_bf16 v[0:3], v[196:199], v[228:231], v[0:3]
	s_barrier
	s_add_i32 s69, s69, 2
	s_add_u32 s4, s4, 0x100
	s_addc_u32 s33, s33, 0
	s_cmp_gt_u32 s69, 41
	s_mov_b64 s[54:55], s[56:57]
	s_cbranch_scc0 .LBB0_323
	s_and_b64 vcc, exec, s[40:41]
	s_cbranch_vccz .LBB0_326
	s_barrier

; #define PG8_STAGE(bufoff, gbase, voff) do { _Pragma("unroll") for (int _i = 0; _i < 2; ++_i) \
;         __builtin_amdgcn_global_load_lds((const unsigned*)((const char*)(gbase) + (voff)[_i]), (PG8_LAS unsigned*)(lds + (bufoff) + ldsw + _i * 8192), 16, 0, 0); } while (0)
; #define PG8_LDA(dst, b, h) do { _Pragma("unroll") for (int m = 0; m < 4; ++m) _Pragma("unroll") for (int k = 0; k < 2; ++k) dst[m][k] = *(const PG8_LAS bf16x8*)(lds + PG8_SA(b, h) + aoff + m * 2048 + k * 1024); } while (0)
; #define PG8_LDB(dst, b, h) do { _Pragma("unroll") for (int n = 0; n < 2; ++n) _Pragma("unroll") for (int k = 0; k < 2; ++k) dst[n][k] = *(const PG8_LAS bf16x8*)(lds + PG8_SB(b, h) + boff + n * 2048 + k * 1024); } while (0)
; #define PG8_MMA(ai, bj, At, Bt) do { __builtin_amdgcn_s_setprio(1); _Pragma("unroll") for (int m = 0; m < 4; ++m) _Pragma("unroll") for (int n = 0; n < 2; ++n) _Pragma("unroll") for (int k = 0; k < 2; ++k) \
;         acc[ai][bj][m][n] = __builtin_amdgcn_mfma_f32_16x16x32_bf16(Bt[n][k], At[m][k], acc[ai][bj][m][n], 0, 0, 0); __builtin_amdgcn_s_setprio(0); } while (0)
; #define PG8_WAIT_V(n) asm volatile("s_waitcnt vmcnt(" #n ")" ::: "memory")
; #define PG8_BAR __builtin_amdgcn_s_barrier()
; template <class Epi, class Sched, bool ALIGN_EPI = false, bool SP2 = false>
; __device__ __forceinline__ void gemm_phase(PG8_LAS unsigned char* lds, const Gemm g, const Sched& S, const Epi& E) {
;     ...
;         for (int t = 0; t < nt; t += 2) {
;             const bool last = (t == nt - 2);
;             const char* a1 = cA + (size_t)(t + 1) * kstep;
;             const char* a2 = last ? nA : cA + (size_t)(t + 2) * kstep; const char* b2 = last ? nB : cB + (size_t)(t + 2) * kstep;
;             const char* a3 = a2 + kstep; const char* b3 = b2 + kstep;
;             if (last && has_next) S.a_ready(nxt);
;             if constexpr (SP2) {
;             PG8_LDB(B0, 0, 0); PG8_LDB(B1, 0, 1); PG8_SCHED; PG8_LDA(At, 0, 0); PG8_STAGE(PG8_SA(1, 1), a1 + hstep, voffA);
;             PG8_WAIT_V(8); PG8_WAIT_L(0); PG8_BAR; PG8_MMA(0, 0, At, B0); PG8_MMA(0, 1, At, B1); PG8_BAR; PG8_SCHED;
;             PG8_LDA(At, 0, 1); PG8_STAGE(PG8_SB(0, 0), b2, voffB); PG8_STAGE(PG8_SB(0, 1), b2 + hstep, voffB); PG8_STAGE(PG8_SA(0, 0), a2, voffA);
;             PG8_WAIT_V(8); PG8_WAIT_L(0); PG8_BAR; PG8_MMA(1, 0, At, B0); PG8_MMA(1, 1, At, B1); PG8_BAR; PG8_SCHED;
.LBB0_463:
	ds_read_b128 v[152:155], v172
	ds_read_b128 v[156:159], v172 offset:1024
	ds_read_b128 v[166:169], v172 offset:2048
	ds_read_b128 v[176:179], v172 offset:3072
	ds_read_b128 v[180:183], v173
	ds_read_b128 v[184:187], v173 offset:1024
	ds_read_b128 v[188:191], v173 offset:2048
	ds_read_b128 v[196:199], v173 offset:3072
	s_add_u32 s6, s60, 0xfffc0080
	s_addc_u32 s7, s61, -1
	s_cmp_eq_u32 s72, 12
	s_cselect_b32 s81, s49, s7
	s_cselect_b32 s80, s55, s6
	s_cselect_b32 s79, s53, s33
	s_cselect_b32 s78, vcc_lo, vcc_hi
	s_add_i32 m0, s31, 0xc000
	ds_read_b128 v[200:203], v174
	ds_read_b128 v[204:207], v174 offset:1024
	ds_read_b128 v[208:211], v174 offset:2048
	ds_read_b128 v[212:215], v174 offset:3072
	ds_read_b128 v[216:219], v174 offset:4096
	ds_read_b128 v[220:223], v174 offset:5120
	ds_read_b128 v[224:227], v174 offset:6144
	ds_read_b128 v[228:231], v174 offset:7168
	global_load_lds_dwordx4 v144, s[60:61]
	s_add_i32 m0, s31, 0xe000
	s_nop 0
	global_load_lds_dwordx4 v146, s[60:61]
	s_waitcnt vmcnt(8)
	s_waitcnt lgkmcnt(0)
	s_barrier
	s_waitcnt lgkmcnt(0)
	v_mfma_f32_16x16x32_bf16 v[124:127], v[152:155], v[200:203], v[124:127]
	v_mfma_f32_16x16x32_bf16 v[120:123], v[166:169], v[200:203], v[120:123]
	v_mfma_f32_16x16x32_bf16 v[108:111], v[152:155], v[208:211], v[108:111]
	v_mfma_f32_16x16x32_bf16 v[104:107], v[166:169], v[208:211], v[104:107]
	v_mfma_f32_16x16x32_bf16 v[92:95], v[152:155], v[216:219], v[92:95]
	v_mfma_f32_16x16x32_bf16 v[88:91], v[166:169], v[216:219], v[88:91]
	v_mfma_f32_16x16x32_bf16 v[76:79], v[152:155], v[224:227], v[76:79]
	v_mfma_f32_16x16x32_bf16 v[72:75], v[166:169], v[224:227], v[72:75]
	v_mfma_f32_16x16x32_bf16 v[124:127], v[156:159], v[204:207], v[124:127]
	v_mfma_f32_16x16x32_bf16 v[120:123], v[176:179], v[204:207], v[120:123]
	v_mfma_f32_16x16x32_bf16 v[108:111], v[156:159], v[212:215], v[108:111]
	v_mfma_f32_16x16x32_bf16 v[104:107], v[176:179], v[212:215], v[104:107]
	v_mfma_f32_16x16x32_bf16 v[92:95], v[156:159], v[220:223], v[92:95]
	v_mfma_f32_16x16x32_bf16 v[88:91], v[176:179], v[220:223], v[88:91]
	v_mfma_f32_16x16x32_bf16 v[76:79], v[156:159], v[228:231], v[76:79]
	v_mfma_f32_16x16x32_bf16 v[72:75], v[176:179], v[228:231], v[72:75]
	v_mfma_f32_16x16x32_bf16 v[116:119], v[180:183], v[200:203], v[116:119]
	v_mfma_f32_16x16x32_bf16 v[112:115], v[188:191], v[200:203], v[112:115]
	v_mfma_f32_16x16x32_bf16 v[100:103], v[180:183], v[208:211], v[100:103]
	v_mfma_f32_16x16x32_bf16 v[96:99], v[188:191], v[208:211], v[96:99]
	v_mfma_f32_16x16x32_bf16 v[84:87], v[180:183], v[216:219], v[84:87]
	v_mfma_f32_16x16x32_bf16 v[80:83], v[188:191], v[216:219], v[80:83]
	v_mfma_f32_16x16x32_bf16 v[68:71], v[180:183], v[224:227], v[68:71]
	v_mfma_f32_16x16x32_bf16 v[64:67], v[188:191], v[224:227], v[64:67]
	v_mfma_f32_16x16x32_bf16 v[116:119], v[184:187], v[204:207], v[116:119]
	v_mfma_f32_16x16x32_bf16 v[112:115], v[196:199], v[204:207], v[112:115]
	v_mfma_f32_16x16x32_bf16 v[100:103], v[184:187], v[212:215], v[100:103]
	v_mfma_f32_16x16x32_bf16 v[96:99], v[196:199], v[212:215], v[96:99]
	v_mfma_f32_16x16x32_bf16 v[84:87], v[184:187], v[220:223], v[84:87]
	v_mfma_f32_16x16x32_bf16 v[80:83], v[196:199], v[220:223], v[80:83]
	v_mfma_f32_16x16x32_bf16 v[68:71], v[184:187], v[228:231], v[68:71]
	v_mfma_f32_16x16x32_bf16 v[64:67], v[196:199], v[228:231], v[64:67]
	s_barrier
	s_add_i32 s6, s69, s30
	s_mov_b32 m0, s6
	ds_read_b128 v[200:203], v174 offset:16384
	ds_read_b128 v[204:207], v174 offset:17408
	ds_read_b128 v[208:211], v174 offset:18432
	ds_read_b128 v[212:215], v174 offset:19456
	ds_read_b128 v[216:219], v174 offset:20480
	ds_read_b128 v[220:223], v174 offset:21504
	ds_read_b128 v[224:227], v174 offset:22528
	ds_read_b128 v[228:231], v174 offset:23552
	global_load_lds_dwordx4 v134, s[78:79]
	s_add_i32 m0, s6, 0x2000
	s_add_u32 s6, s78, 0x40000
	s_addc_u32 s7, s79, 0
	s_add_i32 s73, s74, s30
	global_load_lds_dwordx4 v138, s[78:79]
	s_mov_b32 m0, s73
	global_load_lds_dwordx4 v134, s[6:7]
	s_add_i32 m0, s73, 0x2000
	s_nop 0
	global_load_lds_dwordx4 v138, s[6:7]
	s_mov_b32 m0, s31
	s_nop 0
	global_load_lds_dwordx4 v132, s[80:81]
	s_mov_b32 m0, s36
	s_nop 0
	global_load_lds_dwordx4 v136, s[80:81]
	s_waitcnt vmcnt(8)
	s_waitcnt lgkmcnt(0)
	s_barrier
	s_waitcnt lgkmcnt(0)
	v_mfma_f32_16x16x32_bf16 v[60:63], v[152:155], v[200:203], v[60:63]
	v_mfma_f32_16x16x32_bf16 v[56:59], v[166:169], v[200:203], v[56:59]
	v_mfma_f32_16x16x32_bf16 v[44:47], v[152:155], v[208:211], v[44:47]
	v_mfma_f32_16x16x32_bf16 v[40:43], v[166:169], v[208:211], v[40:43]
	v_mfma_f32_16x16x32_bf16 v[28:31], v[152:155], v[216:219], v[28:31]
	v_mfma_f32_16x16x32_bf16 v[24:27], v[166:169], v[216:219], v[24:27]
	v_mfma_f32_16x16x32_bf16 v[12:15], v[152:155], v[224:227], v[12:15]
	v_mfma_f32_16x16x32_bf16 v[8:11], v[166:169], v[224:227], v[8:11]
	v_mfma_f32_16x16x32_bf16 v[60:63], v[156:159], v[204:207], v[60:63]
	v_mfma_f32_16x16x32_bf16 v[56:59], v[176:179], v[204:207], v[56:59]
	v_mfma_f32_16x16x32_bf16 v[44:47], v[156:159], v[212:215], v[44:47]
	v_mfma_f32_16x16x32_bf16 v[40:43], v[176:179], v[212:215], v[40:43]
	v_mfma_f32_16x16x32_bf16 v[28:31], v[156:159], v[220:223], v[28:31]
	v_mfma_f32_16x16x32_bf16 v[24:27], v[176:179], v[220:223], v[24:27]
	v_mfma_f32_16x16x32_bf16 v[12:15], v[156:159], v[228:231], v[12:15]
	v_mfma_f32_16x16x32_bf16 v[8:11], v[176:179], v[228:231], v[8:11]
	v_mfma_f32_16x16x32_bf16 v[52:55], v[180:183], v[200:203], v[52:55]
	v_mfma_f32_16x16x32_bf16 v[48:51], v[188:191], v[200:203], v[48:51]
	v_mfma_f32_16x16x32_bf16 v[36:39], v[180:183], v[208:211], v[36:39]
	v_mfma_f32_16x16x32_bf16 v[32:35], v[188:191], v[208:211], v[32:35]
	v_mfma_f32_16x16x32_bf16 v[20:23], v[180:183], v[216:219], v[20:23]
	v_mfma_f32_16x16x32_bf16 v[16:19], v[188:191], v[216:219], v[16:19]
	v_mfma_f32_16x16x32_bf16 v[4:7], v[180:183], v[224:227], v[4:7]
	v_mfma_f32_16x16x32_bf16 v[0:3], v[188:191], v[224:227], v[0:3]
	v_mfma_f32_16x16x32_bf16 v[52:55], v[184:187], v[204:207], v[52:55]
	v_mfma_f32_16x16x32_bf16 v[48:51], v[196:199], v[204:207], v[48:51]
	v_mfma_f32_16x16x32_bf16 v[36:39], v[184:187], v[212:215], v[36:39]
	v_mfma_f32_16x16x32_bf16 v[32:35], v[196:199], v[212:215], v[32:35]
	v_mfma_f32_16x16x32_bf16 v[20:23], v[184:187], v[220:223], v[20:23]
	v_mfma_f32_16x16x32_bf16 v[16:19], v[196:199], v[220:223], v[16:19]
	v_mfma_f32_16x16x32_bf16 v[4:7], v[184:187], v[228:231], v[4:7]
	v_mfma_f32_16x16x32_bf16 v[0:3], v[196:199], v[228:231], v[0:3]
	s_barrier
; #define PG8_STAGE(bufoff, gbase, voff) do { _Pragma("unroll") for (int _i = 0; _i < 2; ++_i) \
;         __builtin_amdgcn_global_load_lds((const unsigned*)((const char*)(gbase) + (voff)[_i]), (PG8_LAS unsigned*)(lds + (bufoff) + ldsw + _i * 8192), 16, 0, 0); } while (0)
; #define PG8_LDA(dst, b, h) do { _Pragma("unroll") for (int m = 0; m < 4; ++m) _Pragma("unroll") for (int k = 0; k < 2; ++k) dst[m][k] = *(const PG8_LAS bf16x8*)(lds + PG8_SA(b, h) + aoff + m * 2048 + k * 1024); } while (0)
; #define PG8_LDB(dst, b, h) do { _Pragma("unroll") for (int n = 0; n < 2; ++n) _Pragma("unroll") for (int k = 0; k < 2; ++k) dst[n][k] = *(const PG8_LAS bf16x8*)(lds + PG8_SB(b, h) + boff + n * 2048 + k * 1024); } while (0)
; #define PG8_MMA(ai, bj, At, Bt) do { __builtin_amdgcn_s_setprio(1); _Pragma("unroll") for (int m = 0; m < 4; ++m) _Pragma("unroll") for (int n = 0; n < 2; ++n) _Pragma("unroll") for (int k = 0; k < 2; ++k) \
;         acc[ai][bj][m][n] = __builtin_amdgcn_mfma_f32_16x16x32_bf16(Bt[n][k], At[m][k], acc[ai][bj][m][n], 0, 0, 0); __builtin_amdgcn_s_setprio(0); } while (0)
; #define PG8_WAIT_V(n) asm volatile("s_waitcnt vmcnt(" #n ")" ::: "memory")
; #define PG8_WAIT_L(n) asm volatile("s_waitcnt lgkmcnt(" #n ")" ::: "memory")
; #define PG8_BAR __builtin_amdgcn_s_barrier()
; #define PG8_SCHED __builtin_amdgcn_sched_barrier(0)
; template <class Epi, class Sched, bool ALIGN_EPI = false, bool SP2 = false>
; __device__ __forceinline__ void gemm_phase(PG8_LAS unsigned char* lds, const Gemm g, const Sched& S, const Epi& E) {
;     ...
;         for (int t = 0; t < nt; t += 2) {
;             const bool last = (t == nt - 2);
;     ...
;             PG8_LDB(B0, 1, 0); PG8_LDB(B1, 1, 1); PG8_SCHED; PG8_LDA(At, 1, 0); PG8_STAGE(PG8_SA(0, 1), a2 + hstep, voffA);
;             PG8_WAIT_V(8); PG8_WAIT_L(0); PG8_BAR; PG8_MMA(0, 0, At, B0); PG8_MMA(0, 1, At, B1); PG8_BAR; PG8_SCHED;
;             PG8_LDA(At, 1, 1); PG8_STAGE(PG8_SB(1, 0), b3, voffB); PG8_STAGE(PG8_SB(1, 1), b3 + hstep, voffB); PG8_STAGE(PG8_SA(1, 0), a3, voffA);
;             PG8_WAIT_V(8); PG8_WAIT_L(0); PG8_BAR; PG8_MMA(1, 0, At, B0); PG8_MMA(1, 1, At, B1); PG8_BAR; PG8_SCHED;
	s_add_i32 s73, 0, 0x18000
	v_add_u32_e32 v175, s73, v143
	s_add_i32 s82, 0, 0x1c000
	ds_read_b128 v[152:155], v175
	ds_read_b128 v[156:159], v175 offset:1024
	ds_read_b128 v[166:169], v175 offset:2048
	ds_read_b128 v[176:179], v175 offset:3072
	v_add_u32_e32 v175, s82, v143
	ds_read_b128 v[180:183], v175
	ds_read_b128 v[184:187], v175 offset:1024
	ds_read_b128 v[188:191], v175 offset:2048
	ds_read_b128 v[196:199], v175 offset:3072
	s_add_u32 s6, s80, 0x40000
	s_addc_u32 s7, s81, 0
	s_mov_b32 m0, s37
	ds_read_b128 v[200:203], v174 offset:32768
	ds_read_b128 v[204:207], v174 offset:33792
	ds_read_b128 v[208:211], v174 offset:34816
	ds_read_b128 v[212:215], v174 offset:35840
	ds_read_b128 v[216:219], v174 offset:36864
	ds_read_b128 v[220:223], v174 offset:37888
	ds_read_b128 v[224:227], v174 offset:38912
	ds_read_b128 v[228:231], v174 offset:39936
	global_load_lds_dwordx4 v132, s[6:7]
	s_mov_b32 m0, s42
	s_nop 0
	global_load_lds_dwordx4 v136, s[6:7]
	s_waitcnt vmcnt(8)
	s_waitcnt lgkmcnt(0)
	s_barrier
	s_waitcnt lgkmcnt(0)
	v_mfma_f32_16x16x32_bf16 v[124:127], v[152:155], v[200:203], v[124:127]
	v_mfma_f32_16x16x32_bf16 v[120:123], v[166:169], v[200:203], v[120:123]
	v_mfma_f32_16x16x32_bf16 v[108:111], v[152:155], v[208:211], v[108:111]
	v_mfma_f32_16x16x32_bf16 v[104:107], v[166:169], v[208:211], v[104:107]
	v_mfma_f32_16x16x32_bf16 v[92:95], v[152:155], v[216:219], v[92:95]
	v_mfma_f32_16x16x32_bf16 v[88:91], v[166:169], v[216:219], v[88:91]
	v_mfma_f32_16x16x32_bf16 v[76:79], v[152:155], v[224:227], v[76:79]
	v_mfma_f32_16x16x32_bf16 v[72:75], v[166:169], v[224:227], v[72:75]
	v_mfma_f32_16x16x32_bf16 v[124:127], v[156:159], v[204:207], v[124:127]
	v_mfma_f32_16x16x32_bf16 v[120:123], v[176:179], v[204:207], v[120:123]
	v_mfma_f32_16x16x32_bf16 v[108:111], v[156:159], v[212:215], v[108:111]
	v_mfma_f32_16x16x32_bf16 v[104:107], v[176:179], v[212:215], v[104:107]
	v_mfma_f32_16x16x32_bf16 v[92:95], v[156:159], v[220:223], v[92:95]
	v_mfma_f32_16x16x32_bf16 v[88:91], v[176:179], v[220:223], v[88:91]
	v_mfma_f32_16x16x32_bf16 v[76:79], v[156:159], v[228:231], v[76:79]
	v_mfma_f32_16x16x32_bf16 v[72:75], v[176:179], v[228:231], v[72:75]
	v_mfma_f32_16x16x32_bf16 v[116:119], v[180:183], v[200:203], v[116:119]
	v_mfma_f32_16x16x32_bf16 v[112:115], v[188:191], v[200:203], v[112:115]
	v_mfma_f32_16x16x32_bf16 v[100:103], v[180:183], v[208:211], v[100:103]
	v_mfma_f32_16x16x32_bf16 v[96:99], v[188:191], v[208:211], v[96:99]
	v_mfma_f32_16x16x32_bf16 v[84:87], v[180:183], v[216:219], v[84:87]
	v_mfma_f32_16x16x32_bf16 v[80:83], v[188:191], v[216:219], v[80:83]
	v_mfma_f32_16x16x32_bf16 v[68:71], v[180:183], v[224:227], v[68:71]
	v_mfma_f32_16x16x32_bf16 v[64:67], v[188:191], v[224:227], v[64:67]
	v_mfma_f32_16x16x32_bf16 v[116:119], v[184:187], v[204:207], v[116:119]
	v_mfma_f32_16x16x32_bf16 v[112:115], v[196:199], v[204:207], v[112:115]
	v_mfma_f32_16x16x32_bf16 v[100:103], v[184:187], v[212:215], v[100:103]
	v_mfma_f32_16x16x32_bf16 v[96:99], v[196:199], v[212:215], v[96:99]
	v_mfma_f32_16x16x32_bf16 v[84:87], v[184:187], v[220:223], v[84:87]
	v_mfma_f32_16x16x32_bf16 v[80:83], v[196:199], v[220:223], v[80:83]
	v_mfma_f32_16x16x32_bf16 v[68:71], v[184:187], v[228:231], v[68:71]
	v_mfma_f32_16x16x32_bf16 v[64:67], v[196:199], v[228:231], v[64:67]
	s_barrier
	s_add_i32 s6, s73, s30
	s_add_u32 s98, s78, 0x80
	s_addc_u32 s99, s79, 0
	s_add_u32 s100, s80, 0x80
	s_addc_u32 s101, s81, 0
	s_mov_b32 m0, s6
	ds_read_b128 v[200:203], v174 offset:49152
	ds_read_b128 v[204:207], v174 offset:50176
	ds_read_b128 v[208:211], v174 offset:51200
	ds_read_b128 v[212:215], v174 offset:52224
	ds_read_b128 v[216:219], v174 offset:53248
	ds_read_b128 v[220:223], v174 offset:54272
	ds_read_b128 v[224:227], v174 offset:55296
	ds_read_b128 v[228:231], v174 offset:56320
	global_load_lds_dwordx4 v134, s[98:99]
	s_add_i32 m0, s6, 0x2000
	s_add_u32 s6, s78, 0x40080
	s_addc_u32 s7, s79, 0
	s_add_i32 s73, s82, s30
	global_load_lds_dwordx4 v138, s[98:99]
	s_mov_b32 m0, s73
	s_nop 0
	global_load_lds_dwordx4 v134, s[6:7]
	s_add_i32 m0, s73, 0x2000
	s_nop 0
	global_load_lds_dwordx4 v138, s[6:7]
	s_mov_b32 m0, s67
	s_nop 0
	global_load_lds_dwordx4 v132, s[100:101]
	s_mov_b32 m0, s68
	s_nop 0
	global_load_lds_dwordx4 v136, s[100:101]
	s_waitcnt vmcnt(8)
	s_waitcnt lgkmcnt(0)
	s_barrier
	s_waitcnt lgkmcnt(0)
	v_mfma_f32_16x16x32_bf16 v[60:63], v[152:155], v[200:203], v[60:63]
	v_mfma_f32_16x16x32_bf16 v[56:59], v[166:169], v[200:203], v[56:59]
	v_mfma_f32_16x16x32_bf16 v[44:47], v[152:155], v[208:211], v[44:47]
	v_mfma_f32_16x16x32_bf16 v[40:43], v[166:169], v[208:211], v[40:43]
	v_mfma_f32_16x16x32_bf16 v[28:31], v[152:155], v[216:219], v[28:31]
	v_mfma_f32_16x16x32_bf16 v[24:27], v[166:169], v[216:219], v[24:27]
	v_mfma_f32_16x16x32_bf16 v[12:15], v[152:155], v[224:227], v[12:15]
	v_mfma_f32_16x16x32_bf16 v[8:11], v[166:169], v[224:227], v[8:11]
	v_mfma_f32_16x16x32_bf16 v[60:63], v[156:159], v[204:207], v[60:63]
	v_mfma_f32_16x16x32_bf16 v[56:59], v[176:179], v[204:207], v[56:59]
	v_mfma_f32_16x16x32_bf16 v[44:47], v[156:159], v[212:215], v[44:47]
	v_mfma_f32_16x16x32_bf16 v[40:43], v[176:179], v[212:215], v[40:43]
	v_mfma_f32_16x16x32_bf16 v[28:31], v[156:159], v[220:223], v[28:31]
	v_mfma_f32_16x16x32_bf16 v[24:27], v[176:179], v[220:223], v[24:27]
	v_mfma_f32_16x16x32_bf16 v[12:15], v[156:159], v[228:231], v[12:15]
	v_mfma_f32_16x16x32_bf16 v[8:11], v[176:179], v[228:231], v[8:11]
	v_mfma_f32_16x16x32_bf16 v[52:55], v[180:183], v[200:203], v[52:55]
	v_mfma_f32_16x16x32_bf16 v[48:51], v[188:191], v[200:203], v[48:51]
	v_mfma_f32_16x16x32_bf16 v[36:39], v[180:183], v[208:211], v[36:39]
	v_mfma_f32_16x16x32_bf16 v[32:35], v[188:191], v[208:211], v[32:35]
	v_mfma_f32_16x16x32_bf16 v[20:23], v[180:183], v[216:219], v[20:23]
	v_mfma_f32_16x16x32_bf16 v[16:19], v[188:191], v[216:219], v[16:19]
	v_mfma_f32_16x16x32_bf16 v[4:7], v[180:183], v[224:227], v[4:7]
	v_mfma_f32_16x16x32_bf16 v[0:3], v[188:191], v[224:227], v[0:3]
	v_mfma_f32_16x16x32_bf16 v[52:55], v[184:187], v[204:207], v[52:55]
	v_mfma_f32_16x16x32_bf16 v[48:51], v[196:199], v[204:207], v[48:51]
	v_mfma_f32_16x16x32_bf16 v[36:39], v[184:187], v[212:215], v[36:39]
	v_mfma_f32_16x16x32_bf16 v[32:35], v[196:199], v[212:215], v[32:35]
	v_mfma_f32_16x16x32_bf16 v[20:23], v[184:187], v[220:223], v[20:23]
	v_mfma_f32_16x16x32_bf16 v[16:19], v[196:199], v[220:223], v[16:19]
	v_mfma_f32_16x16x32_bf16 v[4:7], v[184:187], v[228:231], v[4:7]
	v_mfma_f32_16x16x32_bf16 v[0:3], v[196:199], v[228:231], v[0:3]
	s_barrier
	s_add_i32 s72, s72, 2
	s_add_u32 s60, s60, 0x100
	s_addc_u32 s61, s61, 0
	s_add_u32 vcc_hi, vcc_hi, 0x100
	s_addc_u32 s33, s33, 0
	s_cmp_gt_u32 s72, 13
	s_cbranch_scc0 .LBB0_463
	s_and_b64 vcc, exec, s[50:51]
	s_cbranch_vccz .LBB0_466
	s_barrier

; #define PG8_STAGE(bufoff, gbase, voff) do { _Pragma("unroll") for (int _i = 0; _i < 2; ++_i) \
;         __builtin_amdgcn_global_load_lds((const unsigned*)((const char*)(gbase) + (voff)[_i]), (PG8_LAS unsigned*)(lds + (bufoff) + ldsw + _i * 8192), 16, 0, 0); } while (0)
; #define PG8_LDA(dst, b, h) do { _Pragma("unroll") for (int m = 0; m < 4; ++m) _Pragma("unroll") for (int k = 0; k < 2; ++k) dst[m][k] = *(const PG8_LAS bf16x8*)(lds + PG8_SA(b, h) + aoff + m * 2048 + k * 1024); } while (0)
; #define PG8_LDB(dst, b, h) do { _Pragma("unroll") for (int n = 0; n < 2; ++n) _Pragma("unroll") for (int k = 0; k < 2; ++k) dst[n][k] = *(const PG8_LAS bf16x8*)(lds + PG8_SB(b, h) + boff + n * 2048 + k * 1024); } while (0)
; #define PG8_MMA(ai, bj, At, Bt) do { __builtin_amdgcn_s_setprio(1); _Pragma("unroll") for (int m = 0; m < 4; ++m) _Pragma("unroll") for (int n = 0; n < 2; ++n) _Pragma("unroll") for (int k = 0; k < 2; ++k) \
;         acc[ai][bj][m][n] = __builtin_amdgcn_mfma_f32_16x16x32_bf16(Bt[n][k], At[m][k], acc[ai][bj][m][n], 0, 0, 0); __builtin_amdgcn_s_setprio(0); } while (0)
; #define PG8_WAIT_V(n) asm volatile("s_waitcnt vmcnt(" #n ")" ::: "memory")
; #define PG8_BAR __builtin_amdgcn_s_barrier()
; template <class Epi, class Sched, bool ALIGN_EPI = false, bool SP2 = false>
; __device__ __forceinline__ void gemm_phase(PG8_LAS unsigned char* lds, const Gemm g, const Sched& S, const Epi& E) {
;     ...
;         for (int t = 0; t < nt; t += 2) {
;             const bool last = (t == nt - 2);
;             const char* a1 = cA + (size_t)(t + 1) * kstep;
;             const char* a2 = last ? nA : cA + (size_t)(t + 2) * kstep; const char* b2 = last ? nB : cB + (size_t)(t + 2) * kstep;
;             const char* a3 = a2 + kstep; const char* b3 = b2 + kstep;
;             if (last && has_next) S.a_ready(nxt);
;             if constexpr (SP2) {
;             PG8_LDB(B0, 0, 0); PG8_LDB(B1, 0, 1); PG8_SCHED; PG8_LDA(At, 0, 0); PG8_STAGE(PG8_SA(1, 1), a1 + hstep, voffA);
;             PG8_WAIT_V(8); PG8_WAIT_L(0); PG8_BAR; PG8_MMA(0, 0, At, B0); PG8_MMA(0, 1, At, B1); PG8_BAR; PG8_SCHED;
;             PG8_LDA(At, 0, 1); PG8_STAGE(PG8_SB(0, 0), b2, voffB); PG8_STAGE(PG8_SB(0, 1), b2 + hstep, voffB); PG8_STAGE(PG8_SA(0, 0), a2, voffA);
;             PG8_WAIT_V(8); PG8_WAIT_L(0); PG8_BAR; PG8_MMA(1, 0, At, B0); PG8_MMA(1, 1, At, B1); PG8_BAR; PG8_SCHED;
.LBB0_777:
	ds_read_b128 v[144:147], v158
	ds_read_b128 v[168:171], v158 offset:1024
	ds_read_b128 v[172:175], v158 offset:2048
	ds_read_b128 v[176:179], v158 offset:3072
	ds_read_b128 v[180:183], v159
	ds_read_b128 v[184:187], v159 offset:1024
	ds_read_b128 v[188:191], v159 offset:2048
	ds_read_b128 v[196:199], v159 offset:3072
	s_add_u32 s60, s58, 0x100
	s_addc_u32 s61, s59, 0
	s_cmp_eq_u32 s72, 8
	s_cselect_b32 s81, s49, s61
	s_cselect_b32 s80, s48, s60
	s_cselect_b32 s79, s57, vcc_lo
	s_cselect_b32 s78, s56, s33
	s_add_i32 m0, s76, 0xc000
	ds_read_b128 v[200:203], v163
	ds_read_b128 v[204:207], v163 offset:1024
	ds_read_b128 v[208:211], v163 offset:2048
	ds_read_b128 v[212:215], v163 offset:3072
	ds_read_b128 v[216:219], v163 offset:4096
	ds_read_b128 v[220:223], v163 offset:5120
	ds_read_b128 v[224:227], v163 offset:6144
	ds_read_b128 v[228:231], v163 offset:7168
	global_load_lds_dwordx4 v136, s[58:59]
	s_add_i32 m0, s76, 0xe000
	s_nop 0
	global_load_lds_dwordx4 v138, s[58:59]
	s_waitcnt vmcnt(8)
	s_waitcnt lgkmcnt(0)
	s_barrier
	s_waitcnt lgkmcnt(0)
	v_mfma_f32_16x16x32_bf16 v[124:127], v[144:147], v[200:203], v[124:127]
	v_mfma_f32_16x16x32_bf16 v[120:123], v[172:175], v[200:203], v[120:123]
	v_mfma_f32_16x16x32_bf16 v[108:111], v[144:147], v[208:211], v[108:111]
	v_mfma_f32_16x16x32_bf16 v[104:107], v[172:175], v[208:211], v[104:107]
	v_mfma_f32_16x16x32_bf16 v[92:95], v[144:147], v[216:219], v[92:95]
	v_mfma_f32_16x16x32_bf16 v[88:91], v[172:175], v[216:219], v[88:91]
	v_mfma_f32_16x16x32_bf16 v[76:79], v[144:147], v[224:227], v[76:79]
	v_mfma_f32_16x16x32_bf16 v[72:75], v[172:175], v[224:227], v[72:75]
	v_mfma_f32_16x16x32_bf16 v[124:127], v[168:171], v[204:207], v[124:127]
	v_mfma_f32_16x16x32_bf16 v[120:123], v[176:179], v[204:207], v[120:123]
	v_mfma_f32_16x16x32_bf16 v[108:111], v[168:171], v[212:215], v[108:111]
	v_mfma_f32_16x16x32_bf16 v[104:107], v[176:179], v[212:215], v[104:107]
	v_mfma_f32_16x16x32_bf16 v[92:95], v[168:171], v[220:223], v[92:95]
	v_mfma_f32_16x16x32_bf16 v[88:91], v[176:179], v[220:223], v[88:91]
	v_mfma_f32_16x16x32_bf16 v[76:79], v[168:171], v[228:231], v[76:79]
	v_mfma_f32_16x16x32_bf16 v[72:75], v[176:179], v[228:231], v[72:75]
	v_mfma_f32_16x16x32_bf16 v[116:119], v[180:183], v[200:203], v[116:119]
	v_mfma_f32_16x16x32_bf16 v[112:115], v[188:191], v[200:203], v[112:115]
	v_mfma_f32_16x16x32_bf16 v[100:103], v[180:183], v[208:211], v[100:103]
	v_mfma_f32_16x16x32_bf16 v[96:99], v[188:191], v[208:211], v[96:99]
	v_mfma_f32_16x16x32_bf16 v[84:87], v[180:183], v[216:219], v[84:87]
	v_mfma_f32_16x16x32_bf16 v[80:83], v[188:191], v[216:219], v[80:83]
	v_mfma_f32_16x16x32_bf16 v[68:71], v[180:183], v[224:227], v[68:71]
	v_mfma_f32_16x16x32_bf16 v[64:67], v[188:191], v[224:227], v[64:67]
	v_mfma_f32_16x16x32_bf16 v[116:119], v[184:187], v[204:207], v[116:119]
	v_mfma_f32_16x16x32_bf16 v[112:115], v[196:199], v[204:207], v[112:115]
	v_mfma_f32_16x16x32_bf16 v[100:103], v[184:187], v[212:215], v[100:103]
	v_mfma_f32_16x16x32_bf16 v[96:99], v[196:199], v[212:215], v[96:99]
	v_mfma_f32_16x16x32_bf16 v[84:87], v[184:187], v[220:223], v[84:87]
	v_mfma_f32_16x16x32_bf16 v[80:83], v[196:199], v[220:223], v[80:83]
	v_mfma_f32_16x16x32_bf16 v[68:71], v[184:187], v[228:231], v[68:71]
	v_mfma_f32_16x16x32_bf16 v[64:67], v[196:199], v[228:231], v[64:67]
	s_barrier
	s_add_i32 s6, s26, s67
	s_mov_b32 m0, s6
	ds_read_b128 v[200:203], v163 offset:16384
	ds_read_b128 v[204:207], v163 offset:17408
	ds_read_b128 v[208:211], v163 offset:18432
	ds_read_b128 v[212:215], v163 offset:19456
	ds_read_b128 v[216:219], v163 offset:20480
	ds_read_b128 v[220:223], v163 offset:21504
	ds_read_b128 v[224:227], v163 offset:22528
	ds_read_b128 v[228:231], v163 offset:23552
	global_load_lds_dwordx4 v130, s[78:79]
	s_add_i32 m0, s6, 0x2000
	s_add_u32 s6, s78, 0x30000
	s_addc_u32 s7, s79, 0
	s_add_i32 s58, s74, s67
	global_load_lds_dwordx4 v134, s[78:79]
	s_mov_b32 m0, s58
	global_load_lds_dwordx4 v130, s[6:7]
	s_add_i32 m0, s58, 0x2000
	s_nop 0
	global_load_lds_dwordx4 v134, s[6:7]
	s_mov_b32 m0, s76
	s_nop 0
	global_load_lds_dwordx4 v128, s[80:81]
	s_mov_b32 m0, s77
	s_nop 0
	global_load_lds_dwordx4 v132, s[80:81]
	s_waitcnt vmcnt(8)
	s_waitcnt lgkmcnt(0)
	s_barrier
	s_waitcnt lgkmcnt(0)
	v_mfma_f32_16x16x32_bf16 v[60:63], v[144:147], v[200:203], v[60:63]
	v_mfma_f32_16x16x32_bf16 v[56:59], v[172:175], v[200:203], v[56:59]
	v_mfma_f32_16x16x32_bf16 v[44:47], v[144:147], v[208:211], v[44:47]
	v_mfma_f32_16x16x32_bf16 v[40:43], v[172:175], v[208:211], v[40:43]
	v_mfma_f32_16x16x32_bf16 v[28:31], v[144:147], v[216:219], v[28:31]
	v_mfma_f32_16x16x32_bf16 v[24:27], v[172:175], v[216:219], v[24:27]
	v_mfma_f32_16x16x32_bf16 v[12:15], v[144:147], v[224:227], v[12:15]
	v_mfma_f32_16x16x32_bf16 v[8:11], v[172:175], v[224:227], v[8:11]
	v_mfma_f32_16x16x32_bf16 v[60:63], v[168:171], v[204:207], v[60:63]
	v_mfma_f32_16x16x32_bf16 v[56:59], v[176:179], v[204:207], v[56:59]
	v_mfma_f32_16x16x32_bf16 v[44:47], v[168:171], v[212:215], v[44:47]
	v_mfma_f32_16x16x32_bf16 v[40:43], v[176:179], v[212:215], v[40:43]
	v_mfma_f32_16x16x32_bf16 v[28:31], v[168:171], v[220:223], v[28:31]
	v_mfma_f32_16x16x32_bf16 v[24:27], v[176:179], v[220:223], v[24:27]
	v_mfma_f32_16x16x32_bf16 v[12:15], v[168:171], v[228:231], v[12:15]
	v_mfma_f32_16x16x32_bf16 v[8:11], v[176:179], v[228:231], v[8:11]
	v_mfma_f32_16x16x32_bf16 v[52:55], v[180:183], v[200:203], v[52:55]
	v_mfma_f32_16x16x32_bf16 v[48:51], v[188:191], v[200:203], v[48:51]
	v_mfma_f32_16x16x32_bf16 v[36:39], v[180:183], v[208:211], v[36:39]
	v_mfma_f32_16x16x32_bf16 v[32:35], v[188:191], v[208:211], v[32:35]
	v_mfma_f32_16x16x32_bf16 v[20:23], v[180:183], v[216:219], v[20:23]
	v_mfma_f32_16x16x32_bf16 v[16:19], v[188:191], v[216:219], v[16:19]
	v_mfma_f32_16x16x32_bf16 v[4:7], v[180:183], v[224:227], v[4:7]
	v_mfma_f32_16x16x32_bf16 v[0:3], v[188:191], v[224:227], v[0:3]
	v_mfma_f32_16x16x32_bf16 v[52:55], v[184:187], v[204:207], v[52:55]
	v_mfma_f32_16x16x32_bf16 v[48:51], v[196:199], v[204:207], v[48:51]
	v_mfma_f32_16x16x32_bf16 v[36:39], v[184:187], v[212:215], v[36:39]
	v_mfma_f32_16x16x32_bf16 v[32:35], v[196:199], v[212:215], v[32:35]
	v_mfma_f32_16x16x32_bf16 v[20:23], v[184:187], v[220:223], v[20:23]
	v_mfma_f32_16x16x32_bf16 v[16:19], v[196:199], v[220:223], v[16:19]
	v_mfma_f32_16x16x32_bf16 v[4:7], v[184:187], v[228:231], v[4:7]
	v_mfma_f32_16x16x32_bf16 v[0:3], v[196:199], v[228:231], v[0:3]
	s_barrier
; #define PG8_STAGE(bufoff, gbase, voff) do { _Pragma("unroll") for (int _i = 0; _i < 2; ++_i) \
;         __builtin_amdgcn_global_load_lds((const unsigned*)((const char*)(gbase) + (voff)[_i]), (PG8_LAS unsigned*)(lds + (bufoff) + ldsw + _i * 8192), 16, 0, 0); } while (0)
; #define PG8_LDA(dst, b, h) do { _Pragma("unroll") for (int m = 0; m < 4; ++m) _Pragma("unroll") for (int k = 0; k < 2; ++k) dst[m][k] = *(const PG8_LAS bf16x8*)(lds + PG8_SA(b, h) + aoff + m * 2048 + k * 1024); } while (0)
; #define PG8_LDB(dst, b, h) do { _Pragma("unroll") for (int n = 0; n < 2; ++n) _Pragma("unroll") for (int k = 0; k < 2; ++k) dst[n][k] = *(const PG8_LAS bf16x8*)(lds + PG8_SB(b, h) + boff + n * 2048 + k * 1024); } while (0)
; #define PG8_MMA(ai, bj, At, Bt) do { __builtin_amdgcn_s_setprio(1); _Pragma("unroll") for (int m = 0; m < 4; ++m) _Pragma("unroll") for (int n = 0; n < 2; ++n) _Pragma("unroll") for (int k = 0; k < 2; ++k) \
;         acc[ai][bj][m][n] = __builtin_amdgcn_mfma_f32_16x16x32_bf16(Bt[n][k], At[m][k], acc[ai][bj][m][n], 0, 0, 0); __builtin_amdgcn_s_setprio(0); } while (0)
; #define PG8_WAIT_V(n) asm volatile("s_waitcnt vmcnt(" #n ")" ::: "memory")
; #define PG8_WAIT_L(n) asm volatile("s_waitcnt lgkmcnt(" #n ")" ::: "memory")
; #define PG8_BAR __builtin_amdgcn_s_barrier()
; #define PG8_SCHED __builtin_amdgcn_sched_barrier(0)
; template <class Epi, class Sched, bool ALIGN_EPI = false, bool SP2 = false>
; __device__ __forceinline__ void gemm_phase(PG8_LAS unsigned char* lds, const Gemm g, const Sched& S, const Epi& E) {
;     ...
;         for (int t = 0; t < nt; t += 2) {
;             const bool last = (t == nt - 2);
;     ...
;             PG8_LDB(B0, 1, 0); PG8_LDB(B1, 1, 1); PG8_SCHED; PG8_LDA(At, 1, 0); PG8_STAGE(PG8_SA(0, 1), a2 + hstep, voffA);
;             PG8_WAIT_V(8); PG8_WAIT_L(0); PG8_BAR; PG8_MMA(0, 0, At, B0); PG8_MMA(0, 1, At, B1); PG8_BAR; PG8_SCHED;
;             PG8_LDA(At, 1, 1); PG8_STAGE(PG8_SB(1, 0), b3, voffB); PG8_STAGE(PG8_SB(1, 1), b3 + hstep, voffB); PG8_STAGE(PG8_SA(1, 0), a3, voffA);
;             PG8_WAIT_V(8); PG8_WAIT_L(0); PG8_BAR; PG8_MMA(1, 0, At, B0); PG8_MMA(1, 1, At, B1); PG8_BAR; PG8_SCHED;
	s_add_i32 s58, 0, 0x18000
	v_add_u32_e32 v167, s58, v156
	s_add_i32 s59, 0, 0x1c000
	ds_read_b128 v[144:147], v167
	ds_read_b128 v[168:171], v167 offset:1024
	ds_read_b128 v[172:175], v167 offset:2048
	ds_read_b128 v[176:179], v167 offset:3072
	v_add_u32_e32 v167, s59, v156
	ds_read_b128 v[180:183], v167
	ds_read_b128 v[184:187], v167 offset:1024
	ds_read_b128 v[188:191], v167 offset:2048
	ds_read_b128 v[196:199], v167 offset:3072
	s_add_u32 s6, s80, 0x30000
	s_addc_u32 s7, s81, 0
	s_mov_b32 m0, s36
	ds_read_b128 v[200:203], v163 offset:32768
	ds_read_b128 v[204:207], v163 offset:33792
	ds_read_b128 v[208:211], v163 offset:34816
	ds_read_b128 v[212:215], v163 offset:35840
	ds_read_b128 v[216:219], v163 offset:36864
	ds_read_b128 v[220:223], v163 offset:37888
	ds_read_b128 v[224:227], v163 offset:38912
	ds_read_b128 v[228:231], v163 offset:39936
	global_load_lds_dwordx4 v128, s[6:7]
	s_mov_b32 m0, s37
	s_nop 0
	global_load_lds_dwordx4 v132, s[6:7]
	s_waitcnt vmcnt(8)
	s_waitcnt lgkmcnt(0)
	s_barrier
	s_waitcnt lgkmcnt(0)
	v_mfma_f32_16x16x32_bf16 v[124:127], v[144:147], v[200:203], v[124:127]
	v_mfma_f32_16x16x32_bf16 v[120:123], v[172:175], v[200:203], v[120:123]
	v_mfma_f32_16x16x32_bf16 v[108:111], v[144:147], v[208:211], v[108:111]
	v_mfma_f32_16x16x32_bf16 v[104:107], v[172:175], v[208:211], v[104:107]
	v_mfma_f32_16x16x32_bf16 v[92:95], v[144:147], v[216:219], v[92:95]
	v_mfma_f32_16x16x32_bf16 v[88:91], v[172:175], v[216:219], v[88:91]
	v_mfma_f32_16x16x32_bf16 v[76:79], v[144:147], v[224:227], v[76:79]
	v_mfma_f32_16x16x32_bf16 v[72:75], v[172:175], v[224:227], v[72:75]
	v_mfma_f32_16x16x32_bf16 v[124:127], v[168:171], v[204:207], v[124:127]
	v_mfma_f32_16x16x32_bf16 v[120:123], v[176:179], v[204:207], v[120:123]
	v_mfma_f32_16x16x32_bf16 v[108:111], v[168:171], v[212:215], v[108:111]
	v_mfma_f32_16x16x32_bf16 v[104:107], v[176:179], v[212:215], v[104:107]
	v_mfma_f32_16x16x32_bf16 v[92:95], v[168:171], v[220:223], v[92:95]
	v_mfma_f32_16x16x32_bf16 v[88:91], v[176:179], v[220:223], v[88:91]
	v_mfma_f32_16x16x32_bf16 v[76:79], v[168:171], v[228:231], v[76:79]
	v_mfma_f32_16x16x32_bf16 v[72:75], v[176:179], v[228:231], v[72:75]
	v_mfma_f32_16x16x32_bf16 v[116:119], v[180:183], v[200:203], v[116:119]
	v_mfma_f32_16x16x32_bf16 v[112:115], v[188:191], v[200:203], v[112:115]
	v_mfma_f32_16x16x32_bf16 v[100:103], v[180:183], v[208:211], v[100:103]
	v_mfma_f32_16x16x32_bf16 v[96:99], v[188:191], v[208:211], v[96:99]
	v_mfma_f32_16x16x32_bf16 v[84:87], v[180:183], v[216:219], v[84:87]
	v_mfma_f32_16x16x32_bf16 v[80:83], v[188:191], v[216:219], v[80:83]
	v_mfma_f32_16x16x32_bf16 v[68:71], v[180:183], v[224:227], v[68:71]
	v_mfma_f32_16x16x32_bf16 v[64:67], v[188:191], v[224:227], v[64:67]
	v_mfma_f32_16x16x32_bf16 v[116:119], v[184:187], v[204:207], v[116:119]
	v_mfma_f32_16x16x32_bf16 v[112:115], v[196:199], v[204:207], v[112:115]
	v_mfma_f32_16x16x32_bf16 v[100:103], v[184:187], v[212:215], v[100:103]
	v_mfma_f32_16x16x32_bf16 v[96:99], v[196:199], v[212:215], v[96:99]
	v_mfma_f32_16x16x32_bf16 v[84:87], v[184:187], v[220:223], v[84:87]
	v_mfma_f32_16x16x32_bf16 v[80:83], v[196:199], v[220:223], v[80:83]
	v_mfma_f32_16x16x32_bf16 v[68:71], v[184:187], v[228:231], v[68:71]
	v_mfma_f32_16x16x32_bf16 v[64:67], v[196:199], v[228:231], v[64:67]
	s_barrier
	s_add_i32 s6, s58, s67
	s_add_u32 s98, s78, 0x80
	s_addc_u32 s99, s79, 0
	s_add_u32 s100, s80, 0x80
	s_addc_u32 s101, s81, 0
	s_mov_b32 m0, s6
	ds_read_b128 v[200:203], v163 offset:49152
	ds_read_b128 v[204:207], v163 offset:50176
	ds_read_b128 v[208:211], v163 offset:51200
	ds_read_b128 v[212:215], v163 offset:52224
	ds_read_b128 v[216:219], v163 offset:53248
	ds_read_b128 v[220:223], v163 offset:54272
	ds_read_b128 v[224:227], v163 offset:55296
	ds_read_b128 v[228:231], v163 offset:56320
	global_load_lds_dwordx4 v130, s[98:99]
	s_add_i32 m0, s6, 0x2000
	s_add_u32 s6, s78, 0x30080
	s_addc_u32 s7, s79, 0
	s_add_i32 s58, s59, s67
	global_load_lds_dwordx4 v134, s[98:99]
	s_mov_b32 m0, s58
	s_nop 0
	global_load_lds_dwordx4 v130, s[6:7]
	s_add_i32 m0, s58, 0x2000
	s_nop 0
	global_load_lds_dwordx4 v134, s[6:7]
	s_mov_b32 m0, s31
	s_nop 0
	global_load_lds_dwordx4 v128, s[100:101]
	s_mov_b32 m0, s4
	s_nop 0
	global_load_lds_dwordx4 v132, s[100:101]
	s_waitcnt vmcnt(8)
	s_waitcnt lgkmcnt(0)
	s_barrier
	s_waitcnt lgkmcnt(0)
	v_mfma_f32_16x16x32_bf16 v[60:63], v[144:147], v[200:203], v[60:63]
	v_mfma_f32_16x16x32_bf16 v[56:59], v[172:175], v[200:203], v[56:59]
	v_mfma_f32_16x16x32_bf16 v[44:47], v[144:147], v[208:211], v[44:47]
	v_mfma_f32_16x16x32_bf16 v[40:43], v[172:175], v[208:211], v[40:43]
	v_mfma_f32_16x16x32_bf16 v[28:31], v[144:147], v[216:219], v[28:31]
	v_mfma_f32_16x16x32_bf16 v[24:27], v[172:175], v[216:219], v[24:27]
	v_mfma_f32_16x16x32_bf16 v[12:15], v[144:147], v[224:227], v[12:15]
	v_mfma_f32_16x16x32_bf16 v[8:11], v[172:175], v[224:227], v[8:11]
	v_mfma_f32_16x16x32_bf16 v[60:63], v[168:171], v[204:207], v[60:63]
	v_mfma_f32_16x16x32_bf16 v[56:59], v[176:179], v[204:207], v[56:59]
	v_mfma_f32_16x16x32_bf16 v[44:47], v[168:171], v[212:215], v[44:47]
	v_mfma_f32_16x16x32_bf16 v[40:43], v[176:179], v[212:215], v[40:43]
	v_mfma_f32_16x16x32_bf16 v[28:31], v[168:171], v[220:223], v[28:31]
	v_mfma_f32_16x16x32_bf16 v[24:27], v[176:179], v[220:223], v[24:27]
	v_mfma_f32_16x16x32_bf16 v[12:15], v[168:171], v[228:231], v[12:15]
	v_mfma_f32_16x16x32_bf16 v[8:11], v[176:179], v[228:231], v[8:11]
	v_mfma_f32_16x16x32_bf16 v[52:55], v[180:183], v[200:203], v[52:55]
	v_mfma_f32_16x16x32_bf16 v[48:51], v[188:191], v[200:203], v[48:51]
	v_mfma_f32_16x16x32_bf16 v[36:39], v[180:183], v[208:211], v[36:39]
	v_mfma_f32_16x16x32_bf16 v[32:35], v[188:191], v[208:211], v[32:35]
	v_mfma_f32_16x16x32_bf16 v[20:23], v[180:183], v[216:219], v[20:23]
	v_mfma_f32_16x16x32_bf16 v[16:19], v[188:191], v[216:219], v[16:19]
	v_mfma_f32_16x16x32_bf16 v[4:7], v[180:183], v[224:227], v[4:7]
	v_mfma_f32_16x16x32_bf16 v[0:3], v[188:191], v[224:227], v[0:3]
	v_mfma_f32_16x16x32_bf16 v[52:55], v[184:187], v[204:207], v[52:55]
	v_mfma_f32_16x16x32_bf16 v[48:51], v[196:199], v[204:207], v[48:51]
	v_mfma_f32_16x16x32_bf16 v[36:39], v[184:187], v[212:215], v[36:39]
	v_mfma_f32_16x16x32_bf16 v[32:35], v[196:199], v[212:215], v[32:35]
	v_mfma_f32_16x16x32_bf16 v[20:23], v[184:187], v[220:223], v[20:23]
	v_mfma_f32_16x16x32_bf16 v[16:19], v[196:199], v[220:223], v[16:19]
	v_mfma_f32_16x16x32_bf16 v[4:7], v[184:187], v[228:231], v[4:7]
	v_mfma_f32_16x16x32_bf16 v[0:3], v[196:199], v[228:231], v[0:3]
	s_barrier
	s_add_i32 s72, s72, 2
	s_add_u32 s33, s33, 0x100
	s_addc_u32 vcc_lo, vcc_lo, 0
	s_cmp_gt_u32 s72, 9
	s_mov_b64 s[58:59], s[60:61]
	s_cbranch_scc0 .LBB0_777
	s_and_b64 vcc, exec, s[54:55]
	s_cbranch_vccz .LBB0_780
	s_barrier

; #define PG8_STAGE(bufoff, gbase, voff) do { _Pragma("unroll") for (int _i = 0; _i < 2; ++_i) \
;         __builtin_amdgcn_global_load_lds((const unsigned*)((const char*)(gbase) + (voff)[_i]), (PG8_LAS unsigned*)(lds + (bufoff) + ldsw + _i * 8192), 16, 0, 0); } while (0)
; #define PG8_LDA(dst, b, h) do { _Pragma("unroll") for (int m = 0; m < 4; ++m) _Pragma("unroll") for (int k = 0; k < 2; ++k) dst[m][k] = *(const PG8_LAS bf16x8*)(lds + PG8_SA(b, h) + aoff + m * 2048 + k * 1024); } while (0)
; #define PG8_LDB(dst, b, h) do { _Pragma("unroll") for (int n = 0; n < 2; ++n) _Pragma("unroll") for (int k = 0; k < 2; ++k) dst[n][k] = *(const PG8_LAS bf16x8*)(lds + PG8_SB(b, h) + boff + n * 2048 + k * 1024); } while (0)
; #define PG8_MMA(ai, bj, At, Bt) do { __builtin_amdgcn_s_setprio(1); _Pragma("unroll") for (int m = 0; m < 4; ++m) _Pragma("unroll") for (int n = 0; n < 2; ++n) _Pragma("unroll") for (int k = 0; k < 2; ++k) \
;         acc[ai][bj][m][n] = __builtin_amdgcn_mfma_f32_16x16x32_bf16(Bt[n][k], At[m][k], acc[ai][bj][m][n], 0, 0, 0); __builtin_amdgcn_s_setprio(0); } while (0)
; #define PG8_WAIT_V(n) asm volatile("s_waitcnt vmcnt(" #n ")" ::: "memory")
; #define PG8_WAIT_L(n) asm volatile("s_waitcnt lgkmcnt(" #n ")" ::: "memory")
; template <class Epi, class Sched, bool ALIGN_EPI = false, bool SP2 = false>
; __device__ __forceinline__ void gemm_phase(PG8_LAS unsigned char* lds, const Gemm g, const Sched& S, const Epi& E) {
;     ...
;             const bool last = (t == nt - 2);
;             const char* a1 = cA + (size_t)(t + 1) * kstep;
;             const char* a2 = last ? nA : cA + (size_t)(t + 2) * kstep; const char* b2 = last ? nB : cB + (size_t)(t + 2) * kstep;
;             const char* a3 = a2 + kstep; const char* b3 = b2 + kstep;
;             if (last && has_next) S.a_ready(nxt);
;             if constexpr (SP2) {
;             PG8_LDB(B0, 0, 0); PG8_LDB(B1, 0, 1); PG8_SCHED; PG8_LDA(At, 0, 0); PG8_STAGE(PG8_SA(1, 1), a1 + hstep, voffA);
;             PG8_WAIT_V(8); PG8_WAIT_L(0); PG8_BAR; PG8_MMA(0, 0, At, B0); PG8_MMA(0, 1, At, B1); PG8_BAR; PG8_SCHED;
;             PG8_LDA(At, 0, 1); PG8_STAGE(PG8_SB(0, 0), b2, voffB); PG8_STAGE(PG8_SB(0, 1), b2 + hstep, voffB); PG8_STAGE(PG8_SA(0, 0), a2, voffA);
;             PG8_WAIT_V(8); PG8_WAIT_L(0); PG8_BAR; PG8_MMA(1, 0, At, B0); PG8_MMA(1, 1, At, B1); PG8_BAR; PG8_SCHED;
.LBB0_901:
	ds_read_b128 v[144:147], v159
	ds_read_b128 v[168:171], v159 offset:1024
	ds_read_b128 v[172:175], v159 offset:2048
	ds_read_b128 v[176:179], v159 offset:3072
	ds_read_b128 v[180:183], v163
	ds_read_b128 v[184:187], v163 offset:1024
	ds_read_b128 v[188:191], v163 offset:2048
	ds_read_b128 v[196:199], v163 offset:3072
	s_add_u32 s6, s56, 0xfffc0080
	s_addc_u32 s7, s57, -1
	s_cmp_eq_u32 s72, 12
	s_cselect_b32 s61, s49, s7
	s_cselect_b32 s60, s76, s6
	s_cselect_b32 s59, s41, s33
	s_cselect_b32 s58, s77, s78
	s_add_i32 m0, s30, 0xc000
	ds_read_b128 v[200:203], v166
	ds_read_b128 v[204:207], v166 offset:1024
	ds_read_b128 v[208:211], v166 offset:2048
	ds_read_b128 v[212:215], v166 offset:3072
	ds_read_b128 v[216:219], v166 offset:4096
	ds_read_b128 v[220:223], v166 offset:5120
	ds_read_b128 v[224:227], v166 offset:6144
	ds_read_b128 v[228:231], v166 offset:7168
	global_load_lds_dwordx4 v136, s[56:57]
	s_add_i32 m0, s30, 0xe000
	s_nop 0
	global_load_lds_dwordx4 v138, s[56:57]
	s_waitcnt vmcnt(8)
	s_waitcnt lgkmcnt(0)
	s_barrier
	s_waitcnt lgkmcnt(0)
	v_mfma_f32_16x16x32_bf16 v[124:127], v[144:147], v[200:203], v[124:127]
	v_mfma_f32_16x16x32_bf16 v[116:119], v[172:175], v[200:203], v[116:119]
	v_mfma_f32_16x16x32_bf16 v[108:111], v[144:147], v[208:211], v[108:111]
	v_mfma_f32_16x16x32_bf16 v[100:103], v[172:175], v[208:211], v[100:103]
	v_mfma_f32_16x16x32_bf16 v[92:95], v[144:147], v[216:219], v[92:95]
	v_mfma_f32_16x16x32_bf16 v[84:87], v[172:175], v[216:219], v[84:87]
	v_mfma_f32_16x16x32_bf16 v[76:79], v[144:147], v[224:227], v[76:79]
	v_mfma_f32_16x16x32_bf16 v[68:71], v[172:175], v[224:227], v[68:71]
	v_mfma_f32_16x16x32_bf16 v[124:127], v[168:171], v[204:207], v[124:127]
	v_mfma_f32_16x16x32_bf16 v[116:119], v[176:179], v[204:207], v[116:119]
	v_mfma_f32_16x16x32_bf16 v[108:111], v[168:171], v[212:215], v[108:111]
	v_mfma_f32_16x16x32_bf16 v[100:103], v[176:179], v[212:215], v[100:103]
	v_mfma_f32_16x16x32_bf16 v[92:95], v[168:171], v[220:223], v[92:95]
	v_mfma_f32_16x16x32_bf16 v[84:87], v[176:179], v[220:223], v[84:87]
	v_mfma_f32_16x16x32_bf16 v[76:79], v[168:171], v[228:231], v[76:79]
	v_mfma_f32_16x16x32_bf16 v[68:71], v[176:179], v[228:231], v[68:71]
	v_mfma_f32_16x16x32_bf16 v[120:123], v[180:183], v[200:203], v[120:123]
	v_mfma_f32_16x16x32_bf16 v[112:115], v[188:191], v[200:203], v[112:115]
	v_mfma_f32_16x16x32_bf16 v[104:107], v[180:183], v[208:211], v[104:107]
	v_mfma_f32_16x16x32_bf16 v[96:99], v[188:191], v[208:211], v[96:99]
	v_mfma_f32_16x16x32_bf16 v[88:91], v[180:183], v[216:219], v[88:91]
	v_mfma_f32_16x16x32_bf16 v[80:83], v[188:191], v[216:219], v[80:83]
	v_mfma_f32_16x16x32_bf16 v[72:75], v[180:183], v[224:227], v[72:75]
	v_mfma_f32_16x16x32_bf16 v[64:67], v[188:191], v[224:227], v[64:67]
	v_mfma_f32_16x16x32_bf16 v[120:123], v[184:187], v[204:207], v[120:123]
	v_mfma_f32_16x16x32_bf16 v[112:115], v[196:199], v[204:207], v[112:115]
	v_mfma_f32_16x16x32_bf16 v[104:107], v[184:187], v[212:215], v[104:107]
	v_mfma_f32_16x16x32_bf16 v[96:99], v[196:199], v[212:215], v[96:99]
	v_mfma_f32_16x16x32_bf16 v[88:91], v[184:187], v[220:223], v[88:91]
	v_mfma_f32_16x16x32_bf16 v[80:83], v[196:199], v[220:223], v[80:83]
	v_mfma_f32_16x16x32_bf16 v[72:75], v[184:187], v[228:231], v[72:75]
	v_mfma_f32_16x16x32_bf16 v[64:67], v[196:199], v[228:231], v[64:67]
	s_barrier
	s_add_i32 s6, s67, s27
	s_mov_b32 m0, s6
	ds_read_b128 v[200:203], v166 offset:16384
	ds_read_b128 v[204:207], v166 offset:17408
	ds_read_b128 v[208:211], v166 offset:18432
	ds_read_b128 v[212:215], v166 offset:19456
	ds_read_b128 v[216:219], v166 offset:20480
	ds_read_b128 v[220:223], v166 offset:21504
	ds_read_b128 v[224:227], v166 offset:22528
	ds_read_b128 v[228:231], v166 offset:23552
	global_load_lds_dwordx4 v132, s[58:59]
	s_add_i32 m0, s6, 0x2000
	s_add_u32 s6, s58, 0x40000
	s_addc_u32 s7, s59, 0
	s_add_i32 s73, s68, s27
	global_load_lds_dwordx4 v128, s[58:59]
	s_mov_b32 m0, s73
	global_load_lds_dwordx4 v132, s[6:7]
	s_add_i32 m0, s73, 0x2000
	s_nop 0
	global_load_lds_dwordx4 v128, s[6:7]
	s_mov_b32 m0, s30
	s_nop 0
	global_load_lds_dwordx4 v134, s[60:61]
	s_mov_b32 m0, s31
	s_nop 0
	global_load_lds_dwordx4 v130, s[60:61]
	s_waitcnt vmcnt(8)
	s_waitcnt lgkmcnt(0)
	s_barrier
	s_waitcnt lgkmcnt(0)
	v_mfma_f32_16x16x32_bf16 v[60:63], v[144:147], v[200:203], v[60:63]
	v_mfma_f32_16x16x32_bf16 v[52:55], v[172:175], v[200:203], v[52:55]
	v_mfma_f32_16x16x32_bf16 v[44:47], v[144:147], v[208:211], v[44:47]
	v_mfma_f32_16x16x32_bf16 v[36:39], v[172:175], v[208:211], v[36:39]
	v_mfma_f32_16x16x32_bf16 v[28:31], v[144:147], v[216:219], v[28:31]
	v_mfma_f32_16x16x32_bf16 v[20:23], v[172:175], v[216:219], v[20:23]
	v_mfma_f32_16x16x32_bf16 v[12:15], v[144:147], v[224:227], v[12:15]
	v_mfma_f32_16x16x32_bf16 v[4:7], v[172:175], v[224:227], v[4:7]
	v_mfma_f32_16x16x32_bf16 v[60:63], v[168:171], v[204:207], v[60:63]
	v_mfma_f32_16x16x32_bf16 v[52:55], v[176:179], v[204:207], v[52:55]
	v_mfma_f32_16x16x32_bf16 v[44:47], v[168:171], v[212:215], v[44:47]
	v_mfma_f32_16x16x32_bf16 v[36:39], v[176:179], v[212:215], v[36:39]
	v_mfma_f32_16x16x32_bf16 v[28:31], v[168:171], v[220:223], v[28:31]
	v_mfma_f32_16x16x32_bf16 v[20:23], v[176:179], v[220:223], v[20:23]
	v_mfma_f32_16x16x32_bf16 v[12:15], v[168:171], v[228:231], v[12:15]
	v_mfma_f32_16x16x32_bf16 v[4:7], v[176:179], v[228:231], v[4:7]
	v_mfma_f32_16x16x32_bf16 v[56:59], v[180:183], v[200:203], v[56:59]
	v_mfma_f32_16x16x32_bf16 v[48:51], v[188:191], v[200:203], v[48:51]
	v_mfma_f32_16x16x32_bf16 v[40:43], v[180:183], v[208:211], v[40:43]
	v_mfma_f32_16x16x32_bf16 v[32:35], v[188:191], v[208:211], v[32:35]
	v_mfma_f32_16x16x32_bf16 v[24:27], v[180:183], v[216:219], v[24:27]
	v_mfma_f32_16x16x32_bf16 v[16:19], v[188:191], v[216:219], v[16:19]
	v_mfma_f32_16x16x32_bf16 v[8:11], v[180:183], v[224:227], v[8:11]
	v_mfma_f32_16x16x32_bf16 v[0:3], v[188:191], v[224:227], v[0:3]
	v_mfma_f32_16x16x32_bf16 v[56:59], v[184:187], v[204:207], v[56:59]
	v_mfma_f32_16x16x32_bf16 v[48:51], v[196:199], v[204:207], v[48:51]
	v_mfma_f32_16x16x32_bf16 v[40:43], v[184:187], v[212:215], v[40:43]
	v_mfma_f32_16x16x32_bf16 v[32:35], v[196:199], v[212:215], v[32:35]
	v_mfma_f32_16x16x32_bf16 v[24:27], v[184:187], v[220:223], v[24:27]
	v_mfma_f32_16x16x32_bf16 v[16:19], v[196:199], v[220:223], v[16:19]
	v_mfma_f32_16x16x32_bf16 v[8:11], v[184:187], v[228:231], v[8:11]
	v_mfma_f32_16x16x32_bf16 v[0:3], v[196:199], v[228:231], v[0:3]
	s_barrier
; #define PG8_STAGE(bufoff, gbase, voff) do { _Pragma("unroll") for (int _i = 0; _i < 2; ++_i) \
;         __builtin_amdgcn_global_load_lds((const unsigned*)((const char*)(gbase) + (voff)[_i]), (PG8_LAS unsigned*)(lds + (bufoff) + ldsw + _i * 8192), 16, 0, 0); } while (0)
; #define PG8_LDA(dst, b, h) do { _Pragma("unroll") for (int m = 0; m < 4; ++m) _Pragma("unroll") for (int k = 0; k < 2; ++k) dst[m][k] = *(const PG8_LAS bf16x8*)(lds + PG8_SA(b, h) + aoff + m * 2048 + k * 1024); } while (0)
; #define PG8_LDB(dst, b, h) do { _Pragma("unroll") for (int n = 0; n < 2; ++n) _Pragma("unroll") for (int k = 0; k < 2; ++k) dst[n][k] = *(const PG8_LAS bf16x8*)(lds + PG8_SB(b, h) + boff + n * 2048 + k * 1024); } while (0)
; #define PG8_MMA(ai, bj, At, Bt) do { __builtin_amdgcn_s_setprio(1); _Pragma("unroll") for (int m = 0; m < 4; ++m) _Pragma("unroll") for (int n = 0; n < 2; ++n) _Pragma("unroll") for (int k = 0; k < 2; ++k) \
;         acc[ai][bj][m][n] = __builtin_amdgcn_mfma_f32_16x16x32_bf16(Bt[n][k], At[m][k], acc[ai][bj][m][n], 0, 0, 0); __builtin_amdgcn_s_setprio(0); } while (0)
; #define PG8_WAIT_V(n) asm volatile("s_waitcnt vmcnt(" #n ")" ::: "memory")
; #define PG8_WAIT_L(n) asm volatile("s_waitcnt lgkmcnt(" #n ")" ::: "memory")
; #define PG8_BAR __builtin_amdgcn_s_barrier()
; #define PG8_SCHED __builtin_amdgcn_sched_barrier(0)
; template <class Epi, class Sched, bool ALIGN_EPI = false, bool SP2 = false>
; __device__ __forceinline__ void gemm_phase(PG8_LAS unsigned char* lds, const Gemm g, const Sched& S, const Epi& E) {
;     ...
;             PG8_LDB(B0, 1, 0); PG8_LDB(B1, 1, 1); PG8_SCHED; PG8_LDA(At, 1, 0); PG8_STAGE(PG8_SA(0, 1), a2 + hstep, voffA);
;             PG8_WAIT_V(8); PG8_WAIT_L(0); PG8_BAR; PG8_MMA(0, 0, At, B0); PG8_MMA(0, 1, At, B1); PG8_BAR; PG8_SCHED;
;             PG8_LDA(At, 1, 1); PG8_STAGE(PG8_SB(1, 0), b3, voffB); PG8_STAGE(PG8_SB(1, 1), b3 + hstep, voffB); PG8_STAGE(PG8_SA(1, 0), a3, voffA);
;             PG8_WAIT_V(8); PG8_WAIT_L(0); PG8_BAR; PG8_MMA(1, 0, At, B0); PG8_MMA(1, 1, At, B1); PG8_BAR; PG8_SCHED;
	s_add_i32 s73, 0, 0x18000
	v_add_u32_e32 v167, s73, v156
	s_add_i32 s79, 0, 0x1c000
	ds_read_b128 v[144:147], v167
	ds_read_b128 v[168:171], v167 offset:1024
	ds_read_b128 v[172:175], v167 offset:2048
	ds_read_b128 v[176:179], v167 offset:3072
	v_add_u32_e32 v167, s79, v156
	ds_read_b128 v[180:183], v167
	ds_read_b128 v[184:187], v167 offset:1024
	ds_read_b128 v[188:191], v167 offset:2048
	ds_read_b128 v[196:199], v167 offset:3072
	s_add_u32 s6, s60, 0x40000
	s_addc_u32 s7, s61, 0
	s_mov_b32 m0, s42
	ds_read_b128 v[200:203], v166 offset:32768
	ds_read_b128 v[204:207], v166 offset:33792
	ds_read_b128 v[208:211], v166 offset:34816
	ds_read_b128 v[212:215], v166 offset:35840
	ds_read_b128 v[216:219], v166 offset:36864
	ds_read_b128 v[220:223], v166 offset:37888
	ds_read_b128 v[224:227], v166 offset:38912
	ds_read_b128 v[228:231], v166 offset:39936
	global_load_lds_dwordx4 v134, s[6:7]
	s_mov_b32 m0, s43
	s_nop 0
	global_load_lds_dwordx4 v130, s[6:7]
	s_waitcnt vmcnt(8)
	s_waitcnt lgkmcnt(0)
	s_barrier
	s_waitcnt lgkmcnt(0)
	v_mfma_f32_16x16x32_bf16 v[124:127], v[144:147], v[200:203], v[124:127]
	v_mfma_f32_16x16x32_bf16 v[116:119], v[172:175], v[200:203], v[116:119]
	v_mfma_f32_16x16x32_bf16 v[108:111], v[144:147], v[208:211], v[108:111]
	v_mfma_f32_16x16x32_bf16 v[100:103], v[172:175], v[208:211], v[100:103]
	v_mfma_f32_16x16x32_bf16 v[92:95], v[144:147], v[216:219], v[92:95]
	v_mfma_f32_16x16x32_bf16 v[84:87], v[172:175], v[216:219], v[84:87]
	v_mfma_f32_16x16x32_bf16 v[76:79], v[144:147], v[224:227], v[76:79]
	v_mfma_f32_16x16x32_bf16 v[68:71], v[172:175], v[224:227], v[68:71]
	v_mfma_f32_16x16x32_bf16 v[124:127], v[168:171], v[204:207], v[124:127]
	v_mfma_f32_16x16x32_bf16 v[116:119], v[176:179], v[204:207], v[116:119]
	v_mfma_f32_16x16x32_bf16 v[108:111], v[168:171], v[212:215], v[108:111]
	v_mfma_f32_16x16x32_bf16 v[100:103], v[176:179], v[212:215], v[100:103]
	v_mfma_f32_16x16x32_bf16 v[92:95], v[168:171], v[220:223], v[92:95]
	v_mfma_f32_16x16x32_bf16 v[84:87], v[176:179], v[220:223], v[84:87]
	v_mfma_f32_16x16x32_bf16 v[76:79], v[168:171], v[228:231], v[76:79]
	v_mfma_f32_16x16x32_bf16 v[68:71], v[176:179], v[228:231], v[68:71]
	v_mfma_f32_16x16x32_bf16 v[120:123], v[180:183], v[200:203], v[120:123]
	v_mfma_f32_16x16x32_bf16 v[112:115], v[188:191], v[200:203], v[112:115]
	v_mfma_f32_16x16x32_bf16 v[104:107], v[180:183], v[208:211], v[104:107]
	v_mfma_f32_16x16x32_bf16 v[96:99], v[188:191], v[208:211], v[96:99]
	v_mfma_f32_16x16x32_bf16 v[88:91], v[180:183], v[216:219], v[88:91]
	v_mfma_f32_16x16x32_bf16 v[80:83], v[188:191], v[216:219], v[80:83]
	v_mfma_f32_16x16x32_bf16 v[72:75], v[180:183], v[224:227], v[72:75]
	v_mfma_f32_16x16x32_bf16 v[64:67], v[188:191], v[224:227], v[64:67]
	v_mfma_f32_16x16x32_bf16 v[120:123], v[184:187], v[204:207], v[120:123]
	v_mfma_f32_16x16x32_bf16 v[112:115], v[196:199], v[204:207], v[112:115]
	v_mfma_f32_16x16x32_bf16 v[104:107], v[184:187], v[212:215], v[104:107]
	v_mfma_f32_16x16x32_bf16 v[96:99], v[196:199], v[212:215], v[96:99]
	v_mfma_f32_16x16x32_bf16 v[88:91], v[184:187], v[220:223], v[88:91]
	v_mfma_f32_16x16x32_bf16 v[80:83], v[196:199], v[220:223], v[80:83]
	v_mfma_f32_16x16x32_bf16 v[72:75], v[184:187], v[228:231], v[72:75]
	v_mfma_f32_16x16x32_bf16 v[64:67], v[196:199], v[228:231], v[64:67]
	s_barrier
	s_add_i32 s6, s73, s27
	s_add_u32 s98, s58, 0x80
	s_addc_u32 s99, s59, 0
	s_add_u32 s100, s60, 0x80
	s_addc_u32 s101, s61, 0
	s_mov_b32 m0, s6
	ds_read_b128 v[200:203], v166 offset:49152
	ds_read_b128 v[204:207], v166 offset:50176
	ds_read_b128 v[208:211], v166 offset:51200
	ds_read_b128 v[212:215], v166 offset:52224
	ds_read_b128 v[216:219], v166 offset:53248
	ds_read_b128 v[220:223], v166 offset:54272
	ds_read_b128 v[224:227], v166 offset:55296
	ds_read_b128 v[228:231], v166 offset:56320
	global_load_lds_dwordx4 v132, s[98:99]
	s_add_i32 m0, s6, 0x2000
	s_add_u32 s6, s58, 0x40080
	s_addc_u32 s7, s59, 0
	s_add_i32 s58, s79, s27
	global_load_lds_dwordx4 v128, s[98:99]
	s_mov_b32 m0, s58
	s_nop 0
	global_load_lds_dwordx4 v132, s[6:7]
	s_add_i32 m0, s58, 0x2000
	s_nop 0
	global_load_lds_dwordx4 v128, s[6:7]
	s_mov_b32 m0, s44
	s_nop 0
	global_load_lds_dwordx4 v134, s[100:101]
	s_mov_b32 m0, s45
	s_nop 0
	global_load_lds_dwordx4 v130, s[100:101]
	s_waitcnt vmcnt(8)
	s_waitcnt lgkmcnt(0)
	s_barrier
	s_waitcnt lgkmcnt(0)
	v_mfma_f32_16x16x32_bf16 v[60:63], v[144:147], v[200:203], v[60:63]
	v_mfma_f32_16x16x32_bf16 v[52:55], v[172:175], v[200:203], v[52:55]
	v_mfma_f32_16x16x32_bf16 v[44:47], v[144:147], v[208:211], v[44:47]
	v_mfma_f32_16x16x32_bf16 v[36:39], v[172:175], v[208:211], v[36:39]
	v_mfma_f32_16x16x32_bf16 v[28:31], v[144:147], v[216:219], v[28:31]
	v_mfma_f32_16x16x32_bf16 v[20:23], v[172:175], v[216:219], v[20:23]
	v_mfma_f32_16x16x32_bf16 v[12:15], v[144:147], v[224:227], v[12:15]
	v_mfma_f32_16x16x32_bf16 v[4:7], v[172:175], v[224:227], v[4:7]
	v_mfma_f32_16x16x32_bf16 v[60:63], v[168:171], v[204:207], v[60:63]
	v_mfma_f32_16x16x32_bf16 v[52:55], v[176:179], v[204:207], v[52:55]
	v_mfma_f32_16x16x32_bf16 v[44:47], v[168:171], v[212:215], v[44:47]
	v_mfma_f32_16x16x32_bf16 v[36:39], v[176:179], v[212:215], v[36:39]
	v_mfma_f32_16x16x32_bf16 v[28:31], v[168:171], v[220:223], v[28:31]
	v_mfma_f32_16x16x32_bf16 v[20:23], v[176:179], v[220:223], v[20:23]
	v_mfma_f32_16x16x32_bf16 v[12:15], v[168:171], v[228:231], v[12:15]
	v_mfma_f32_16x16x32_bf16 v[4:7], v[176:179], v[228:231], v[4:7]
	v_mfma_f32_16x16x32_bf16 v[56:59], v[180:183], v[200:203], v[56:59]
	v_mfma_f32_16x16x32_bf16 v[48:51], v[188:191], v[200:203], v[48:51]
	v_mfma_f32_16x16x32_bf16 v[40:43], v[180:183], v[208:211], v[40:43]
	v_mfma_f32_16x16x32_bf16 v[32:35], v[188:191], v[208:211], v[32:35]
	v_mfma_f32_16x16x32_bf16 v[24:27], v[180:183], v[216:219], v[24:27]
	v_mfma_f32_16x16x32_bf16 v[16:19], v[188:191], v[216:219], v[16:19]
	v_mfma_f32_16x16x32_bf16 v[8:11], v[180:183], v[224:227], v[8:11]
	v_mfma_f32_16x16x32_bf16 v[0:3], v[188:191], v[224:227], v[0:3]
	v_mfma_f32_16x16x32_bf16 v[56:59], v[184:187], v[204:207], v[56:59]
	v_mfma_f32_16x16x32_bf16 v[48:51], v[196:199], v[204:207], v[48:51]
	v_mfma_f32_16x16x32_bf16 v[40:43], v[184:187], v[212:215], v[40:43]
	v_mfma_f32_16x16x32_bf16 v[32:35], v[196:199], v[212:215], v[32:35]
	v_mfma_f32_16x16x32_bf16 v[24:27], v[184:187], v[220:223], v[24:27]
	v_mfma_f32_16x16x32_bf16 v[16:19], v[196:199], v[220:223], v[16:19]
	v_mfma_f32_16x16x32_bf16 v[8:11], v[184:187], v[228:231], v[8:11]
	v_mfma_f32_16x16x32_bf16 v[0:3], v[196:199], v[228:231], v[0:3]
	s_barrier
	s_add_i32 s72, s72, 2
	s_add_u32 s56, s56, 0x100
	s_addc_u32 s57, s57, 0
	s_add_u32 s78, s78, 0x100
	s_addc_u32 s33, s33, 0
	s_cmp_gt_u32 s72, 13
	s_cbranch_scc0 .LBB0_901
	s_and_b64 vcc, exec, s[38:39]
	s_cbranch_vccz .LBB0_904
	s_barrier

; #define PG8_STAGE(bufoff, gbase, voff) do { _Pragma("unroll") for (int _i = 0; _i < 2; ++_i) \
;         __builtin_amdgcn_global_load_lds((const unsigned*)((const char*)(gbase) + (voff)[_i]), (PG8_LAS unsigned*)(lds + (bufoff) + ldsw + _i * 8192), 16, 0, 0); } while (0)
; #define PG8_LDA(dst, b, h) do { _Pragma("unroll") for (int m = 0; m < 4; ++m) _Pragma("unroll") for (int k = 0; k < 2; ++k) dst[m][k] = *(const PG8_LAS bf16x8*)(lds + PG8_SA(b, h) + aoff + m * 2048 + k * 1024); } while (0)
; #define PG8_LDB(dst, b, h) do { _Pragma("unroll") for (int n = 0; n < 2; ++n) _Pragma("unroll") for (int k = 0; k < 2; ++k) dst[n][k] = *(const PG8_LAS bf16x8*)(lds + PG8_SB(b, h) + boff + n * 2048 + k * 1024); } while (0)
; #define PG8_MMA(ai, bj, At, Bt) do { __builtin_amdgcn_s_setprio(1); _Pragma("unroll") for (int m = 0; m < 4; ++m) _Pragma("unroll") for (int n = 0; n < 2; ++n) _Pragma("unroll") for (int k = 0; k < 2; ++k) \
;         acc[ai][bj][m][n] = __builtin_amdgcn_mfma_f32_16x16x32_bf16(Bt[n][k], At[m][k], acc[ai][bj][m][n], 0, 0, 0); __builtin_amdgcn_s_setprio(0); } while (0)
; #define PG8_WAIT_V(n) asm volatile("s_waitcnt vmcnt(" #n ")" ::: "memory")
; #define PG8_WAIT_L(n) asm volatile("s_waitcnt lgkmcnt(" #n ")" ::: "memory")
; template <class Epi, class Sched, bool ALIGN_EPI = false, bool SP2 = false>
; __device__ __forceinline__ void gemm_phase(PG8_LAS unsigned char* lds, const Gemm g, const Sched& S, const Epi& E) {
;     ...
;             const bool last = (t == nt - 2);
;             const char* a1 = cA + (size_t)(t + 1) * kstep;
;             const char* a2 = last ? nA : cA + (size_t)(t + 2) * kstep; const char* b2 = last ? nB : cB + (size_t)(t + 2) * kstep;
;             const char* a3 = a2 + kstep; const char* b3 = b2 + kstep;
;             if (last && has_next) S.a_ready(nxt);
;             if constexpr (SP2) {
;             PG8_LDB(B0, 0, 0); PG8_LDB(B1, 0, 1); PG8_SCHED; PG8_LDA(At, 0, 0); PG8_STAGE(PG8_SA(1, 1), a1 + hstep, voffA);
;             PG8_WAIT_V(8); PG8_WAIT_L(0); PG8_BAR; PG8_MMA(0, 0, At, B0); PG8_MMA(0, 1, At, B1); PG8_BAR; PG8_SCHED;
;             PG8_LDA(At, 0, 1); PG8_STAGE(PG8_SB(0, 0), b2, voffB); PG8_STAGE(PG8_SB(0, 1), b2 + hstep, voffB); PG8_STAGE(PG8_SA(0, 0), a2, voffA);
;             PG8_WAIT_V(8); PG8_WAIT_L(0); PG8_BAR; PG8_MMA(1, 0, At, B0); PG8_MMA(1, 1, At, B1); PG8_BAR; PG8_SCHED;
.LBB0_1014:
	ds_read_b128 v[144:147], v158
	ds_read_b128 v[168:171], v158 offset:1024
	ds_read_b128 v[172:175], v158 offset:2048
	ds_read_b128 v[176:179], v158 offset:3072
	ds_read_b128 v[180:183], v159
	ds_read_b128 v[184:187], v159 offset:1024
	ds_read_b128 v[188:191], v159 offset:2048
	ds_read_b128 v[196:199], v159 offset:3072
	s_add_u32 s58, s56, 0x100
	s_addc_u32 s59, s57, 0
	s_cmp_eq_u32 s72, 40
	s_cselect_b32 s79, s51, s59
	s_cselect_b32 s78, s50, s58
	s_cselect_b32 s61, s55, s80
	s_cselect_b32 s60, s54, s33
	s_add_i32 m0, s45, 0xc000
	ds_read_b128 v[200:203], v163
	ds_read_b128 v[204:207], v163 offset:1024
	ds_read_b128 v[208:211], v163 offset:2048
	ds_read_b128 v[212:215], v163 offset:3072
	ds_read_b128 v[216:219], v163 offset:4096
	ds_read_b128 v[220:223], v163 offset:5120
	ds_read_b128 v[224:227], v163 offset:6144
	ds_read_b128 v[228:231], v163 offset:7168
	global_load_lds_dwordx4 v136, s[56:57]
	s_add_i32 m0, s45, 0xe000
	s_nop 0
	global_load_lds_dwordx4 v138, s[56:57]
	s_waitcnt vmcnt(8)
	s_waitcnt lgkmcnt(0)
	s_barrier
	s_waitcnt lgkmcnt(0)
	v_mfma_f32_16x16x32_bf16 v[124:127], v[144:147], v[200:203], v[124:127]
	v_mfma_f32_16x16x32_bf16 v[120:123], v[172:175], v[200:203], v[120:123]
	v_mfma_f32_16x16x32_bf16 v[108:111], v[144:147], v[208:211], v[108:111]
	v_mfma_f32_16x16x32_bf16 v[104:107], v[172:175], v[208:211], v[104:107]
	v_mfma_f32_16x16x32_bf16 v[92:95], v[144:147], v[216:219], v[92:95]
	v_mfma_f32_16x16x32_bf16 v[88:91], v[172:175], v[216:219], v[88:91]
	v_mfma_f32_16x16x32_bf16 v[76:79], v[144:147], v[224:227], v[76:79]
	v_mfma_f32_16x16x32_bf16 v[72:75], v[172:175], v[224:227], v[72:75]
	v_mfma_f32_16x16x32_bf16 v[124:127], v[168:171], v[204:207], v[124:127]
	v_mfma_f32_16x16x32_bf16 v[120:123], v[176:179], v[204:207], v[120:123]
	v_mfma_f32_16x16x32_bf16 v[108:111], v[168:171], v[212:215], v[108:111]
	v_mfma_f32_16x16x32_bf16 v[104:107], v[176:179], v[212:215], v[104:107]
	v_mfma_f32_16x16x32_bf16 v[92:95], v[168:171], v[220:223], v[92:95]
	v_mfma_f32_16x16x32_bf16 v[88:91], v[176:179], v[220:223], v[88:91]
	v_mfma_f32_16x16x32_bf16 v[76:79], v[168:171], v[228:231], v[76:79]
	v_mfma_f32_16x16x32_bf16 v[72:75], v[176:179], v[228:231], v[72:75]
	v_mfma_f32_16x16x32_bf16 v[116:119], v[180:183], v[200:203], v[116:119]
	v_mfma_f32_16x16x32_bf16 v[112:115], v[188:191], v[200:203], v[112:115]
	v_mfma_f32_16x16x32_bf16 v[100:103], v[180:183], v[208:211], v[100:103]
	v_mfma_f32_16x16x32_bf16 v[96:99], v[188:191], v[208:211], v[96:99]
	v_mfma_f32_16x16x32_bf16 v[84:87], v[180:183], v[216:219], v[84:87]
	v_mfma_f32_16x16x32_bf16 v[80:83], v[188:191], v[216:219], v[80:83]
	v_mfma_f32_16x16x32_bf16 v[68:71], v[180:183], v[224:227], v[68:71]
	v_mfma_f32_16x16x32_bf16 v[64:67], v[188:191], v[224:227], v[64:67]
	v_mfma_f32_16x16x32_bf16 v[116:119], v[184:187], v[204:207], v[116:119]
	v_mfma_f32_16x16x32_bf16 v[112:115], v[196:199], v[204:207], v[112:115]
	v_mfma_f32_16x16x32_bf16 v[100:103], v[184:187], v[212:215], v[100:103]
	v_mfma_f32_16x16x32_bf16 v[96:99], v[196:199], v[212:215], v[96:99]
	v_mfma_f32_16x16x32_bf16 v[84:87], v[184:187], v[220:223], v[84:87]
	v_mfma_f32_16x16x32_bf16 v[80:83], v[196:199], v[220:223], v[80:83]
	v_mfma_f32_16x16x32_bf16 v[68:71], v[184:187], v[228:231], v[68:71]
	v_mfma_f32_16x16x32_bf16 v[64:67], v[196:199], v[228:231], v[64:67]
	s_barrier
	s_add_i32 s6, s26, s44
	s_mov_b32 m0, s6
	ds_read_b128 v[200:203], v163 offset:16384
	ds_read_b128 v[204:207], v163 offset:17408
	ds_read_b128 v[208:211], v163 offset:18432
	ds_read_b128 v[212:215], v163 offset:19456
	ds_read_b128 v[216:219], v163 offset:20480
	ds_read_b128 v[220:223], v163 offset:21504
	ds_read_b128 v[224:227], v163 offset:22528
	ds_read_b128 v[228:231], v163 offset:23552
	global_load_lds_dwordx4 v130, s[60:61]
	s_add_i32 m0, s6, 0x2000
	s_add_u32 s6, s60, 0xb0000
	s_addc_u32 s7, s61, 0
	s_add_i32 s56, s74, s44
	global_load_lds_dwordx4 v134, s[60:61]
	s_mov_b32 m0, s56
	global_load_lds_dwordx4 v130, s[6:7]
	s_add_i32 m0, s56, 0x2000
	s_nop 0
	global_load_lds_dwordx4 v134, s[6:7]
	s_mov_b32 m0, s45
	s_nop 0
	global_load_lds_dwordx4 v128, s[78:79]
	s_mov_b32 m0, s67
	s_nop 0
	global_load_lds_dwordx4 v132, s[78:79]
	s_waitcnt vmcnt(8)
	s_waitcnt lgkmcnt(0)
	s_barrier
	s_waitcnt lgkmcnt(0)
	v_mfma_f32_16x16x32_bf16 v[60:63], v[144:147], v[200:203], v[60:63]
	v_mfma_f32_16x16x32_bf16 v[56:59], v[172:175], v[200:203], v[56:59]
	v_mfma_f32_16x16x32_bf16 v[44:47], v[144:147], v[208:211], v[44:47]
	v_mfma_f32_16x16x32_bf16 v[40:43], v[172:175], v[208:211], v[40:43]
	v_mfma_f32_16x16x32_bf16 v[28:31], v[144:147], v[216:219], v[28:31]
	v_mfma_f32_16x16x32_bf16 v[24:27], v[172:175], v[216:219], v[24:27]
	v_mfma_f32_16x16x32_bf16 v[12:15], v[144:147], v[224:227], v[12:15]
	v_mfma_f32_16x16x32_bf16 v[8:11], v[172:175], v[224:227], v[8:11]
	v_mfma_f32_16x16x32_bf16 v[60:63], v[168:171], v[204:207], v[60:63]
	v_mfma_f32_16x16x32_bf16 v[56:59], v[176:179], v[204:207], v[56:59]
	v_mfma_f32_16x16x32_bf16 v[44:47], v[168:171], v[212:215], v[44:47]
	v_mfma_f32_16x16x32_bf16 v[40:43], v[176:179], v[212:215], v[40:43]
	v_mfma_f32_16x16x32_bf16 v[28:31], v[168:171], v[220:223], v[28:31]
	v_mfma_f32_16x16x32_bf16 v[24:27], v[176:179], v[220:223], v[24:27]
	v_mfma_f32_16x16x32_bf16 v[12:15], v[168:171], v[228:231], v[12:15]
	v_mfma_f32_16x16x32_bf16 v[8:11], v[176:179], v[228:231], v[8:11]
	v_mfma_f32_16x16x32_bf16 v[52:55], v[180:183], v[200:203], v[52:55]
	v_mfma_f32_16x16x32_bf16 v[48:51], v[188:191], v[200:203], v[48:51]
	v_mfma_f32_16x16x32_bf16 v[36:39], v[180:183], v[208:211], v[36:39]
	v_mfma_f32_16x16x32_bf16 v[32:35], v[188:191], v[208:211], v[32:35]
	v_mfma_f32_16x16x32_bf16 v[20:23], v[180:183], v[216:219], v[20:23]
	v_mfma_f32_16x16x32_bf16 v[16:19], v[188:191], v[216:219], v[16:19]
	v_mfma_f32_16x16x32_bf16 v[4:7], v[180:183], v[224:227], v[4:7]
	v_mfma_f32_16x16x32_bf16 v[0:3], v[188:191], v[224:227], v[0:3]
	v_mfma_f32_16x16x32_bf16 v[52:55], v[184:187], v[204:207], v[52:55]
	v_mfma_f32_16x16x32_bf16 v[48:51], v[196:199], v[204:207], v[48:51]
	v_mfma_f32_16x16x32_bf16 v[36:39], v[184:187], v[212:215], v[36:39]
	v_mfma_f32_16x16x32_bf16 v[32:35], v[196:199], v[212:215], v[32:35]
	v_mfma_f32_16x16x32_bf16 v[20:23], v[184:187], v[220:223], v[20:23]
	v_mfma_f32_16x16x32_bf16 v[16:19], v[196:199], v[220:223], v[16:19]
	v_mfma_f32_16x16x32_bf16 v[4:7], v[184:187], v[228:231], v[4:7]
	v_mfma_f32_16x16x32_bf16 v[0:3], v[196:199], v[228:231], v[0:3]
	s_barrier
; #define PG8_STAGE(bufoff, gbase, voff) do { _Pragma("unroll") for (int _i = 0; _i < 2; ++_i) \
;         __builtin_amdgcn_global_load_lds((const unsigned*)((const char*)(gbase) + (voff)[_i]), (PG8_LAS unsigned*)(lds + (bufoff) + ldsw + _i * 8192), 16, 0, 0); } while (0)
; #define PG8_LDA(dst, b, h) do { _Pragma("unroll") for (int m = 0; m < 4; ++m) _Pragma("unroll") for (int k = 0; k < 2; ++k) dst[m][k] = *(const PG8_LAS bf16x8*)(lds + PG8_SA(b, h) + aoff + m * 2048 + k * 1024); } while (0)
; #define PG8_LDB(dst, b, h) do { _Pragma("unroll") for (int n = 0; n < 2; ++n) _Pragma("unroll") for (int k = 0; k < 2; ++k) dst[n][k] = *(const PG8_LAS bf16x8*)(lds + PG8_SB(b, h) + boff + n * 2048 + k * 1024); } while (0)
; #define PG8_MMA(ai, bj, At, Bt) do { __builtin_amdgcn_s_setprio(1); _Pragma("unroll") for (int m = 0; m < 4; ++m) _Pragma("unroll") for (int n = 0; n < 2; ++n) _Pragma("unroll") for (int k = 0; k < 2; ++k) \
;         acc[ai][bj][m][n] = __builtin_amdgcn_mfma_f32_16x16x32_bf16(Bt[n][k], At[m][k], acc[ai][bj][m][n], 0, 0, 0); __builtin_amdgcn_s_setprio(0); } while (0)
; #define PG8_WAIT_V(n) asm volatile("s_waitcnt vmcnt(" #n ")" ::: "memory")
; #define PG8_WAIT_L(n) asm volatile("s_waitcnt lgkmcnt(" #n ")" ::: "memory")
; #define PG8_BAR __builtin_amdgcn_s_barrier()
; #define PG8_SCHED __builtin_amdgcn_sched_barrier(0)
; template <class Epi, class Sched, bool ALIGN_EPI = false, bool SP2 = false>
; __device__ __forceinline__ void gemm_phase(PG8_LAS unsigned char* lds, const Gemm g, const Sched& S, const Epi& E) {
;     ...
;             PG8_LDB(B0, 1, 0); PG8_LDB(B1, 1, 1); PG8_SCHED; PG8_LDA(At, 1, 0); PG8_STAGE(PG8_SA(0, 1), a2 + hstep, voffA);
;             PG8_WAIT_V(8); PG8_WAIT_L(0); PG8_BAR; PG8_MMA(0, 0, At, B0); PG8_MMA(0, 1, At, B1); PG8_BAR; PG8_SCHED;
;             PG8_LDA(At, 1, 1); PG8_STAGE(PG8_SB(1, 0), b3, voffB); PG8_STAGE(PG8_SB(1, 1), b3 + hstep, voffB); PG8_STAGE(PG8_SA(1, 0), a3, voffA);
;             PG8_WAIT_V(8); PG8_WAIT_L(0); PG8_BAR; PG8_MMA(1, 0, At, B0); PG8_MMA(1, 1, At, B1); PG8_BAR; PG8_SCHED;
	s_add_i32 s56, 0, 0x18000
	v_add_u32_e32 v167, s56, v156
	s_add_i32 s57, 0, 0x1c000
	ds_read_b128 v[144:147], v167
	ds_read_b128 v[168:171], v167 offset:1024
	ds_read_b128 v[172:175], v167 offset:2048
	ds_read_b128 v[176:179], v167 offset:3072
	v_add_u32_e32 v167, s57, v156
	ds_read_b128 v[180:183], v167
	ds_read_b128 v[184:187], v167 offset:1024
	ds_read_b128 v[188:191], v167 offset:2048
	ds_read_b128 v[196:199], v167 offset:3072
	s_add_u32 s6, s78, 0xb0000
	s_addc_u32 s7, s79, 0
	s_mov_b32 m0, s76
	ds_read_b128 v[200:203], v163 offset:32768
	ds_read_b128 v[204:207], v163 offset:33792
	ds_read_b128 v[208:211], v163 offset:34816
	ds_read_b128 v[212:215], v163 offset:35840
	ds_read_b128 v[216:219], v163 offset:36864
	ds_read_b128 v[220:223], v163 offset:37888
	ds_read_b128 v[224:227], v163 offset:38912
	ds_read_b128 v[228:231], v163 offset:39936
	global_load_lds_dwordx4 v128, s[6:7]
	s_mov_b32 m0, s77
	s_nop 0
	global_load_lds_dwordx4 v132, s[6:7]
	s_waitcnt vmcnt(8)
	s_waitcnt lgkmcnt(0)
	s_barrier
	s_waitcnt lgkmcnt(0)
	v_mfma_f32_16x16x32_bf16 v[124:127], v[144:147], v[200:203], v[124:127]
	v_mfma_f32_16x16x32_bf16 v[120:123], v[172:175], v[200:203], v[120:123]
	v_mfma_f32_16x16x32_bf16 v[108:111], v[144:147], v[208:211], v[108:111]
	v_mfma_f32_16x16x32_bf16 v[104:107], v[172:175], v[208:211], v[104:107]
	v_mfma_f32_16x16x32_bf16 v[92:95], v[144:147], v[216:219], v[92:95]
	v_mfma_f32_16x16x32_bf16 v[88:91], v[172:175], v[216:219], v[88:91]
	v_mfma_f32_16x16x32_bf16 v[76:79], v[144:147], v[224:227], v[76:79]
	v_mfma_f32_16x16x32_bf16 v[72:75], v[172:175], v[224:227], v[72:75]
	v_mfma_f32_16x16x32_bf16 v[124:127], v[168:171], v[204:207], v[124:127]
	v_mfma_f32_16x16x32_bf16 v[120:123], v[176:179], v[204:207], v[120:123]
	v_mfma_f32_16x16x32_bf16 v[108:111], v[168:171], v[212:215], v[108:111]
	v_mfma_f32_16x16x32_bf16 v[104:107], v[176:179], v[212:215], v[104:107]
	v_mfma_f32_16x16x32_bf16 v[92:95], v[168:171], v[220:223], v[92:95]
	v_mfma_f32_16x16x32_bf16 v[88:91], v[176:179], v[220:223], v[88:91]
	v_mfma_f32_16x16x32_bf16 v[76:79], v[168:171], v[228:231], v[76:79]
	v_mfma_f32_16x16x32_bf16 v[72:75], v[176:179], v[228:231], v[72:75]
	v_mfma_f32_16x16x32_bf16 v[116:119], v[180:183], v[200:203], v[116:119]
	v_mfma_f32_16x16x32_bf16 v[112:115], v[188:191], v[200:203], v[112:115]
	v_mfma_f32_16x16x32_bf16 v[100:103], v[180:183], v[208:211], v[100:103]
	v_mfma_f32_16x16x32_bf16 v[96:99], v[188:191], v[208:211], v[96:99]
	v_mfma_f32_16x16x32_bf16 v[84:87], v[180:183], v[216:219], v[84:87]
	v_mfma_f32_16x16x32_bf16 v[80:83], v[188:191], v[216:219], v[80:83]
	v_mfma_f32_16x16x32_bf16 v[68:71], v[180:183], v[224:227], v[68:71]
	v_mfma_f32_16x16x32_bf16 v[64:67], v[188:191], v[224:227], v[64:67]
	v_mfma_f32_16x16x32_bf16 v[116:119], v[184:187], v[204:207], v[116:119]
	v_mfma_f32_16x16x32_bf16 v[112:115], v[196:199], v[204:207], v[112:115]
	v_mfma_f32_16x16x32_bf16 v[100:103], v[184:187], v[212:215], v[100:103]
	v_mfma_f32_16x16x32_bf16 v[96:99], v[196:199], v[212:215], v[96:99]
	v_mfma_f32_16x16x32_bf16 v[84:87], v[184:187], v[220:223], v[84:87]
	v_mfma_f32_16x16x32_bf16 v[80:83], v[196:199], v[220:223], v[80:83]
	v_mfma_f32_16x16x32_bf16 v[68:71], v[184:187], v[228:231], v[68:71]
	v_mfma_f32_16x16x32_bf16 v[64:67], v[196:199], v[228:231], v[64:67]
	s_barrier
	s_add_i32 s6, s56, s44
	s_add_u32 s98, s60, 0x80
	s_addc_u32 s99, s61, 0
	s_add_u32 s100, s78, 0x80
	s_addc_u32 s101, s79, 0
	s_mov_b32 m0, s6
	ds_read_b128 v[200:203], v163 offset:49152
	ds_read_b128 v[204:207], v163 offset:50176
	ds_read_b128 v[208:211], v163 offset:51200
	ds_read_b128 v[212:215], v163 offset:52224
	ds_read_b128 v[216:219], v163 offset:53248
	ds_read_b128 v[220:223], v163 offset:54272
	ds_read_b128 v[224:227], v163 offset:55296
	ds_read_b128 v[228:231], v163 offset:56320
	global_load_lds_dwordx4 v130, s[98:99]
	s_add_i32 m0, s6, 0x2000
	s_add_u32 s6, s60, 0xb0080
	s_addc_u32 s7, s61, 0
	s_add_i32 s56, s57, s44
	global_load_lds_dwordx4 v134, s[98:99]
	s_mov_b32 m0, s56
	s_nop 0
	global_load_lds_dwordx4 v130, s[6:7]
	s_add_i32 m0, s56, 0x2000
	s_nop 0
	global_load_lds_dwordx4 v134, s[6:7]
	s_mov_b32 m0, s31
	s_nop 0
	global_load_lds_dwordx4 v128, s[100:101]
	s_mov_b32 m0, s4
	s_nop 0
	global_load_lds_dwordx4 v132, s[100:101]
	s_waitcnt vmcnt(8)
	s_waitcnt lgkmcnt(0)
	s_barrier
	s_waitcnt lgkmcnt(0)
	v_mfma_f32_16x16x32_bf16 v[60:63], v[144:147], v[200:203], v[60:63]
	v_mfma_f32_16x16x32_bf16 v[56:59], v[172:175], v[200:203], v[56:59]
	v_mfma_f32_16x16x32_bf16 v[44:47], v[144:147], v[208:211], v[44:47]
	v_mfma_f32_16x16x32_bf16 v[40:43], v[172:175], v[208:211], v[40:43]
	v_mfma_f32_16x16x32_bf16 v[28:31], v[144:147], v[216:219], v[28:31]
	v_mfma_f32_16x16x32_bf16 v[24:27], v[172:175], v[216:219], v[24:27]
	v_mfma_f32_16x16x32_bf16 v[12:15], v[144:147], v[224:227], v[12:15]
	v_mfma_f32_16x16x32_bf16 v[8:11], v[172:175], v[224:227], v[8:11]
	v_mfma_f32_16x16x32_bf16 v[60:63], v[168:171], v[204:207], v[60:63]
	v_mfma_f32_16x16x32_bf16 v[56:59], v[176:179], v[204:207], v[56:59]
	v_mfma_f32_16x16x32_bf16 v[44:47], v[168:171], v[212:215], v[44:47]
	v_mfma_f32_16x16x32_bf16 v[40:43], v[176:179], v[212:215], v[40:43]
	v_mfma_f32_16x16x32_bf16 v[28:31], v[168:171], v[220:223], v[28:31]
	v_mfma_f32_16x16x32_bf16 v[24:27], v[176:179], v[220:223], v[24:27]
	v_mfma_f32_16x16x32_bf16 v[12:15], v[168:171], v[228:231], v[12:15]
	v_mfma_f32_16x16x32_bf16 v[8:11], v[176:179], v[228:231], v[8:11]
	v_mfma_f32_16x16x32_bf16 v[52:55], v[180:183], v[200:203], v[52:55]
	v_mfma_f32_16x16x32_bf16 v[48:51], v[188:191], v[200:203], v[48:51]
	v_mfma_f32_16x16x32_bf16 v[36:39], v[180:183], v[208:211], v[36:39]
	v_mfma_f32_16x16x32_bf16 v[32:35], v[188:191], v[208:211], v[32:35]
	v_mfma_f32_16x16x32_bf16 v[20:23], v[180:183], v[216:219], v[20:23]
	v_mfma_f32_16x16x32_bf16 v[16:19], v[188:191], v[216:219], v[16:19]
	v_mfma_f32_16x16x32_bf16 v[4:7], v[180:183], v[224:227], v[4:7]
	v_mfma_f32_16x16x32_bf16 v[0:3], v[188:191], v[224:227], v[0:3]
	v_mfma_f32_16x16x32_bf16 v[52:55], v[184:187], v[204:207], v[52:55]
	v_mfma_f32_16x16x32_bf16 v[48:51], v[196:199], v[204:207], v[48:51]
	v_mfma_f32_16x16x32_bf16 v[36:39], v[184:187], v[212:215], v[36:39]
	v_mfma_f32_16x16x32_bf16 v[32:35], v[196:199], v[212:215], v[32:35]
	v_mfma_f32_16x16x32_bf16 v[20:23], v[184:187], v[220:223], v[20:23]
	v_mfma_f32_16x16x32_bf16 v[16:19], v[196:199], v[220:223], v[16:19]
	v_mfma_f32_16x16x32_bf16 v[4:7], v[184:187], v[228:231], v[4:7]
	v_mfma_f32_16x16x32_bf16 v[0:3], v[196:199], v[228:231], v[0:3]
	s_barrier
	s_add_i32 s72, s72, 2
	s_add_u32 s33, s33, 0x100
	s_addc_u32 s80, s80, 0
	s_cmp_gt_u32 s72, 41
	s_mov_b64 s[56:57], s[58:59]
	s_cbranch_scc0 .LBB0_1014
	s_and_b64 vcc, exec, s[52:53]
	s_cbranch_vccz .LBB0_1017
	s_barrier

; #define PG8_STAGE(bufoff, gbase, voff) do { _Pragma("unroll") for (int _i = 0; _i < 2; ++_i) \
;         __builtin_amdgcn_global_load_lds((const unsigned*)((const char*)(gbase) + (voff)[_i]), (PG8_LAS unsigned*)(lds + (bufoff) + ldsw + _i * 8192), 16, 0, 0); } while (0)
; #define PG8_LDA(dst, b, h) do { _Pragma("unroll") for (int m = 0; m < 4; ++m) _Pragma("unroll") for (int k = 0; k < 2; ++k) dst[m][k] = *(const PG8_LAS bf16x8*)(lds + PG8_SA(b, h) + aoff + m * 2048 + k * 1024); } while (0)
; #define PG8_LDB(dst, b, h) do { _Pragma("unroll") for (int n = 0; n < 2; ++n) _Pragma("unroll") for (int k = 0; k < 2; ++k) dst[n][k] = *(const PG8_LAS bf16x8*)(lds + PG8_SB(b, h) + boff + n * 2048 + k * 1024); } while (0)
; #define PG8_MMA(ai, bj, At, Bt) do { __builtin_amdgcn_s_setprio(1); _Pragma("unroll") for (int m = 0; m < 4; ++m) _Pragma("unroll") for (int n = 0; n < 2; ++n) _Pragma("unroll") for (int k = 0; k < 2; ++k) \
;         acc[ai][bj][m][n] = __builtin_amdgcn_mfma_f32_16x16x32_bf16(Bt[n][k], At[m][k], acc[ai][bj][m][n], 0, 0, 0); __builtin_amdgcn_s_setprio(0); } while (0)
; #define PG8_WAIT_V(n) asm volatile("s_waitcnt vmcnt(" #n ")" ::: "memory")
; #define PG8_WAIT_L(n) asm volatile("s_waitcnt lgkmcnt(" #n ")" ::: "memory")
; template <class Epi, class Sched, bool ALIGN_EPI = false, bool SP2 = false>
; __device__ __forceinline__ void gemm_phase(PG8_LAS unsigned char* lds, const Gemm g, const Sched& S, const Epi& E) {
;     ...
;             const bool last = (t == nt - 2);
;             const char* a1 = cA + (size_t)(t + 1) * kstep;
;             const char* a2 = last ? nA : cA + (size_t)(t + 2) * kstep; const char* b2 = last ? nB : cB + (size_t)(t + 2) * kstep;
;             const char* a3 = a2 + kstep; const char* b3 = b2 + kstep;
;             if (last && has_next) S.a_ready(nxt);
;             if constexpr (SP2) {
;             PG8_LDB(B0, 0, 0); PG8_LDB(B1, 0, 1); PG8_SCHED; PG8_LDA(At, 0, 0); PG8_STAGE(PG8_SA(1, 1), a1 + hstep, voffA);
;             PG8_WAIT_V(8); PG8_WAIT_L(0); PG8_BAR; PG8_MMA(0, 0, At, B0); PG8_MMA(0, 1, At, B1); PG8_BAR; PG8_SCHED;
;             PG8_LDA(At, 0, 1); PG8_STAGE(PG8_SB(0, 0), b2, voffB); PG8_STAGE(PG8_SB(0, 1), b2 + hstep, voffB); PG8_STAGE(PG8_SA(0, 0), a2, voffA);
;             PG8_WAIT_V(8); PG8_WAIT_L(0); PG8_BAR; PG8_MMA(1, 0, At, B0); PG8_MMA(1, 1, At, B1); PG8_BAR; PG8_SCHED;
.LBB0_1617:
	ds_read_b128 v[32:35], v191
	ds_read_b128 v[36:39], v191 offset:1024
	ds_read_b128 v[48:51], v191 offset:2048
	ds_read_b128 v[52:55], v191 offset:3072
	ds_read_b128 v[128:131], v195
	ds_read_b128 v[148:151], v195 offset:1024
	ds_read_b128 v[152:155], v195 offset:2048
	ds_read_b128 v[180:183], v195 offset:3072
	s_add_u32 s6, s56, 0xfffc0080
	s_addc_u32 s7, s57, -1
	s_cmp_eq_u32 s69, 12
	s_cselect_b32 s61, s26, s7
	s_cselect_b32 s60, s29, s6
	s_cselect_b32 s59, s49, s33
	s_cselect_b32 s58, s51, s68
	s_add_i32 m0, s78, 0xc000
	ds_read_b128 v[184:187], v198
	ds_read_b128 v[200:203], v198 offset:1024
	ds_read_b128 v[204:207], v198 offset:2048
	ds_read_b128 v[208:211], v198 offset:3072
	ds_read_b128 v[212:215], v198 offset:4096
	ds_read_b128 v[216:219], v198 offset:5120
	ds_read_b128 v[220:223], v198 offset:6144
	ds_read_b128 v[224:227], v198 offset:7168
	global_load_lds_dwordx4 v172, s[56:57]
	s_add_i32 m0, s78, 0xe000
	s_nop 0
	global_load_lds_dwordx4 v174, s[56:57]
	s_waitcnt vmcnt(8)
	s_waitcnt lgkmcnt(0)
	s_barrier
	s_waitcnt lgkmcnt(0)
	v_mfma_f32_16x16x32_bf16 v[144:147], v[32:35], v[184:187], v[144:147]
	v_mfma_f32_16x16x32_bf16 v[140:143], v[48:51], v[184:187], v[140:143]
	v_mfma_f32_16x16x32_bf16 v[124:127], v[32:35], v[204:207], v[124:127]
	v_mfma_f32_16x16x32_bf16 v[120:123], v[48:51], v[204:207], v[120:123]
	v_mfma_f32_16x16x32_bf16 v[108:111], v[32:35], v[212:215], v[108:111]
	v_mfma_f32_16x16x32_bf16 v[104:107], v[48:51], v[212:215], v[104:107]
	v_mfma_f32_16x16x32_bf16 v[92:95], v[32:35], v[220:223], v[92:95]
	v_mfma_f32_16x16x32_bf16 v[88:91], v[48:51], v[220:223], v[88:91]
	v_mfma_f32_16x16x32_bf16 v[144:147], v[36:39], v[200:203], v[144:147]
	v_mfma_f32_16x16x32_bf16 v[140:143], v[52:55], v[200:203], v[140:143]
	v_mfma_f32_16x16x32_bf16 v[124:127], v[36:39], v[208:211], v[124:127]
	v_mfma_f32_16x16x32_bf16 v[120:123], v[52:55], v[208:211], v[120:123]
	v_mfma_f32_16x16x32_bf16 v[108:111], v[36:39], v[216:219], v[108:111]
	v_mfma_f32_16x16x32_bf16 v[104:107], v[52:55], v[216:219], v[104:107]
	v_mfma_f32_16x16x32_bf16 v[92:95], v[36:39], v[224:227], v[92:95]
	v_mfma_f32_16x16x32_bf16 v[88:91], v[52:55], v[224:227], v[88:91]
	v_mfma_f32_16x16x32_bf16 v[136:139], v[128:131], v[184:187], v[136:139]
	v_mfma_f32_16x16x32_bf16 v[132:135], v[152:155], v[184:187], v[132:135]
	v_mfma_f32_16x16x32_bf16 v[116:119], v[128:131], v[204:207], v[116:119]
	v_mfma_f32_16x16x32_bf16 v[112:115], v[152:155], v[204:207], v[112:115]
	v_mfma_f32_16x16x32_bf16 v[100:103], v[128:131], v[212:215], v[100:103]
	v_mfma_f32_16x16x32_bf16 v[96:99], v[152:155], v[212:215], v[96:99]
	v_mfma_f32_16x16x32_bf16 v[84:87], v[128:131], v[220:223], v[84:87]
	v_mfma_f32_16x16x32_bf16 v[80:83], v[152:155], v[220:223], v[80:83]
	v_mfma_f32_16x16x32_bf16 v[136:139], v[148:151], v[200:203], v[136:139]
	v_mfma_f32_16x16x32_bf16 v[132:135], v[180:183], v[200:203], v[132:135]
	v_mfma_f32_16x16x32_bf16 v[116:119], v[148:151], v[208:211], v[116:119]
	v_mfma_f32_16x16x32_bf16 v[112:115], v[180:183], v[208:211], v[112:115]
	v_mfma_f32_16x16x32_bf16 v[100:103], v[148:151], v[216:219], v[100:103]
	v_mfma_f32_16x16x32_bf16 v[96:99], v[180:183], v[216:219], v[96:99]
	v_mfma_f32_16x16x32_bf16 v[84:87], v[148:151], v[224:227], v[84:87]
	v_mfma_f32_16x16x32_bf16 v[80:83], v[180:183], v[224:227], v[80:83]
	s_barrier
	s_add_i32 s6, s43, s67
	s_mov_b32 m0, s6
	ds_read_b128 v[184:187], v198 offset:16384
	ds_read_b128 v[200:203], v198 offset:17408
	ds_read_b128 v[204:207], v198 offset:18432
	ds_read_b128 v[208:211], v198 offset:19456
	ds_read_b128 v[212:215], v198 offset:20480
	ds_read_b128 v[216:219], v198 offset:21504
	ds_read_b128 v[220:223], v198 offset:22528
	ds_read_b128 v[224:227], v198 offset:23552
	global_load_lds_dwordx4 v158, s[58:59]
	s_add_i32 m0, s6, 0x2000
	s_add_u32 s6, s58, 0x40000
	s_addc_u32 s7, s59, 0
	s_add_i32 s72, s76, s67
	global_load_lds_dwordx4 v170, s[58:59]
	s_mov_b32 m0, s72
	global_load_lds_dwordx4 v158, s[6:7]
	s_add_i32 m0, s72, 0x2000
	s_nop 0
	global_load_lds_dwordx4 v170, s[6:7]
	s_mov_b32 m0, s78
	s_nop 0
	global_load_lds_dwordx4 v156, s[60:61]
	s_mov_b32 m0, s79
	s_nop 0
	global_load_lds_dwordx4 v164, s[60:61]
	s_waitcnt vmcnt(8)
	s_waitcnt lgkmcnt(0)
	s_barrier
	s_waitcnt lgkmcnt(0)
	v_mfma_f32_16x16x32_bf16 v[76:79], v[32:35], v[184:187], v[76:79]
	v_mfma_f32_16x16x32_bf16 v[72:75], v[48:51], v[184:187], v[72:75]
	v_mfma_f32_16x16x32_bf16 v[60:63], v[32:35], v[204:207], v[60:63]
	v_mfma_f32_16x16x32_bf16 v[56:59], v[48:51], v[204:207], v[56:59]
	v_mfma_f32_16x16x32_bf16 v[28:31], v[32:35], v[212:215], v[28:31]
	v_mfma_f32_16x16x32_bf16 v[24:27], v[48:51], v[212:215], v[24:27]
	v_mfma_f32_16x16x32_bf16 v[12:15], v[32:35], v[220:223], v[12:15]
	v_mfma_f32_16x16x32_bf16 v[8:11], v[48:51], v[220:223], v[8:11]
	v_mfma_f32_16x16x32_bf16 v[76:79], v[36:39], v[200:203], v[76:79]
	v_mfma_f32_16x16x32_bf16 v[72:75], v[52:55], v[200:203], v[72:75]
	v_mfma_f32_16x16x32_bf16 v[60:63], v[36:39], v[208:211], v[60:63]
	v_mfma_f32_16x16x32_bf16 v[56:59], v[52:55], v[208:211], v[56:59]
	v_mfma_f32_16x16x32_bf16 v[28:31], v[36:39], v[216:219], v[28:31]
	v_mfma_f32_16x16x32_bf16 v[24:27], v[52:55], v[216:219], v[24:27]
	v_mfma_f32_16x16x32_bf16 v[12:15], v[36:39], v[224:227], v[12:15]
	v_mfma_f32_16x16x32_bf16 v[8:11], v[52:55], v[224:227], v[8:11]
	v_mfma_f32_16x16x32_bf16 v[44:47], v[128:131], v[204:207], v[44:47]
	v_mfma_f32_16x16x32_bf16 v[40:43], v[152:155], v[204:207], v[40:43]
	v_mfma_f32_16x16x32_bf16 v[20:23], v[128:131], v[212:215], v[20:23]
	v_mfma_f32_16x16x32_bf16 v[16:19], v[152:155], v[212:215], v[16:19]
	v_mfma_f32_16x16x32_bf16 v[4:7], v[128:131], v[220:223], v[4:7]
	v_mfma_f32_16x16x32_bf16 v[0:3], v[152:155], v[220:223], v[0:3]
	v_mfma_f32_16x16x32_bf16 v[32:35], v[128:131], v[184:187], v[68:71]
	v_mfma_f32_16x16x32_bf16 v[36:39], v[152:155], v[184:187], v[64:67]
	v_mfma_f32_16x16x32_bf16 v[44:47], v[148:151], v[208:211], v[44:47]
	v_mfma_f32_16x16x32_bf16 v[40:43], v[180:183], v[208:211], v[40:43]
	v_mfma_f32_16x16x32_bf16 v[20:23], v[148:151], v[216:219], v[20:23]
	v_mfma_f32_16x16x32_bf16 v[16:19], v[180:183], v[216:219], v[16:19]
	v_mfma_f32_16x16x32_bf16 v[4:7], v[148:151], v[224:227], v[4:7]
	v_mfma_f32_16x16x32_bf16 v[0:3], v[180:183], v[224:227], v[0:3]
	v_mfma_f32_16x16x32_bf16 v[32:35], v[148:151], v[200:203], v[32:35]
	v_mfma_f32_16x16x32_bf16 v[36:39], v[180:183], v[200:203], v[36:39]
	s_barrier
; #define PG8_STAGE(bufoff, gbase, voff) do { _Pragma("unroll") for (int _i = 0; _i < 2; ++_i) \
;         __builtin_amdgcn_global_load_lds((const unsigned*)((const char*)(gbase) + (voff)[_i]), (PG8_LAS unsigned*)(lds + (bufoff) + ldsw + _i * 8192), 16, 0, 0); } while (0)
; #define PG8_LDA(dst, b, h) do { _Pragma("unroll") for (int m = 0; m < 4; ++m) _Pragma("unroll") for (int k = 0; k < 2; ++k) dst[m][k] = *(const PG8_LAS bf16x8*)(lds + PG8_SA(b, h) + aoff + m * 2048 + k * 1024); } while (0)
; #define PG8_LDB(dst, b, h) do { _Pragma("unroll") for (int n = 0; n < 2; ++n) _Pragma("unroll") for (int k = 0; k < 2; ++k) dst[n][k] = *(const PG8_LAS bf16x8*)(lds + PG8_SB(b, h) + boff + n * 2048 + k * 1024); } while (0)
; #define PG8_MMA(ai, bj, At, Bt) do { __builtin_amdgcn_s_setprio(1); _Pragma("unroll") for (int m = 0; m < 4; ++m) _Pragma("unroll") for (int n = 0; n < 2; ++n) _Pragma("unroll") for (int k = 0; k < 2; ++k) \
;         acc[ai][bj][m][n] = __builtin_amdgcn_mfma_f32_16x16x32_bf16(Bt[n][k], At[m][k], acc[ai][bj][m][n], 0, 0, 0); __builtin_amdgcn_s_setprio(0); } while (0)
; #define PG8_WAIT_V(n) asm volatile("s_waitcnt vmcnt(" #n ")" ::: "memory")
; #define PG8_WAIT_L(n) asm volatile("s_waitcnt lgkmcnt(" #n ")" ::: "memory")
; #define PG8_BAR __builtin_amdgcn_s_barrier()
; #define PG8_SCHED __builtin_amdgcn_sched_barrier(0)
; template <class Epi, class Sched, bool ALIGN_EPI = false, bool SP2 = false>
; __device__ __forceinline__ void gemm_phase(PG8_LAS unsigned char* lds, const Gemm g, const Sched& S, const Epi& E) {
;     ...
;             PG8_LDB(B0, 1, 0); PG8_LDB(B1, 1, 1); PG8_SCHED; PG8_LDA(At, 1, 0); PG8_STAGE(PG8_SA(0, 1), a2 + hstep, voffA);
;             PG8_WAIT_V(8); PG8_WAIT_L(0); PG8_BAR; PG8_MMA(0, 0, At, B0); PG8_MMA(0, 1, At, B1); PG8_BAR; PG8_SCHED;
;             PG8_LDA(At, 1, 1); PG8_STAGE(PG8_SB(1, 0), b3, voffB); PG8_STAGE(PG8_SB(1, 1), b3 + hstep, voffB); PG8_STAGE(PG8_SA(1, 0), a3, voffA);
;             PG8_WAIT_V(8); PG8_WAIT_L(0); PG8_BAR; PG8_MMA(1, 0, At, B0); PG8_MMA(1, 1, At, B1); PG8_BAR; PG8_SCHED;
	s_add_i32 s72, 0, 0x18000
	s_add_i32 s73, 0, 0x1c000
	v_add_u32_e32 v68, s72, v169
	v_add_u32_e32 v180, s73, v169
	ds_read_b128 v[48:51], v68
	ds_read_b128 v[52:55], v68 offset:1024
	ds_read_b128 v[64:67], v68 offset:2048
	ds_read_b128 v[68:71], v68 offset:3072
	ds_read_b128 v[128:131], v180
	ds_read_b128 v[148:151], v180 offset:1024
	ds_read_b128 v[152:155], v180 offset:2048
	ds_read_b128 v[180:183], v180 offset:3072
	s_add_u32 s6, s60, 0x40000
	s_addc_u32 s7, s61, 0
	s_mov_b32 m0, s80
	ds_read_b128 v[184:187], v198 offset:32768
	ds_read_b128 v[200:203], v198 offset:33792
	ds_read_b128 v[204:207], v198 offset:34816
	ds_read_b128 v[208:211], v198 offset:35840
	ds_read_b128 v[212:215], v198 offset:36864
	ds_read_b128 v[216:219], v198 offset:37888
	ds_read_b128 v[220:223], v198 offset:38912
	ds_read_b128 v[224:227], v198 offset:39936
	global_load_lds_dwordx4 v156, s[6:7]
	s_mov_b32 m0, s81
	s_nop 0
	global_load_lds_dwordx4 v164, s[6:7]
	s_waitcnt vmcnt(8)
	s_waitcnt lgkmcnt(0)
	s_barrier
	s_waitcnt lgkmcnt(0)
	v_mfma_f32_16x16x32_bf16 v[144:147], v[48:51], v[184:187], v[144:147]
	v_mfma_f32_16x16x32_bf16 v[140:143], v[64:67], v[184:187], v[140:143]
	v_mfma_f32_16x16x32_bf16 v[124:127], v[48:51], v[204:207], v[124:127]
	v_mfma_f32_16x16x32_bf16 v[120:123], v[64:67], v[204:207], v[120:123]
	v_mfma_f32_16x16x32_bf16 v[108:111], v[48:51], v[212:215], v[108:111]
	v_mfma_f32_16x16x32_bf16 v[104:107], v[64:67], v[212:215], v[104:107]
	v_mfma_f32_16x16x32_bf16 v[92:95], v[48:51], v[220:223], v[92:95]
	v_mfma_f32_16x16x32_bf16 v[88:91], v[64:67], v[220:223], v[88:91]
	v_mfma_f32_16x16x32_bf16 v[144:147], v[52:55], v[200:203], v[144:147]
	v_mfma_f32_16x16x32_bf16 v[140:143], v[68:71], v[200:203], v[140:143]
	v_mfma_f32_16x16x32_bf16 v[124:127], v[52:55], v[208:211], v[124:127]
	v_mfma_f32_16x16x32_bf16 v[120:123], v[68:71], v[208:211], v[120:123]
	v_mfma_f32_16x16x32_bf16 v[108:111], v[52:55], v[216:219], v[108:111]
	v_mfma_f32_16x16x32_bf16 v[104:107], v[68:71], v[216:219], v[104:107]
	v_mfma_f32_16x16x32_bf16 v[92:95], v[52:55], v[224:227], v[92:95]
	v_mfma_f32_16x16x32_bf16 v[88:91], v[68:71], v[224:227], v[88:91]
	v_mfma_f32_16x16x32_bf16 v[136:139], v[128:131], v[184:187], v[136:139]
	v_mfma_f32_16x16x32_bf16 v[132:135], v[152:155], v[184:187], v[132:135]
	v_mfma_f32_16x16x32_bf16 v[116:119], v[128:131], v[204:207], v[116:119]
	v_mfma_f32_16x16x32_bf16 v[112:115], v[152:155], v[204:207], v[112:115]
	v_mfma_f32_16x16x32_bf16 v[100:103], v[128:131], v[212:215], v[100:103]
	v_mfma_f32_16x16x32_bf16 v[96:99], v[152:155], v[212:215], v[96:99]
	v_mfma_f32_16x16x32_bf16 v[84:87], v[128:131], v[220:223], v[84:87]
	v_mfma_f32_16x16x32_bf16 v[80:83], v[152:155], v[220:223], v[80:83]
	v_mfma_f32_16x16x32_bf16 v[136:139], v[148:151], v[200:203], v[136:139]
	v_mfma_f32_16x16x32_bf16 v[132:135], v[180:183], v[200:203], v[132:135]
	v_mfma_f32_16x16x32_bf16 v[116:119], v[148:151], v[208:211], v[116:119]
	v_mfma_f32_16x16x32_bf16 v[112:115], v[180:183], v[208:211], v[112:115]
	v_mfma_f32_16x16x32_bf16 v[100:103], v[148:151], v[216:219], v[100:103]
	v_mfma_f32_16x16x32_bf16 v[96:99], v[180:183], v[216:219], v[96:99]
	v_mfma_f32_16x16x32_bf16 v[84:87], v[148:151], v[224:227], v[84:87]
	v_mfma_f32_16x16x32_bf16 v[80:83], v[180:183], v[224:227], v[80:83]
	s_barrier
	s_add_i32 s6, s72, s67
	s_add_u32 s98, s58, 0x80
	s_addc_u32 s99, s59, 0
	s_add_u32 s100, s60, 0x80
	s_addc_u32 s101, s61, 0
	s_mov_b32 m0, s6
	ds_read_b128 v[184:187], v198 offset:49152
	ds_read_b128 v[200:203], v198 offset:50176
	ds_read_b128 v[204:207], v198 offset:51200
	ds_read_b128 v[208:211], v198 offset:52224
	ds_read_b128 v[212:215], v198 offset:53248
	ds_read_b128 v[216:219], v198 offset:54272
	ds_read_b128 v[220:223], v198 offset:55296
	ds_read_b128 v[224:227], v198 offset:56320
	global_load_lds_dwordx4 v158, s[98:99]
	s_add_i32 m0, s6, 0x2000
	s_add_u32 s6, s58, 0x40080
	s_addc_u32 s7, s59, 0
	s_add_i32 s58, s73, s67
	global_load_lds_dwordx4 v170, s[98:99]
	s_mov_b32 m0, s58
	s_nop 0
	global_load_lds_dwordx4 v158, s[6:7]
	s_add_i32 m0, s58, 0x2000
	s_nop 0
	global_load_lds_dwordx4 v170, s[6:7]
	s_mov_b32 m0, s45
	s_nop 0
	global_load_lds_dwordx4 v156, s[100:101]
	s_mov_b32 m0, s42
	s_nop 0
	global_load_lds_dwordx4 v164, s[100:101]
	s_waitcnt vmcnt(8)
	s_waitcnt lgkmcnt(0)
	s_barrier
	s_waitcnt lgkmcnt(0)
	v_mfma_f32_16x16x32_bf16 v[76:79], v[48:51], v[184:187], v[76:79]
	v_mfma_f32_16x16x32_bf16 v[72:75], v[64:67], v[184:187], v[72:75]
	v_mfma_f32_16x16x32_bf16 v[60:63], v[48:51], v[204:207], v[60:63]
	v_mfma_f32_16x16x32_bf16 v[56:59], v[64:67], v[204:207], v[56:59]
	v_mfma_f32_16x16x32_bf16 v[28:31], v[48:51], v[212:215], v[28:31]
	v_mfma_f32_16x16x32_bf16 v[24:27], v[64:67], v[212:215], v[24:27]
	v_mfma_f32_16x16x32_bf16 v[12:15], v[48:51], v[220:223], v[12:15]
	v_mfma_f32_16x16x32_bf16 v[8:11], v[64:67], v[220:223], v[8:11]
	v_mfma_f32_16x16x32_bf16 v[76:79], v[52:55], v[200:203], v[76:79]
	v_mfma_f32_16x16x32_bf16 v[72:75], v[68:71], v[200:203], v[72:75]
	v_mfma_f32_16x16x32_bf16 v[60:63], v[52:55], v[208:211], v[60:63]
	v_mfma_f32_16x16x32_bf16 v[56:59], v[68:71], v[208:211], v[56:59]
	v_mfma_f32_16x16x32_bf16 v[28:31], v[52:55], v[216:219], v[28:31]
	v_mfma_f32_16x16x32_bf16 v[24:27], v[68:71], v[216:219], v[24:27]
	v_mfma_f32_16x16x32_bf16 v[12:15], v[52:55], v[224:227], v[12:15]
	v_mfma_f32_16x16x32_bf16 v[8:11], v[68:71], v[224:227], v[8:11]
	v_mfma_f32_16x16x32_bf16 v[32:35], v[128:131], v[184:187], v[32:35]
	v_mfma_f32_16x16x32_bf16 v[68:71], v[148:151], v[200:203], v[32:35]
	v_mfma_f32_16x16x32_bf16 v[32:35], v[152:155], v[184:187], v[36:39]
	v_mfma_f32_16x16x32_bf16 v[64:67], v[180:183], v[200:203], v[32:35]
	v_mfma_f32_16x16x32_bf16 v[32:35], v[128:131], v[204:207], v[44:47]
	v_mfma_f32_16x16x32_bf16 v[44:47], v[148:151], v[208:211], v[32:35]
	v_mfma_f32_16x16x32_bf16 v[32:35], v[152:155], v[204:207], v[40:43]
	v_mfma_f32_16x16x32_bf16 v[20:23], v[128:131], v[212:215], v[20:23]
	v_mfma_f32_16x16x32_bf16 v[16:19], v[152:155], v[212:215], v[16:19]
	v_mfma_f32_16x16x32_bf16 v[4:7], v[128:131], v[220:223], v[4:7]
	v_mfma_f32_16x16x32_bf16 v[0:3], v[152:155], v[220:223], v[0:3]
	v_mfma_f32_16x16x32_bf16 v[40:43], v[180:183], v[208:211], v[32:35]
	v_mfma_f32_16x16x32_bf16 v[20:23], v[148:151], v[216:219], v[20:23]
	v_mfma_f32_16x16x32_bf16 v[16:19], v[180:183], v[216:219], v[16:19]
	v_mfma_f32_16x16x32_bf16 v[4:7], v[148:151], v[224:227], v[4:7]
	v_mfma_f32_16x16x32_bf16 v[0:3], v[180:183], v[224:227], v[0:3]
	s_barrier
	s_add_i32 s69, s69, 2
	s_add_u32 s56, s56, 0x100
	s_addc_u32 s57, s57, 0
	s_add_u32 s68, s68, 0x100
	s_addc_u32 s33, s33, 0
	s_cmp_gt_u32 s69, 13
	s_cbranch_scc0 .LBB0_1617
	v_readlane_b32 s68, v243, 59
	s_and_b64 vcc, exec, s[40:41]
	v_readlane_b32 s69, v243, 60
	s_cbranch_vccz .LBB0_1620
	s_barrier

; #define PG8_STAGE(bufoff, gbase, voff) do { _Pragma("unroll") for (int _i = 0; _i < 2; ++_i) \
;         __builtin_amdgcn_global_load_lds((const unsigned*)((const char*)(gbase) + (voff)[_i]), (PG8_LAS unsigned*)(lds + (bufoff) + ldsw + _i * 8192), 16, 0, 0); } while (0)
; #define PG8_LDA(dst, b, h) do { _Pragma("unroll") for (int m = 0; m < 4; ++m) _Pragma("unroll") for (int k = 0; k < 2; ++k) dst[m][k] = *(const PG8_LAS bf16x8*)(lds + PG8_SA(b, h) + aoff + m * 2048 + k * 1024); } while (0)
; #define PG8_LDB(dst, b, h) do { _Pragma("unroll") for (int n = 0; n < 2; ++n) _Pragma("unroll") for (int k = 0; k < 2; ++k) dst[n][k] = *(const PG8_LAS bf16x8*)(lds + PG8_SB(b, h) + boff + n * 2048 + k * 1024); } while (0)
; #define PG8_MMA(ai, bj, At, Bt) do { __builtin_amdgcn_s_setprio(1); _Pragma("unroll") for (int m = 0; m < 4; ++m) _Pragma("unroll") for (int n = 0; n < 2; ++n) _Pragma("unroll") for (int k = 0; k < 2; ++k) \
;         acc[ai][bj][m][n] = __builtin_amdgcn_mfma_f32_16x16x32_bf16(Bt[n][k], At[m][k], acc[ai][bj][m][n], 0, 0, 0); __builtin_amdgcn_s_setprio(0); } while (0)
; #define PG8_WAIT_V(n) asm volatile("s_waitcnt vmcnt(" #n ")" ::: "memory")
; #define PG8_WAIT_L(n) asm volatile("s_waitcnt lgkmcnt(" #n ")" ::: "memory")
; template <class Epi, class Sched, bool ALIGN_EPI = false, bool SP2 = false>
; __device__ __forceinline__ void gemm_phase(PG8_LAS unsigned char* lds, const Gemm g, const Sched& S, const Epi& E) {
;     ...
;             const bool last = (t == nt - 2);
;             const char* a1 = cA + (size_t)(t + 1) * kstep;
;             const char* a2 = last ? nA : cA + (size_t)(t + 2) * kstep; const char* b2 = last ? nB : cB + (size_t)(t + 2) * kstep;
;             const char* a3 = a2 + kstep; const char* b3 = b2 + kstep;
;             if (last && has_next) S.a_ready(nxt);
;             if constexpr (SP2) {
;             PG8_LDB(B0, 0, 0); PG8_LDB(B1, 0, 1); PG8_SCHED; PG8_LDA(At, 0, 0); PG8_STAGE(PG8_SA(1, 1), a1 + hstep, voffA);
;             PG8_WAIT_V(8); PG8_WAIT_L(0); PG8_BAR; PG8_MMA(0, 0, At, B0); PG8_MMA(0, 1, At, B1); PG8_BAR; PG8_SCHED;
;             PG8_LDA(At, 0, 1); PG8_STAGE(PG8_SB(0, 0), b2, voffB); PG8_STAGE(PG8_SB(0, 1), b2 + hstep, voffB); PG8_STAGE(PG8_SA(0, 0), a2, voffA);
;             PG8_WAIT_V(8); PG8_WAIT_L(0); PG8_BAR; PG8_MMA(1, 0, At, B0); PG8_MMA(1, 1, At, B1); PG8_BAR; PG8_SCHED;
.LBB0_1698:
	ds_read_b128 v[144:147], v153
	ds_read_b128 v[170:173], v153 offset:1024
	ds_read_b128 v[174:177], v153 offset:2048
	ds_read_b128 v[178:181], v153 offset:3072
	ds_read_b128 v[182:185], v154
	ds_read_b128 v[186:189], v154 offset:1024
	ds_read_b128 v[198:201], v154 offset:2048
	ds_read_b128 v[202:205], v154 offset:3072
	s_add_u32 s6, s60, 0xfffc0080
	s_addc_u32 s7, s61, -1
	s_cmp_eq_u32 s72, 12
	s_cselect_b32 s81, s29, s7
	s_cselect_b32 s80, s55, s6
	s_cselect_b32 s79, s53, s33
	s_cselect_b32 s78, s68, s69
	s_add_i32 m0, s43, 0xc000
	ds_read_b128 v[206:209], v155
	ds_read_b128 v[210:213], v155 offset:1024
	ds_read_b128 v[214:217], v155 offset:2048
	ds_read_b128 v[218:221], v155 offset:3072
	ds_read_b128 v[222:225], v155 offset:4096
	ds_read_b128 v[226:229], v155 offset:5120
	ds_read_b128 v[230:233], v155 offset:6144
	ds_read_b128 v[234:237], v155 offset:7168
	global_load_lds_dwordx4 v136, s[60:61]
	s_add_i32 m0, s43, 0xe000
	s_nop 0
	global_load_lds_dwordx4 v138, s[60:61]
	s_waitcnt vmcnt(8)
	s_waitcnt lgkmcnt(0)
	s_barrier
	s_waitcnt lgkmcnt(0)
	v_mfma_f32_16x16x32_bf16 v[124:127], v[144:147], v[206:209], v[124:127]
	v_mfma_f32_16x16x32_bf16 v[120:123], v[174:177], v[206:209], v[120:123]
	v_mfma_f32_16x16x32_bf16 v[108:111], v[144:147], v[214:217], v[108:111]
	v_mfma_f32_16x16x32_bf16 v[104:107], v[174:177], v[214:217], v[104:107]
	v_mfma_f32_16x16x32_bf16 v[92:95], v[144:147], v[222:225], v[92:95]
	v_mfma_f32_16x16x32_bf16 v[88:91], v[174:177], v[222:225], v[88:91]
	v_mfma_f32_16x16x32_bf16 v[76:79], v[144:147], v[230:233], v[76:79]
	v_mfma_f32_16x16x32_bf16 v[72:75], v[174:177], v[230:233], v[72:75]
	v_mfma_f32_16x16x32_bf16 v[124:127], v[170:173], v[210:213], v[124:127]
	v_mfma_f32_16x16x32_bf16 v[120:123], v[178:181], v[210:213], v[120:123]
	v_mfma_f32_16x16x32_bf16 v[108:111], v[170:173], v[218:221], v[108:111]
	v_mfma_f32_16x16x32_bf16 v[104:107], v[178:181], v[218:221], v[104:107]
	v_mfma_f32_16x16x32_bf16 v[92:95], v[170:173], v[226:229], v[92:95]
	v_mfma_f32_16x16x32_bf16 v[88:91], v[178:181], v[226:229], v[88:91]
	v_mfma_f32_16x16x32_bf16 v[76:79], v[170:173], v[234:237], v[76:79]
	v_mfma_f32_16x16x32_bf16 v[72:75], v[178:181], v[234:237], v[72:75]
	v_mfma_f32_16x16x32_bf16 v[116:119], v[182:185], v[206:209], v[116:119]
	v_mfma_f32_16x16x32_bf16 v[112:115], v[198:201], v[206:209], v[112:115]
	v_mfma_f32_16x16x32_bf16 v[100:103], v[182:185], v[214:217], v[100:103]
	v_mfma_f32_16x16x32_bf16 v[96:99], v[198:201], v[214:217], v[96:99]
	v_mfma_f32_16x16x32_bf16 v[84:87], v[182:185], v[222:225], v[84:87]
	v_mfma_f32_16x16x32_bf16 v[80:83], v[198:201], v[222:225], v[80:83]
	v_mfma_f32_16x16x32_bf16 v[68:71], v[182:185], v[230:233], v[68:71]
	v_mfma_f32_16x16x32_bf16 v[64:67], v[198:201], v[230:233], v[64:67]
	v_mfma_f32_16x16x32_bf16 v[116:119], v[186:189], v[210:213], v[116:119]
	v_mfma_f32_16x16x32_bf16 v[112:115], v[202:205], v[210:213], v[112:115]
	v_mfma_f32_16x16x32_bf16 v[100:103], v[186:189], v[218:221], v[100:103]
	v_mfma_f32_16x16x32_bf16 v[96:99], v[202:205], v[218:221], v[96:99]
	v_mfma_f32_16x16x32_bf16 v[84:87], v[186:189], v[226:229], v[84:87]
	v_mfma_f32_16x16x32_bf16 v[80:83], v[202:205], v[226:229], v[80:83]
	v_mfma_f32_16x16x32_bf16 v[68:71], v[186:189], v[234:237], v[68:71]
	v_mfma_f32_16x16x32_bf16 v[64:67], v[202:205], v[234:237], v[64:67]
	s_barrier
	s_add_i32 s6, s26, s42
	s_mov_b32 m0, s6
	ds_read_b128 v[206:209], v155 offset:16384
	ds_read_b128 v[210:213], v155 offset:17408
	ds_read_b128 v[214:217], v155 offset:18432
	ds_read_b128 v[218:221], v155 offset:19456
	ds_read_b128 v[222:225], v155 offset:20480
	ds_read_b128 v[226:229], v155 offset:21504
	ds_read_b128 v[230:233], v155 offset:22528
	ds_read_b128 v[234:237], v155 offset:23552
	global_load_lds_dwordx4 v130, s[78:79]
	s_add_i32 m0, s6, 0x2000
	s_add_u32 s6, s78, 0x40000
	s_addc_u32 s7, s79, 0
	s_add_i32 s73, s74, s42
	global_load_lds_dwordx4 v134, s[78:79]
	s_mov_b32 m0, s73
	global_load_lds_dwordx4 v130, s[6:7]
	s_add_i32 m0, s73, 0x2000
	s_nop 0
	global_load_lds_dwordx4 v134, s[6:7]
	s_mov_b32 m0, s43
	s_nop 0
	global_load_lds_dwordx4 v128, s[80:81]
	s_mov_b32 m0, s44
	s_nop 0
	global_load_lds_dwordx4 v132, s[80:81]
	s_waitcnt vmcnt(8)
	s_waitcnt lgkmcnt(0)
	s_barrier
	s_waitcnt lgkmcnt(0)
	v_mfma_f32_16x16x32_bf16 v[60:63], v[144:147], v[206:209], v[60:63]
	v_mfma_f32_16x16x32_bf16 v[56:59], v[174:177], v[206:209], v[56:59]
	v_mfma_f32_16x16x32_bf16 v[44:47], v[144:147], v[214:217], v[44:47]
	v_mfma_f32_16x16x32_bf16 v[40:43], v[174:177], v[214:217], v[40:43]
	v_mfma_f32_16x16x32_bf16 v[28:31], v[144:147], v[222:225], v[28:31]
	v_mfma_f32_16x16x32_bf16 v[24:27], v[174:177], v[222:225], v[24:27]
	v_mfma_f32_16x16x32_bf16 v[12:15], v[144:147], v[230:233], v[12:15]
	v_mfma_f32_16x16x32_bf16 v[8:11], v[174:177], v[230:233], v[8:11]
	v_mfma_f32_16x16x32_bf16 v[60:63], v[170:173], v[210:213], v[60:63]
	v_mfma_f32_16x16x32_bf16 v[56:59], v[178:181], v[210:213], v[56:59]
	v_mfma_f32_16x16x32_bf16 v[44:47], v[170:173], v[218:221], v[44:47]
	v_mfma_f32_16x16x32_bf16 v[40:43], v[178:181], v[218:221], v[40:43]
	v_mfma_f32_16x16x32_bf16 v[28:31], v[170:173], v[226:229], v[28:31]
	v_mfma_f32_16x16x32_bf16 v[24:27], v[178:181], v[226:229], v[24:27]
	v_mfma_f32_16x16x32_bf16 v[12:15], v[170:173], v[234:237], v[12:15]
	v_mfma_f32_16x16x32_bf16 v[8:11], v[178:181], v[234:237], v[8:11]
	v_mfma_f32_16x16x32_bf16 v[52:55], v[182:185], v[206:209], v[52:55]
	v_mfma_f32_16x16x32_bf16 v[48:51], v[198:201], v[206:209], v[48:51]
	v_mfma_f32_16x16x32_bf16 v[36:39], v[182:185], v[214:217], v[36:39]
	v_mfma_f32_16x16x32_bf16 v[32:35], v[198:201], v[214:217], v[32:35]
	v_mfma_f32_16x16x32_bf16 v[20:23], v[182:185], v[222:225], v[20:23]
	v_mfma_f32_16x16x32_bf16 v[16:19], v[198:201], v[222:225], v[16:19]
	v_mfma_f32_16x16x32_bf16 v[4:7], v[182:185], v[230:233], v[4:7]
	v_mfma_f32_16x16x32_bf16 v[0:3], v[198:201], v[230:233], v[0:3]
	v_mfma_f32_16x16x32_bf16 v[52:55], v[186:189], v[210:213], v[52:55]
	v_mfma_f32_16x16x32_bf16 v[48:51], v[202:205], v[210:213], v[48:51]
	v_mfma_f32_16x16x32_bf16 v[36:39], v[186:189], v[218:221], v[36:39]
	v_mfma_f32_16x16x32_bf16 v[32:35], v[202:205], v[218:221], v[32:35]
	v_mfma_f32_16x16x32_bf16 v[20:23], v[186:189], v[226:229], v[20:23]
	v_mfma_f32_16x16x32_bf16 v[16:19], v[202:205], v[226:229], v[16:19]
	v_mfma_f32_16x16x32_bf16 v[4:7], v[186:189], v[234:237], v[4:7]
	v_mfma_f32_16x16x32_bf16 v[0:3], v[202:205], v[234:237], v[0:3]
	s_barrier
; #define PG8_STAGE(bufoff, gbase, voff) do { _Pragma("unroll") for (int _i = 0; _i < 2; ++_i) \
;         __builtin_amdgcn_global_load_lds((const unsigned*)((const char*)(gbase) + (voff)[_i]), (PG8_LAS unsigned*)(lds + (bufoff) + ldsw + _i * 8192), 16, 0, 0); } while (0)
; #define PG8_LDA(dst, b, h) do { _Pragma("unroll") for (int m = 0; m < 4; ++m) _Pragma("unroll") for (int k = 0; k < 2; ++k) dst[m][k] = *(const PG8_LAS bf16x8*)(lds + PG8_SA(b, h) + aoff + m * 2048 + k * 1024); } while (0)
; #define PG8_LDB(dst, b, h) do { _Pragma("unroll") for (int n = 0; n < 2; ++n) _Pragma("unroll") for (int k = 0; k < 2; ++k) dst[n][k] = *(const PG8_LAS bf16x8*)(lds + PG8_SB(b, h) + boff + n * 2048 + k * 1024); } while (0)
; #define PG8_MMA(ai, bj, At, Bt) do { __builtin_amdgcn_s_setprio(1); _Pragma("unroll") for (int m = 0; m < 4; ++m) _Pragma("unroll") for (int n = 0; n < 2; ++n) _Pragma("unroll") for (int k = 0; k < 2; ++k) \
;         acc[ai][bj][m][n] = __builtin_amdgcn_mfma_f32_16x16x32_bf16(Bt[n][k], At[m][k], acc[ai][bj][m][n], 0, 0, 0); __builtin_amdgcn_s_setprio(0); } while (0)
; #define PG8_WAIT_V(n) asm volatile("s_waitcnt vmcnt(" #n ")" ::: "memory")
; #define PG8_WAIT_L(n) asm volatile("s_waitcnt lgkmcnt(" #n ")" ::: "memory")
; #define PG8_BAR __builtin_amdgcn_s_barrier()
; #define PG8_SCHED __builtin_amdgcn_sched_barrier(0)
; template <class Epi, class Sched, bool ALIGN_EPI = false, bool SP2 = false>
; __device__ __forceinline__ void gemm_phase(PG8_LAS unsigned char* lds, const Gemm g, const Sched& S, const Epi& E) {
;     ...
;             PG8_LDB(B0, 1, 0); PG8_LDB(B1, 1, 1); PG8_SCHED; PG8_LDA(At, 1, 0); PG8_STAGE(PG8_SA(0, 1), a2 + hstep, voffA);
;             PG8_WAIT_V(8); PG8_WAIT_L(0); PG8_BAR; PG8_MMA(0, 0, At, B0); PG8_MMA(0, 1, At, B1); PG8_BAR; PG8_SCHED;
;             PG8_LDA(At, 1, 1); PG8_STAGE(PG8_SB(1, 0), b3, voffB); PG8_STAGE(PG8_SB(1, 1), b3 + hstep, voffB); PG8_STAGE(PG8_SA(1, 0), a3, voffA);
;             PG8_WAIT_V(8); PG8_WAIT_L(0); PG8_BAR; PG8_MMA(1, 0, At, B0); PG8_MMA(1, 1, At, B1); PG8_BAR; PG8_SCHED;
	s_add_i32 s73, 0, 0x18000
	v_add_u32_e32 v157, s73, v151
	s_add_i32 s82, 0, 0x1c000
	ds_read_b128 v[144:147], v157
	ds_read_b128 v[170:173], v157 offset:1024
	ds_read_b128 v[174:177], v157 offset:2048
	ds_read_b128 v[178:181], v157 offset:3072
	v_add_u32_e32 v157, s82, v151
	ds_read_b128 v[182:185], v157
	ds_read_b128 v[186:189], v157 offset:1024
	ds_read_b128 v[198:201], v157 offset:2048
	ds_read_b128 v[202:205], v157 offset:3072
	s_add_u32 s6, s80, 0x40000
	s_addc_u32 s7, s81, 0
	s_mov_b32 m0, s45
	ds_read_b128 v[206:209], v155 offset:32768
	ds_read_b128 v[210:213], v155 offset:33792
	ds_read_b128 v[214:217], v155 offset:34816
	ds_read_b128 v[218:221], v155 offset:35840
	ds_read_b128 v[222:225], v155 offset:36864
	ds_read_b128 v[226:229], v155 offset:37888
	ds_read_b128 v[230:233], v155 offset:38912
	ds_read_b128 v[234:237], v155 offset:39936
	global_load_lds_dwordx4 v128, s[6:7]
	s_mov_b32 m0, s67
	s_nop 0
	global_load_lds_dwordx4 v132, s[6:7]
	s_waitcnt vmcnt(8)
	s_waitcnt lgkmcnt(0)
	s_barrier
	s_waitcnt lgkmcnt(0)
	v_mfma_f32_16x16x32_bf16 v[124:127], v[144:147], v[206:209], v[124:127]
	v_mfma_f32_16x16x32_bf16 v[120:123], v[174:177], v[206:209], v[120:123]
	v_mfma_f32_16x16x32_bf16 v[108:111], v[144:147], v[214:217], v[108:111]
	v_mfma_f32_16x16x32_bf16 v[104:107], v[174:177], v[214:217], v[104:107]
	v_mfma_f32_16x16x32_bf16 v[92:95], v[144:147], v[222:225], v[92:95]
	v_mfma_f32_16x16x32_bf16 v[88:91], v[174:177], v[222:225], v[88:91]
	v_mfma_f32_16x16x32_bf16 v[76:79], v[144:147], v[230:233], v[76:79]
	v_mfma_f32_16x16x32_bf16 v[72:75], v[174:177], v[230:233], v[72:75]
	v_mfma_f32_16x16x32_bf16 v[124:127], v[170:173], v[210:213], v[124:127]
	v_mfma_f32_16x16x32_bf16 v[120:123], v[178:181], v[210:213], v[120:123]
	v_mfma_f32_16x16x32_bf16 v[108:111], v[170:173], v[218:221], v[108:111]
	v_mfma_f32_16x16x32_bf16 v[104:107], v[178:181], v[218:221], v[104:107]
	v_mfma_f32_16x16x32_bf16 v[92:95], v[170:173], v[226:229], v[92:95]
	v_mfma_f32_16x16x32_bf16 v[88:91], v[178:181], v[226:229], v[88:91]
	v_mfma_f32_16x16x32_bf16 v[76:79], v[170:173], v[234:237], v[76:79]
	v_mfma_f32_16x16x32_bf16 v[72:75], v[178:181], v[234:237], v[72:75]
	v_mfma_f32_16x16x32_bf16 v[116:119], v[182:185], v[206:209], v[116:119]
	v_mfma_f32_16x16x32_bf16 v[112:115], v[198:201], v[206:209], v[112:115]
	v_mfma_f32_16x16x32_bf16 v[100:103], v[182:185], v[214:217], v[100:103]
	v_mfma_f32_16x16x32_bf16 v[96:99], v[198:201], v[214:217], v[96:99]
	v_mfma_f32_16x16x32_bf16 v[84:87], v[182:185], v[222:225], v[84:87]
	v_mfma_f32_16x16x32_bf16 v[80:83], v[198:201], v[222:225], v[80:83]
	v_mfma_f32_16x16x32_bf16 v[68:71], v[182:185], v[230:233], v[68:71]
	v_mfma_f32_16x16x32_bf16 v[64:67], v[198:201], v[230:233], v[64:67]
	v_mfma_f32_16x16x32_bf16 v[116:119], v[186:189], v[210:213], v[116:119]
	v_mfma_f32_16x16x32_bf16 v[112:115], v[202:205], v[210:213], v[112:115]
	v_mfma_f32_16x16x32_bf16 v[100:103], v[186:189], v[218:221], v[100:103]
	v_mfma_f32_16x16x32_bf16 v[96:99], v[202:205], v[218:221], v[96:99]
	v_mfma_f32_16x16x32_bf16 v[84:87], v[186:189], v[226:229], v[84:87]
	v_mfma_f32_16x16x32_bf16 v[80:83], v[202:205], v[226:229], v[80:83]
	v_mfma_f32_16x16x32_bf16 v[68:71], v[186:189], v[234:237], v[68:71]
	v_mfma_f32_16x16x32_bf16 v[64:67], v[202:205], v[234:237], v[64:67]
	s_barrier
	s_add_i32 s6, s73, s42
	s_add_u32 s98, s78, 0x80
	s_addc_u32 s99, s79, 0
	s_add_u32 s100, s80, 0x80
	s_addc_u32 s101, s81, 0
	s_mov_b32 m0, s6
	ds_read_b128 v[206:209], v155 offset:49152
	ds_read_b128 v[210:213], v155 offset:50176
	ds_read_b128 v[214:217], v155 offset:51200
	ds_read_b128 v[218:221], v155 offset:52224
	ds_read_b128 v[222:225], v155 offset:53248
	ds_read_b128 v[226:229], v155 offset:54272
	ds_read_b128 v[230:233], v155 offset:55296
	ds_read_b128 v[234:237], v155 offset:56320
	global_load_lds_dwordx4 v130, s[98:99]
	s_add_i32 m0, s6, 0x2000
	s_add_u32 s6, s78, 0x40080
	s_addc_u32 s7, s79, 0
	s_add_i32 s73, s82, s42
	global_load_lds_dwordx4 v134, s[98:99]
	s_mov_b32 m0, s73
	s_nop 0
	global_load_lds_dwordx4 v130, s[6:7]
	s_add_i32 m0, s73, 0x2000
	s_nop 0
	global_load_lds_dwordx4 v134, s[6:7]
	s_mov_b32 m0, s4
	s_nop 0
	global_load_lds_dwordx4 v128, s[100:101]
	s_mov_b32 m0, s77
	s_nop 0
	global_load_lds_dwordx4 v132, s[100:101]
	s_waitcnt vmcnt(8)
	s_waitcnt lgkmcnt(0)
	s_barrier
	s_waitcnt lgkmcnt(0)
	v_mfma_f32_16x16x32_bf16 v[60:63], v[144:147], v[206:209], v[60:63]
	v_mfma_f32_16x16x32_bf16 v[56:59], v[174:177], v[206:209], v[56:59]
	v_mfma_f32_16x16x32_bf16 v[44:47], v[144:147], v[214:217], v[44:47]
	v_mfma_f32_16x16x32_bf16 v[40:43], v[174:177], v[214:217], v[40:43]
	v_mfma_f32_16x16x32_bf16 v[28:31], v[144:147], v[222:225], v[28:31]
	v_mfma_f32_16x16x32_bf16 v[24:27], v[174:177], v[222:225], v[24:27]
	v_mfma_f32_16x16x32_bf16 v[12:15], v[144:147], v[230:233], v[12:15]
	v_mfma_f32_16x16x32_bf16 v[8:11], v[174:177], v[230:233], v[8:11]
	v_mfma_f32_16x16x32_bf16 v[60:63], v[170:173], v[210:213], v[60:63]
	v_mfma_f32_16x16x32_bf16 v[56:59], v[178:181], v[210:213], v[56:59]
	v_mfma_f32_16x16x32_bf16 v[44:47], v[170:173], v[218:221], v[44:47]
	v_mfma_f32_16x16x32_bf16 v[40:43], v[178:181], v[218:221], v[40:43]
	v_mfma_f32_16x16x32_bf16 v[28:31], v[170:173], v[226:229], v[28:31]
	v_mfma_f32_16x16x32_bf16 v[24:27], v[178:181], v[226:229], v[24:27]
	v_mfma_f32_16x16x32_bf16 v[12:15], v[170:173], v[234:237], v[12:15]
	v_mfma_f32_16x16x32_bf16 v[8:11], v[178:181], v[234:237], v[8:11]
	v_mfma_f32_16x16x32_bf16 v[52:55], v[182:185], v[206:209], v[52:55]
	v_mfma_f32_16x16x32_bf16 v[48:51], v[198:201], v[206:209], v[48:51]
	v_mfma_f32_16x16x32_bf16 v[36:39], v[182:185], v[214:217], v[36:39]
	v_mfma_f32_16x16x32_bf16 v[32:35], v[198:201], v[214:217], v[32:35]
	v_mfma_f32_16x16x32_bf16 v[20:23], v[182:185], v[222:225], v[20:23]
	v_mfma_f32_16x16x32_bf16 v[16:19], v[198:201], v[222:225], v[16:19]
	v_mfma_f32_16x16x32_bf16 v[4:7], v[182:185], v[230:233], v[4:7]
	v_mfma_f32_16x16x32_bf16 v[0:3], v[198:201], v[230:233], v[0:3]
	v_mfma_f32_16x16x32_bf16 v[52:55], v[186:189], v[210:213], v[52:55]
	v_mfma_f32_16x16x32_bf16 v[48:51], v[202:205], v[210:213], v[48:51]
	v_mfma_f32_16x16x32_bf16 v[36:39], v[186:189], v[218:221], v[36:39]
	v_mfma_f32_16x16x32_bf16 v[32:35], v[202:205], v[218:221], v[32:35]
	v_mfma_f32_16x16x32_bf16 v[20:23], v[186:189], v[226:229], v[20:23]
	v_mfma_f32_16x16x32_bf16 v[16:19], v[202:205], v[226:229], v[16:19]
	v_mfma_f32_16x16x32_bf16 v[4:7], v[186:189], v[234:237], v[4:7]
	v_mfma_f32_16x16x32_bf16 v[0:3], v[202:205], v[234:237], v[0:3]
	s_barrier
	s_add_i32 s72, s72, 2
	s_add_u32 s60, s60, 0x100
	s_addc_u32 s61, s61, 0
	s_add_u32 s69, s69, 0x100
	s_addc_u32 s33, s33, 0
	s_cmp_gt_u32 s72, 13
	s_cbranch_scc0 .LBB0_1698
	s_and_b64 vcc, exec, s[50:51]
	s_cbranch_vccz .LBB0_1701
	s_barrier

; #define PG8_STAGE(bufoff, gbase, voff) do { _Pragma("unroll") for (int _i = 0; _i < 2; ++_i) \
;         __builtin_amdgcn_global_load_lds((const unsigned*)((const char*)(gbase) + (voff)[_i]), (PG8_LAS unsigned*)(lds + (bufoff) + ldsw + _i * 8192), 16, 0, 0); } while (0)
; #define PG8_LDA(dst, b, h) do { _Pragma("unroll") for (int m = 0; m < 4; ++m) _Pragma("unroll") for (int k = 0; k < 2; ++k) dst[m][k] = *(const PG8_LAS bf16x8*)(lds + PG8_SA(b, h) + aoff + m * 2048 + k * 1024); } while (0)
; #define PG8_LDB(dst, b, h) do { _Pragma("unroll") for (int n = 0; n < 2; ++n) _Pragma("unroll") for (int k = 0; k < 2; ++k) dst[n][k] = *(const PG8_LAS bf16x8*)(lds + PG8_SB(b, h) + boff + n * 2048 + k * 1024); } while (0)
; #define PG8_MMA(ai, bj, At, Bt) do { __builtin_amdgcn_s_setprio(1); _Pragma("unroll") for (int m = 0; m < 4; ++m) _Pragma("unroll") for (int n = 0; n < 2; ++n) _Pragma("unroll") for (int k = 0; k < 2; ++k) \
;         acc[ai][bj][m][n] = __builtin_amdgcn_mfma_f32_16x16x32_bf16(Bt[n][k], At[m][k], acc[ai][bj][m][n], 0, 0, 0); __builtin_amdgcn_s_setprio(0); } while (0)
; #define PG8_WAIT_V(n) asm volatile("s_waitcnt vmcnt(" #n ")" ::: "memory")
; #define PG8_WAIT_L(n) asm volatile("s_waitcnt lgkmcnt(" #n ")" ::: "memory")
; template <class Epi, class Sched, bool ALIGN_EPI = false, bool SP2 = false>
; __device__ __forceinline__ void gemm_phase(PG8_LAS unsigned char* lds, const Gemm g, const Sched& S, const Epi& E) {
;     ...
;             const bool last = (t == nt - 2);
;             const char* a1 = cA + (size_t)(t + 1) * kstep;
;             const char* a2 = last ? nA : cA + (size_t)(t + 2) * kstep; const char* b2 = last ? nB : cB + (size_t)(t + 2) * kstep;
;             const char* a3 = a2 + kstep; const char* b3 = b2 + kstep;
;             if (last && has_next) S.a_ready(nxt);
;             if constexpr (SP2) {
;             PG8_LDB(B0, 0, 0); PG8_LDB(B1, 0, 1); PG8_SCHED; PG8_LDA(At, 0, 0); PG8_STAGE(PG8_SA(1, 1), a1 + hstep, voffA);
;             PG8_WAIT_V(8); PG8_WAIT_L(0); PG8_BAR; PG8_MMA(0, 0, At, B0); PG8_MMA(0, 1, At, B1); PG8_BAR; PG8_SCHED;
;             PG8_LDA(At, 0, 1); PG8_STAGE(PG8_SB(0, 0), b2, voffB); PG8_STAGE(PG8_SB(0, 1), b2 + hstep, voffB); PG8_STAGE(PG8_SA(0, 0), a2, voffA);
;             PG8_WAIT_V(8); PG8_WAIT_L(0); PG8_BAR; PG8_MMA(1, 0, At, B0); PG8_MMA(1, 1, At, B1); PG8_BAR; PG8_SCHED;
.LBB0_1822:
	ds_read_b128 v[144:147], v154
	ds_read_b128 v[168:171], v154 offset:1024
	ds_read_b128 v[172:175], v154 offset:2048
	ds_read_b128 v[176:179], v154 offset:3072
	ds_read_b128 v[180:183], v155
	ds_read_b128 v[184:187], v155 offset:1024
	ds_read_b128 v[188:191], v155 offset:2048
	ds_read_b128 v[198:201], v155 offset:3072
	s_add_u32 s6, s50, 0xfffc0080
	s_addc_u32 s7, s51, -1
	s_cmp_eq_u32 s72, 12
	s_cselect_b32 s55, s39, s7
	s_cselect_b32 s54, s69, s6
	s_cselect_b32 s53, s37, s33
	s_cselect_b32 s52, s74, s75
	s_add_i32 m0, s27, 0xc000
	ds_read_b128 v[202:205], v156
	ds_read_b128 v[206:209], v156 offset:1024
	ds_read_b128 v[210:213], v156 offset:2048
	ds_read_b128 v[214:217], v156 offset:3072
	ds_read_b128 v[218:221], v156 offset:4096
	ds_read_b128 v[222:225], v156 offset:5120
	ds_read_b128 v[226:229], v156 offset:6144
	ds_read_b128 v[230:233], v156 offset:7168
	global_load_lds_dwordx4 v136, s[50:51]
	s_add_i32 m0, s27, 0xe000
	s_nop 0
	global_load_lds_dwordx4 v138, s[50:51]
	s_waitcnt vmcnt(8)
	s_waitcnt lgkmcnt(0)
	s_barrier
	s_waitcnt lgkmcnt(0)
	v_mfma_f32_16x16x32_bf16 v[124:127], v[144:147], v[202:205], v[124:127]
	v_mfma_f32_16x16x32_bf16 v[116:119], v[172:175], v[202:205], v[116:119]
	v_mfma_f32_16x16x32_bf16 v[108:111], v[144:147], v[210:213], v[108:111]
	v_mfma_f32_16x16x32_bf16 v[100:103], v[172:175], v[210:213], v[100:103]
	v_mfma_f32_16x16x32_bf16 v[92:95], v[144:147], v[218:221], v[92:95]
	v_mfma_f32_16x16x32_bf16 v[84:87], v[172:175], v[218:221], v[84:87]
	v_mfma_f32_16x16x32_bf16 v[76:79], v[144:147], v[226:229], v[76:79]
	v_mfma_f32_16x16x32_bf16 v[68:71], v[172:175], v[226:229], v[68:71]
	v_mfma_f32_16x16x32_bf16 v[124:127], v[168:171], v[206:209], v[124:127]
	v_mfma_f32_16x16x32_bf16 v[116:119], v[176:179], v[206:209], v[116:119]
	v_mfma_f32_16x16x32_bf16 v[108:111], v[168:171], v[214:217], v[108:111]
	v_mfma_f32_16x16x32_bf16 v[100:103], v[176:179], v[214:217], v[100:103]
	v_mfma_f32_16x16x32_bf16 v[92:95], v[168:171], v[222:225], v[92:95]
	v_mfma_f32_16x16x32_bf16 v[84:87], v[176:179], v[222:225], v[84:87]
	v_mfma_f32_16x16x32_bf16 v[76:79], v[168:171], v[230:233], v[76:79]
	v_mfma_f32_16x16x32_bf16 v[68:71], v[176:179], v[230:233], v[68:71]
	v_mfma_f32_16x16x32_bf16 v[120:123], v[180:183], v[202:205], v[120:123]
	v_mfma_f32_16x16x32_bf16 v[112:115], v[188:191], v[202:205], v[112:115]
	v_mfma_f32_16x16x32_bf16 v[104:107], v[180:183], v[210:213], v[104:107]
	v_mfma_f32_16x16x32_bf16 v[96:99], v[188:191], v[210:213], v[96:99]
	v_mfma_f32_16x16x32_bf16 v[88:91], v[180:183], v[218:221], v[88:91]
	v_mfma_f32_16x16x32_bf16 v[80:83], v[188:191], v[218:221], v[80:83]
	v_mfma_f32_16x16x32_bf16 v[72:75], v[180:183], v[226:229], v[72:75]
	v_mfma_f32_16x16x32_bf16 v[64:67], v[188:191], v[226:229], v[64:67]
	v_mfma_f32_16x16x32_bf16 v[120:123], v[184:187], v[206:209], v[120:123]
	v_mfma_f32_16x16x32_bf16 v[112:115], v[198:201], v[206:209], v[112:115]
	v_mfma_f32_16x16x32_bf16 v[104:107], v[184:187], v[214:217], v[104:107]
	v_mfma_f32_16x16x32_bf16 v[96:99], v[198:201], v[214:217], v[96:99]
	v_mfma_f32_16x16x32_bf16 v[88:91], v[184:187], v[222:225], v[88:91]
	v_mfma_f32_16x16x32_bf16 v[80:83], v[198:201], v[222:225], v[80:83]
	v_mfma_f32_16x16x32_bf16 v[72:75], v[184:187], v[230:233], v[72:75]
	v_mfma_f32_16x16x32_bf16 v[64:67], v[198:201], v[230:233], v[64:67]
	s_barrier
	s_add_i32 s6, s59, s26
	s_mov_b32 m0, s6
	ds_read_b128 v[202:205], v156 offset:16384
	ds_read_b128 v[206:209], v156 offset:17408
	ds_read_b128 v[210:213], v156 offset:18432
	ds_read_b128 v[214:217], v156 offset:19456
	ds_read_b128 v[218:221], v156 offset:20480
	ds_read_b128 v[222:225], v156 offset:21504
	ds_read_b128 v[226:229], v156 offset:22528
	ds_read_b128 v[230:233], v156 offset:23552
	global_load_lds_dwordx4 v132, s[52:53]
	s_add_i32 m0, s6, 0x2000
	s_add_u32 s6, s52, 0x40000
	s_addc_u32 s7, s53, 0
	s_add_i32 s73, s60, s26
	global_load_lds_dwordx4 v128, s[52:53]
	s_mov_b32 m0, s73
	global_load_lds_dwordx4 v132, s[6:7]
	s_add_i32 m0, s73, 0x2000
	s_nop 0
	global_load_lds_dwordx4 v128, s[6:7]
	s_mov_b32 m0, s27
	s_nop 0
	global_load_lds_dwordx4 v134, s[54:55]
	s_mov_b32 m0, s42
	s_nop 0
	global_load_lds_dwordx4 v130, s[54:55]
	s_waitcnt vmcnt(8)
	s_waitcnt lgkmcnt(0)
	s_barrier
	s_waitcnt lgkmcnt(0)
	v_mfma_f32_16x16x32_bf16 v[60:63], v[144:147], v[202:205], v[60:63]
	v_mfma_f32_16x16x32_bf16 v[52:55], v[172:175], v[202:205], v[52:55]
	v_mfma_f32_16x16x32_bf16 v[44:47], v[144:147], v[210:213], v[44:47]
	v_mfma_f32_16x16x32_bf16 v[36:39], v[172:175], v[210:213], v[36:39]
	v_mfma_f32_16x16x32_bf16 v[28:31], v[144:147], v[218:221], v[28:31]
	v_mfma_f32_16x16x32_bf16 v[20:23], v[172:175], v[218:221], v[20:23]
	v_mfma_f32_16x16x32_bf16 v[12:15], v[144:147], v[226:229], v[12:15]
	v_mfma_f32_16x16x32_bf16 v[4:7], v[172:175], v[226:229], v[4:7]
	v_mfma_f32_16x16x32_bf16 v[60:63], v[168:171], v[206:209], v[60:63]
	v_mfma_f32_16x16x32_bf16 v[52:55], v[176:179], v[206:209], v[52:55]
	v_mfma_f32_16x16x32_bf16 v[44:47], v[168:171], v[214:217], v[44:47]
	v_mfma_f32_16x16x32_bf16 v[36:39], v[176:179], v[214:217], v[36:39]
	v_mfma_f32_16x16x32_bf16 v[28:31], v[168:171], v[222:225], v[28:31]
	v_mfma_f32_16x16x32_bf16 v[20:23], v[176:179], v[222:225], v[20:23]
	v_mfma_f32_16x16x32_bf16 v[12:15], v[168:171], v[230:233], v[12:15]
	v_mfma_f32_16x16x32_bf16 v[4:7], v[176:179], v[230:233], v[4:7]
	v_mfma_f32_16x16x32_bf16 v[56:59], v[180:183], v[202:205], v[56:59]
	v_mfma_f32_16x16x32_bf16 v[48:51], v[188:191], v[202:205], v[48:51]
	v_mfma_f32_16x16x32_bf16 v[40:43], v[180:183], v[210:213], v[40:43]
	v_mfma_f32_16x16x32_bf16 v[32:35], v[188:191], v[210:213], v[32:35]
	v_mfma_f32_16x16x32_bf16 v[24:27], v[180:183], v[218:221], v[24:27]
	v_mfma_f32_16x16x32_bf16 v[16:19], v[188:191], v[218:221], v[16:19]
	v_mfma_f32_16x16x32_bf16 v[8:11], v[180:183], v[226:229], v[8:11]
	v_mfma_f32_16x16x32_bf16 v[0:3], v[188:191], v[226:229], v[0:3]
	v_mfma_f32_16x16x32_bf16 v[56:59], v[184:187], v[206:209], v[56:59]
	v_mfma_f32_16x16x32_bf16 v[48:51], v[198:201], v[206:209], v[48:51]
	v_mfma_f32_16x16x32_bf16 v[40:43], v[184:187], v[214:217], v[40:43]
	v_mfma_f32_16x16x32_bf16 v[32:35], v[198:201], v[214:217], v[32:35]
	v_mfma_f32_16x16x32_bf16 v[24:27], v[184:187], v[222:225], v[24:27]
	v_mfma_f32_16x16x32_bf16 v[16:19], v[198:201], v[222:225], v[16:19]
	v_mfma_f32_16x16x32_bf16 v[8:11], v[184:187], v[230:233], v[8:11]
	v_mfma_f32_16x16x32_bf16 v[0:3], v[198:201], v[230:233], v[0:3]
	s_barrier
; #define PG8_STAGE(bufoff, gbase, voff) do { _Pragma("unroll") for (int _i = 0; _i < 2; ++_i) \
;         __builtin_amdgcn_global_load_lds((const unsigned*)((const char*)(gbase) + (voff)[_i]), (PG8_LAS unsigned*)(lds + (bufoff) + ldsw + _i * 8192), 16, 0, 0); } while (0)
; #define PG8_LDA(dst, b, h) do { _Pragma("unroll") for (int m = 0; m < 4; ++m) _Pragma("unroll") for (int k = 0; k < 2; ++k) dst[m][k] = *(const PG8_LAS bf16x8*)(lds + PG8_SA(b, h) + aoff + m * 2048 + k * 1024); } while (0)
; #define PG8_LDB(dst, b, h) do { _Pragma("unroll") for (int n = 0; n < 2; ++n) _Pragma("unroll") for (int k = 0; k < 2; ++k) dst[n][k] = *(const PG8_LAS bf16x8*)(lds + PG8_SB(b, h) + boff + n * 2048 + k * 1024); } while (0)
; #define PG8_MMA(ai, bj, At, Bt) do { __builtin_amdgcn_s_setprio(1); _Pragma("unroll") for (int m = 0; m < 4; ++m) _Pragma("unroll") for (int n = 0; n < 2; ++n) _Pragma("unroll") for (int k = 0; k < 2; ++k) \
;         acc[ai][bj][m][n] = __builtin_amdgcn_mfma_f32_16x16x32_bf16(Bt[n][k], At[m][k], acc[ai][bj][m][n], 0, 0, 0); __builtin_amdgcn_s_setprio(0); } while (0)
; #define PG8_WAIT_V(n) asm volatile("s_waitcnt vmcnt(" #n ")" ::: "memory")
; #define PG8_WAIT_L(n) asm volatile("s_waitcnt lgkmcnt(" #n ")" ::: "memory")
; #define PG8_BAR __builtin_amdgcn_s_barrier()
; #define PG8_SCHED __builtin_amdgcn_sched_barrier(0)
; template <class Epi, class Sched, bool ALIGN_EPI = false, bool SP2 = false>
; __device__ __forceinline__ void gemm_phase(PG8_LAS unsigned char* lds, const Gemm g, const Sched& S, const Epi& E) {
;     ...
;             PG8_LDB(B0, 1, 0); PG8_LDB(B1, 1, 1); PG8_SCHED; PG8_LDA(At, 1, 0); PG8_STAGE(PG8_SA(0, 1), a2 + hstep, voffA);
;             PG8_WAIT_V(8); PG8_WAIT_L(0); PG8_BAR; PG8_MMA(0, 0, At, B0); PG8_MMA(0, 1, At, B1); PG8_BAR; PG8_SCHED;
;             PG8_LDA(At, 1, 1); PG8_STAGE(PG8_SB(1, 0), b3, voffB); PG8_STAGE(PG8_SB(1, 1), b3 + hstep, voffB); PG8_STAGE(PG8_SA(1, 0), a3, voffA);
;             PG8_WAIT_V(8); PG8_WAIT_L(0); PG8_BAR; PG8_MMA(1, 0, At, B0); PG8_MMA(1, 1, At, B1); PG8_BAR; PG8_SCHED;
	s_add_i32 s73, 0, 0x18000
	v_add_u32_e32 v157, s73, v151
	s_add_i32 s76, 0, 0x1c000
	ds_read_b128 v[144:147], v157
	ds_read_b128 v[168:171], v157 offset:1024
	ds_read_b128 v[172:175], v157 offset:2048
	ds_read_b128 v[176:179], v157 offset:3072
	v_add_u32_e32 v157, s76, v151
	ds_read_b128 v[180:183], v157
	ds_read_b128 v[184:187], v157 offset:1024
	ds_read_b128 v[188:191], v157 offset:2048
	ds_read_b128 v[198:201], v157 offset:3072
	s_add_u32 s6, s54, 0x40000
	s_addc_u32 s7, s55, 0
	s_mov_b32 m0, s43
	ds_read_b128 v[202:205], v156 offset:32768
	ds_read_b128 v[206:209], v156 offset:33792
	ds_read_b128 v[210:213], v156 offset:34816
	ds_read_b128 v[214:217], v156 offset:35840
	ds_read_b128 v[218:221], v156 offset:36864
	ds_read_b128 v[222:225], v156 offset:37888
	ds_read_b128 v[226:229], v156 offset:38912
	ds_read_b128 v[230:233], v156 offset:39936
	global_load_lds_dwordx4 v134, s[6:7]
	s_mov_b32 m0, s56
	s_nop 0
	global_load_lds_dwordx4 v130, s[6:7]
	s_waitcnt vmcnt(8)
	s_waitcnt lgkmcnt(0)
	s_barrier
	s_waitcnt lgkmcnt(0)
	v_mfma_f32_16x16x32_bf16 v[124:127], v[144:147], v[202:205], v[124:127]
	v_mfma_f32_16x16x32_bf16 v[116:119], v[172:175], v[202:205], v[116:119]
	v_mfma_f32_16x16x32_bf16 v[108:111], v[144:147], v[210:213], v[108:111]
	v_mfma_f32_16x16x32_bf16 v[100:103], v[172:175], v[210:213], v[100:103]
	v_mfma_f32_16x16x32_bf16 v[92:95], v[144:147], v[218:221], v[92:95]
	v_mfma_f32_16x16x32_bf16 v[84:87], v[172:175], v[218:221], v[84:87]
	v_mfma_f32_16x16x32_bf16 v[76:79], v[144:147], v[226:229], v[76:79]
	v_mfma_f32_16x16x32_bf16 v[68:71], v[172:175], v[226:229], v[68:71]
	v_mfma_f32_16x16x32_bf16 v[124:127], v[168:171], v[206:209], v[124:127]
	v_mfma_f32_16x16x32_bf16 v[116:119], v[176:179], v[206:209], v[116:119]
	v_mfma_f32_16x16x32_bf16 v[108:111], v[168:171], v[214:217], v[108:111]
	v_mfma_f32_16x16x32_bf16 v[100:103], v[176:179], v[214:217], v[100:103]
	v_mfma_f32_16x16x32_bf16 v[92:95], v[168:171], v[222:225], v[92:95]
	v_mfma_f32_16x16x32_bf16 v[84:87], v[176:179], v[222:225], v[84:87]
	v_mfma_f32_16x16x32_bf16 v[76:79], v[168:171], v[230:233], v[76:79]
	v_mfma_f32_16x16x32_bf16 v[68:71], v[176:179], v[230:233], v[68:71]
	v_mfma_f32_16x16x32_bf16 v[120:123], v[180:183], v[202:205], v[120:123]
	v_mfma_f32_16x16x32_bf16 v[112:115], v[188:191], v[202:205], v[112:115]
	v_mfma_f32_16x16x32_bf16 v[104:107], v[180:183], v[210:213], v[104:107]
	v_mfma_f32_16x16x32_bf16 v[96:99], v[188:191], v[210:213], v[96:99]
	v_mfma_f32_16x16x32_bf16 v[88:91], v[180:183], v[218:221], v[88:91]
	v_mfma_f32_16x16x32_bf16 v[80:83], v[188:191], v[218:221], v[80:83]
	v_mfma_f32_16x16x32_bf16 v[72:75], v[180:183], v[226:229], v[72:75]
	v_mfma_f32_16x16x32_bf16 v[64:67], v[188:191], v[226:229], v[64:67]
	v_mfma_f32_16x16x32_bf16 v[120:123], v[184:187], v[206:209], v[120:123]
	v_mfma_f32_16x16x32_bf16 v[112:115], v[198:201], v[206:209], v[112:115]
	v_mfma_f32_16x16x32_bf16 v[104:107], v[184:187], v[214:217], v[104:107]
	v_mfma_f32_16x16x32_bf16 v[96:99], v[198:201], v[214:217], v[96:99]
	v_mfma_f32_16x16x32_bf16 v[88:91], v[184:187], v[222:225], v[88:91]
	v_mfma_f32_16x16x32_bf16 v[80:83], v[198:201], v[222:225], v[80:83]
	v_mfma_f32_16x16x32_bf16 v[72:75], v[184:187], v[230:233], v[72:75]
	v_mfma_f32_16x16x32_bf16 v[64:67], v[198:201], v[230:233], v[64:67]
	s_barrier
	s_add_i32 s6, s73, s26
	s_add_u32 s98, s52, 0x80
	s_addc_u32 s99, s53, 0
	s_add_u32 s100, s54, 0x80
	s_addc_u32 s101, s55, 0
	s_mov_b32 m0, s6
	ds_read_b128 v[202:205], v156 offset:49152
	ds_read_b128 v[206:209], v156 offset:50176
	ds_read_b128 v[210:213], v156 offset:51200
	ds_read_b128 v[214:217], v156 offset:52224
	ds_read_b128 v[218:221], v156 offset:53248
	ds_read_b128 v[222:225], v156 offset:54272
	ds_read_b128 v[226:229], v156 offset:55296
	ds_read_b128 v[230:233], v156 offset:56320
	global_load_lds_dwordx4 v132, s[98:99]
	s_add_i32 m0, s6, 0x2000
	s_add_u32 s6, s52, 0x40080
	s_addc_u32 s7, s53, 0
	s_add_i32 s52, s76, s26
	global_load_lds_dwordx4 v128, s[98:99]
	s_mov_b32 m0, s52
	s_nop 0
	global_load_lds_dwordx4 v132, s[6:7]
	s_add_i32 m0, s52, 0x2000
	s_nop 0
	global_load_lds_dwordx4 v128, s[6:7]
	s_mov_b32 m0, s57
	s_nop 0
	global_load_lds_dwordx4 v134, s[100:101]
	s_mov_b32 m0, s58
	s_nop 0
	global_load_lds_dwordx4 v130, s[100:101]
	s_waitcnt vmcnt(8)
	s_waitcnt lgkmcnt(0)
	s_barrier
	s_waitcnt lgkmcnt(0)
	v_mfma_f32_16x16x32_bf16 v[60:63], v[144:147], v[202:205], v[60:63]
	v_mfma_f32_16x16x32_bf16 v[52:55], v[172:175], v[202:205], v[52:55]
	v_mfma_f32_16x16x32_bf16 v[44:47], v[144:147], v[210:213], v[44:47]
	v_mfma_f32_16x16x32_bf16 v[36:39], v[172:175], v[210:213], v[36:39]
	v_mfma_f32_16x16x32_bf16 v[28:31], v[144:147], v[218:221], v[28:31]
	v_mfma_f32_16x16x32_bf16 v[20:23], v[172:175], v[218:221], v[20:23]
	v_mfma_f32_16x16x32_bf16 v[12:15], v[144:147], v[226:229], v[12:15]
	v_mfma_f32_16x16x32_bf16 v[4:7], v[172:175], v[226:229], v[4:7]
	v_mfma_f32_16x16x32_bf16 v[60:63], v[168:171], v[206:209], v[60:63]
	v_mfma_f32_16x16x32_bf16 v[52:55], v[176:179], v[206:209], v[52:55]
	v_mfma_f32_16x16x32_bf16 v[44:47], v[168:171], v[214:217], v[44:47]
	v_mfma_f32_16x16x32_bf16 v[36:39], v[176:179], v[214:217], v[36:39]
	v_mfma_f32_16x16x32_bf16 v[28:31], v[168:171], v[222:225], v[28:31]
	v_mfma_f32_16x16x32_bf16 v[20:23], v[176:179], v[222:225], v[20:23]
	v_mfma_f32_16x16x32_bf16 v[12:15], v[168:171], v[230:233], v[12:15]
	v_mfma_f32_16x16x32_bf16 v[4:7], v[176:179], v[230:233], v[4:7]
	v_mfma_f32_16x16x32_bf16 v[56:59], v[180:183], v[202:205], v[56:59]
	v_mfma_f32_16x16x32_bf16 v[48:51], v[188:191], v[202:205], v[48:51]
	v_mfma_f32_16x16x32_bf16 v[40:43], v[180:183], v[210:213], v[40:43]
	v_mfma_f32_16x16x32_bf16 v[32:35], v[188:191], v[210:213], v[32:35]
	v_mfma_f32_16x16x32_bf16 v[24:27], v[180:183], v[218:221], v[24:27]
	v_mfma_f32_16x16x32_bf16 v[16:19], v[188:191], v[218:221], v[16:19]
	v_mfma_f32_16x16x32_bf16 v[8:11], v[180:183], v[226:229], v[8:11]
	v_mfma_f32_16x16x32_bf16 v[0:3], v[188:191], v[226:229], v[0:3]
	v_mfma_f32_16x16x32_bf16 v[56:59], v[184:187], v[206:209], v[56:59]
	v_mfma_f32_16x16x32_bf16 v[48:51], v[198:201], v[206:209], v[48:51]
	v_mfma_f32_16x16x32_bf16 v[40:43], v[184:187], v[214:217], v[40:43]
	v_mfma_f32_16x16x32_bf16 v[32:35], v[198:201], v[214:217], v[32:35]
	v_mfma_f32_16x16x32_bf16 v[24:27], v[184:187], v[222:225], v[24:27]
	v_mfma_f32_16x16x32_bf16 v[16:19], v[198:201], v[222:225], v[16:19]
	v_mfma_f32_16x16x32_bf16 v[8:11], v[184:187], v[230:233], v[8:11]
	v_mfma_f32_16x16x32_bf16 v[0:3], v[198:201], v[230:233], v[0:3]
	s_barrier
	s_add_i32 s72, s72, 2
	s_add_u32 s50, s50, 0x100
	s_addc_u32 s51, s51, 0
	s_add_u32 s75, s75, 0x100
	s_addc_u32 s33, s33, 0
	s_cmp_gt_u32 s72, 13
	s_cbranch_scc0 .LBB0_1822
	v_readlane_b32 s74, v243, 57
	s_and_b64 vcc, exec, s[34:35]
	v_readlane_b32 s75, v243, 58
	s_cbranch_vccz .LBB0_1825
	s_barrier

; #define PG8_STAGE(bufoff, gbase, voff) do { _Pragma("unroll") for (int _i = 0; _i < 2; ++_i) \
;         __builtin_amdgcn_global_load_lds((const unsigned*)((const char*)(gbase) + (voff)[_i]), (PG8_LAS unsigned*)(lds + (bufoff) + ldsw + _i * 8192), 16, 0, 0); } while (0)
; #define PG8_LDA(dst, b, h) do { _Pragma("unroll") for (int m = 0; m < 4; ++m) _Pragma("unroll") for (int k = 0; k < 2; ++k) dst[m][k] = *(const PG8_LAS bf16x8*)(lds + PG8_SA(b, h) + aoff + m * 2048 + k * 1024); } while (0)
; #define PG8_LDB(dst, b, h) do { _Pragma("unroll") for (int n = 0; n < 2; ++n) _Pragma("unroll") for (int k = 0; k < 2; ++k) dst[n][k] = *(const PG8_LAS bf16x8*)(lds + PG8_SB(b, h) + boff + n * 2048 + k * 1024); } while (0)
; #define PG8_MMA(ai, bj, At, Bt) do { __builtin_amdgcn_s_setprio(1); _Pragma("unroll") for (int m = 0; m < 4; ++m) _Pragma("unroll") for (int n = 0; n < 2; ++n) _Pragma("unroll") for (int k = 0; k < 2; ++k) \
;         acc[ai][bj][m][n] = __builtin_amdgcn_mfma_f32_16x16x32_bf16(Bt[n][k], At[m][k], acc[ai][bj][m][n], 0, 0, 0); __builtin_amdgcn_s_setprio(0); } while (0)
; #define PG8_WAIT_V(n) asm volatile("s_waitcnt vmcnt(" #n ")" ::: "memory")
; #define PG8_WAIT_L(n) asm volatile("s_waitcnt lgkmcnt(" #n ")" ::: "memory")
; template <class Epi, class Sched, bool ALIGN_EPI = false, bool SP2 = false>
; __device__ __forceinline__ void gemm_phase(PG8_LAS unsigned char* lds, const Gemm g, const Sched& S, const Epi& E) {
;     ...
;             const bool last = (t == nt - 2);
;             const char* a1 = cA + (size_t)(t + 1) * kstep;
;             const char* a2 = last ? nA : cA + (size_t)(t + 2) * kstep; const char* b2 = last ? nB : cB + (size_t)(t + 2) * kstep;
;             const char* a3 = a2 + kstep; const char* b3 = b2 + kstep;
;             if (last && has_next) S.a_ready(nxt);
;             if constexpr (SP2) {
;             PG8_LDB(B0, 0, 0); PG8_LDB(B1, 0, 1); PG8_SCHED; PG8_LDA(At, 0, 0); PG8_STAGE(PG8_SA(1, 1), a1 + hstep, voffA);
;             PG8_WAIT_V(8); PG8_WAIT_L(0); PG8_BAR; PG8_MMA(0, 0, At, B0); PG8_MMA(0, 1, At, B1); PG8_BAR; PG8_SCHED;
;             PG8_LDA(At, 0, 1); PG8_STAGE(PG8_SB(0, 0), b2, voffB); PG8_STAGE(PG8_SB(0, 1), b2 + hstep, voffB); PG8_STAGE(PG8_SA(0, 0), a2, voffA);
;             PG8_WAIT_V(8); PG8_WAIT_L(0); PG8_BAR; PG8_MMA(1, 0, At, B0); PG8_MMA(1, 1, At, B1); PG8_BAR; PG8_SCHED;
.LBB0_1935:
	ds_read_b128 v[144:147], v153
	ds_read_b128 v[168:171], v153 offset:1024
	ds_read_b128 v[172:175], v153 offset:2048
	ds_read_b128 v[176:179], v153 offset:3072
	ds_read_b128 v[180:183], v154
	ds_read_b128 v[184:187], v154 offset:1024
	ds_read_b128 v[188:191], v154 offset:2048
	ds_read_b128 v[198:201], v154 offset:3072
	s_add_u32 s50, s48, 0x100
	s_addc_u32 s51, s49, 0
	s_cmp_eq_u32 s72, 40
	s_cselect_b32 s55, s41, s51
	s_cselect_b32 s54, s40, s50
	s_cselect_b32 s53, s47, s77
	s_cselect_b32 s52, s46, s33
	s_add_i32 m0, s58, 0xc000
	ds_read_b128 v[202:205], v155
	ds_read_b128 v[206:209], v155 offset:1024
	ds_read_b128 v[210:213], v155 offset:2048
	ds_read_b128 v[214:217], v155 offset:3072
	ds_read_b128 v[218:221], v155 offset:4096
	ds_read_b128 v[222:225], v155 offset:5120
	ds_read_b128 v[226:229], v155 offset:6144
	ds_read_b128 v[230:233], v155 offset:7168
	global_load_lds_dwordx4 v136, s[48:49]
	s_add_i32 m0, s58, 0xe000
	s_nop 0
	global_load_lds_dwordx4 v138, s[48:49]
	s_waitcnt vmcnt(8)
	s_waitcnt lgkmcnt(0)
	s_barrier
	s_waitcnt lgkmcnt(0)
	v_mfma_f32_16x16x32_bf16 v[124:127], v[144:147], v[202:205], v[124:127]
	v_mfma_f32_16x16x32_bf16 v[120:123], v[172:175], v[202:205], v[120:123]
	v_mfma_f32_16x16x32_bf16 v[108:111], v[144:147], v[210:213], v[108:111]
	v_mfma_f32_16x16x32_bf16 v[104:107], v[172:175], v[210:213], v[104:107]
	v_mfma_f32_16x16x32_bf16 v[92:95], v[144:147], v[218:221], v[92:95]
	v_mfma_f32_16x16x32_bf16 v[88:91], v[172:175], v[218:221], v[88:91]
	v_mfma_f32_16x16x32_bf16 v[76:79], v[144:147], v[226:229], v[76:79]
	v_mfma_f32_16x16x32_bf16 v[72:75], v[172:175], v[226:229], v[72:75]
	v_mfma_f32_16x16x32_bf16 v[124:127], v[168:171], v[206:209], v[124:127]
	v_mfma_f32_16x16x32_bf16 v[120:123], v[176:179], v[206:209], v[120:123]
	v_mfma_f32_16x16x32_bf16 v[108:111], v[168:171], v[214:217], v[108:111]
	v_mfma_f32_16x16x32_bf16 v[104:107], v[176:179], v[214:217], v[104:107]
	v_mfma_f32_16x16x32_bf16 v[92:95], v[168:171], v[222:225], v[92:95]
	v_mfma_f32_16x16x32_bf16 v[88:91], v[176:179], v[222:225], v[88:91]
	v_mfma_f32_16x16x32_bf16 v[76:79], v[168:171], v[230:233], v[76:79]
	v_mfma_f32_16x16x32_bf16 v[72:75], v[176:179], v[230:233], v[72:75]
	v_mfma_f32_16x16x32_bf16 v[116:119], v[180:183], v[202:205], v[116:119]
	v_mfma_f32_16x16x32_bf16 v[112:115], v[188:191], v[202:205], v[112:115]
	v_mfma_f32_16x16x32_bf16 v[100:103], v[180:183], v[210:213], v[100:103]
	v_mfma_f32_16x16x32_bf16 v[96:99], v[188:191], v[210:213], v[96:99]
	v_mfma_f32_16x16x32_bf16 v[84:87], v[180:183], v[218:221], v[84:87]
	v_mfma_f32_16x16x32_bf16 v[80:83], v[188:191], v[218:221], v[80:83]
	v_mfma_f32_16x16x32_bf16 v[68:71], v[180:183], v[226:229], v[68:71]
	v_mfma_f32_16x16x32_bf16 v[64:67], v[188:191], v[226:229], v[64:67]
	v_mfma_f32_16x16x32_bf16 v[116:119], v[184:187], v[206:209], v[116:119]
	v_mfma_f32_16x16x32_bf16 v[112:115], v[198:201], v[206:209], v[112:115]
	v_mfma_f32_16x16x32_bf16 v[100:103], v[184:187], v[214:217], v[100:103]
	v_mfma_f32_16x16x32_bf16 v[96:99], v[198:201], v[214:217], v[96:99]
	v_mfma_f32_16x16x32_bf16 v[84:87], v[184:187], v[222:225], v[84:87]
	v_mfma_f32_16x16x32_bf16 v[80:83], v[198:201], v[222:225], v[80:83]
	v_mfma_f32_16x16x32_bf16 v[68:71], v[184:187], v[230:233], v[68:71]
	v_mfma_f32_16x16x32_bf16 v[64:67], v[198:201], v[230:233], v[64:67]
	s_barrier
	s_add_i32 s6, s26, s57
	s_mov_b32 m0, s6
	ds_read_b128 v[202:205], v155 offset:16384
	ds_read_b128 v[206:209], v155 offset:17408
	ds_read_b128 v[210:213], v155 offset:18432
	ds_read_b128 v[214:217], v155 offset:19456
	ds_read_b128 v[218:221], v155 offset:20480
	ds_read_b128 v[222:225], v155 offset:21504
	ds_read_b128 v[226:229], v155 offset:22528
	ds_read_b128 v[230:233], v155 offset:23552
	global_load_lds_dwordx4 v130, s[52:53]
	s_add_i32 m0, s6, 0x2000
	s_add_u32 s6, s52, 0xb0000
	s_addc_u32 s7, s53, 0
	s_add_i32 s48, s74, s57
	global_load_lds_dwordx4 v134, s[52:53]
	s_mov_b32 m0, s48
	global_load_lds_dwordx4 v130, s[6:7]
	s_add_i32 m0, s48, 0x2000
	s_nop 0
	global_load_lds_dwordx4 v134, s[6:7]
	s_mov_b32 m0, s58
	s_nop 0
	global_load_lds_dwordx4 v128, s[54:55]
	s_mov_b32 m0, s59
	s_nop 0
	global_load_lds_dwordx4 v132, s[54:55]
	s_waitcnt vmcnt(8)
	s_waitcnt lgkmcnt(0)
	s_barrier
	s_waitcnt lgkmcnt(0)
	v_mfma_f32_16x16x32_bf16 v[60:63], v[144:147], v[202:205], v[60:63]
	v_mfma_f32_16x16x32_bf16 v[56:59], v[172:175], v[202:205], v[56:59]
	v_mfma_f32_16x16x32_bf16 v[44:47], v[144:147], v[210:213], v[44:47]
	v_mfma_f32_16x16x32_bf16 v[40:43], v[172:175], v[210:213], v[40:43]
	v_mfma_f32_16x16x32_bf16 v[28:31], v[144:147], v[218:221], v[28:31]
	v_mfma_f32_16x16x32_bf16 v[24:27], v[172:175], v[218:221], v[24:27]
	v_mfma_f32_16x16x32_bf16 v[12:15], v[144:147], v[226:229], v[12:15]
	v_mfma_f32_16x16x32_bf16 v[8:11], v[172:175], v[226:229], v[8:11]
	v_mfma_f32_16x16x32_bf16 v[60:63], v[168:171], v[206:209], v[60:63]
	v_mfma_f32_16x16x32_bf16 v[56:59], v[176:179], v[206:209], v[56:59]
	v_mfma_f32_16x16x32_bf16 v[44:47], v[168:171], v[214:217], v[44:47]
	v_mfma_f32_16x16x32_bf16 v[40:43], v[176:179], v[214:217], v[40:43]
	v_mfma_f32_16x16x32_bf16 v[28:31], v[168:171], v[222:225], v[28:31]
	v_mfma_f32_16x16x32_bf16 v[24:27], v[176:179], v[222:225], v[24:27]
	v_mfma_f32_16x16x32_bf16 v[12:15], v[168:171], v[230:233], v[12:15]
	v_mfma_f32_16x16x32_bf16 v[8:11], v[176:179], v[230:233], v[8:11]
	v_mfma_f32_16x16x32_bf16 v[52:55], v[180:183], v[202:205], v[52:55]
	v_mfma_f32_16x16x32_bf16 v[48:51], v[188:191], v[202:205], v[48:51]
	v_mfma_f32_16x16x32_bf16 v[36:39], v[180:183], v[210:213], v[36:39]
	v_mfma_f32_16x16x32_bf16 v[32:35], v[188:191], v[210:213], v[32:35]
	v_mfma_f32_16x16x32_bf16 v[20:23], v[180:183], v[218:221], v[20:23]
	v_mfma_f32_16x16x32_bf16 v[16:19], v[188:191], v[218:221], v[16:19]
	v_mfma_f32_16x16x32_bf16 v[4:7], v[180:183], v[226:229], v[4:7]
	v_mfma_f32_16x16x32_bf16 v[0:3], v[188:191], v[226:229], v[0:3]
	v_mfma_f32_16x16x32_bf16 v[52:55], v[184:187], v[206:209], v[52:55]
	v_mfma_f32_16x16x32_bf16 v[48:51], v[198:201], v[206:209], v[48:51]
	v_mfma_f32_16x16x32_bf16 v[36:39], v[184:187], v[214:217], v[36:39]
	v_mfma_f32_16x16x32_bf16 v[32:35], v[198:201], v[214:217], v[32:35]
	v_mfma_f32_16x16x32_bf16 v[20:23], v[184:187], v[222:225], v[20:23]
	v_mfma_f32_16x16x32_bf16 v[16:19], v[198:201], v[222:225], v[16:19]
	v_mfma_f32_16x16x32_bf16 v[4:7], v[184:187], v[230:233], v[4:7]
	v_mfma_f32_16x16x32_bf16 v[0:3], v[198:201], v[230:233], v[0:3]
	s_barrier
; #define PG8_STAGE(bufoff, gbase, voff) do { _Pragma("unroll") for (int _i = 0; _i < 2; ++_i) \
;         __builtin_amdgcn_global_load_lds((const unsigned*)((const char*)(gbase) + (voff)[_i]), (PG8_LAS unsigned*)(lds + (bufoff) + ldsw + _i * 8192), 16, 0, 0); } while (0)
; #define PG8_LDA(dst, b, h) do { _Pragma("unroll") for (int m = 0; m < 4; ++m) _Pragma("unroll") for (int k = 0; k < 2; ++k) dst[m][k] = *(const PG8_LAS bf16x8*)(lds + PG8_SA(b, h) + aoff + m * 2048 + k * 1024); } while (0)
; #define PG8_LDB(dst, b, h) do { _Pragma("unroll") for (int n = 0; n < 2; ++n) _Pragma("unroll") for (int k = 0; k < 2; ++k) dst[n][k] = *(const PG8_LAS bf16x8*)(lds + PG8_SB(b, h) + boff + n * 2048 + k * 1024); } while (0)
; #define PG8_MMA(ai, bj, At, Bt) do { __builtin_amdgcn_s_setprio(1); _Pragma("unroll") for (int m = 0; m < 4; ++m) _Pragma("unroll") for (int n = 0; n < 2; ++n) _Pragma("unroll") for (int k = 0; k < 2; ++k) \
;         acc[ai][bj][m][n] = __builtin_amdgcn_mfma_f32_16x16x32_bf16(Bt[n][k], At[m][k], acc[ai][bj][m][n], 0, 0, 0); __builtin_amdgcn_s_setprio(0); } while (0)
; #define PG8_WAIT_V(n) asm volatile("s_waitcnt vmcnt(" #n ")" ::: "memory")
; #define PG8_WAIT_L(n) asm volatile("s_waitcnt lgkmcnt(" #n ")" ::: "memory")
; #define PG8_BAR __builtin_amdgcn_s_barrier()
; #define PG8_SCHED __builtin_amdgcn_sched_barrier(0)
; template <class Epi, class Sched, bool ALIGN_EPI = false, bool SP2 = false>
; __device__ __forceinline__ void gemm_phase(PG8_LAS unsigned char* lds, const Gemm g, const Sched& S, const Epi& E) {
;     ...
;             PG8_LDB(B0, 1, 0); PG8_LDB(B1, 1, 1); PG8_SCHED; PG8_LDA(At, 1, 0); PG8_STAGE(PG8_SA(0, 1), a2 + hstep, voffA);
;             PG8_WAIT_V(8); PG8_WAIT_L(0); PG8_BAR; PG8_MMA(0, 0, At, B0); PG8_MMA(0, 1, At, B1); PG8_BAR; PG8_SCHED;
;             PG8_LDA(At, 1, 1); PG8_STAGE(PG8_SB(1, 0), b3, voffB); PG8_STAGE(PG8_SB(1, 1), b3 + hstep, voffB); PG8_STAGE(PG8_SA(1, 0), a3, voffA);
;             PG8_WAIT_V(8); PG8_WAIT_L(0); PG8_BAR; PG8_MMA(1, 0, At, B0); PG8_MMA(1, 1, At, B1); PG8_BAR; PG8_SCHED;
	s_add_i32 s48, 0, 0x18000
	v_add_u32_e32 v157, s48, v151
	s_add_i32 s49, 0, 0x1c000
	ds_read_b128 v[144:147], v157
	ds_read_b128 v[168:171], v157 offset:1024
	ds_read_b128 v[172:175], v157 offset:2048
	ds_read_b128 v[176:179], v157 offset:3072
	v_add_u32_e32 v157, s49, v151
	ds_read_b128 v[180:183], v157
	ds_read_b128 v[184:187], v157 offset:1024
	ds_read_b128 v[188:191], v157 offset:2048
	ds_read_b128 v[198:201], v157 offset:3072
	s_add_u32 s6, s54, 0xb0000
	s_addc_u32 s7, s55, 0
	s_mov_b32 m0, s60
	ds_read_b128 v[202:205], v155 offset:32768
	ds_read_b128 v[206:209], v155 offset:33792
	ds_read_b128 v[210:213], v155 offset:34816
	ds_read_b128 v[214:217], v155 offset:35840
	ds_read_b128 v[218:221], v155 offset:36864
	ds_read_b128 v[222:225], v155 offset:37888
	ds_read_b128 v[226:229], v155 offset:38912
	ds_read_b128 v[230:233], v155 offset:39936
	global_load_lds_dwordx4 v128, s[6:7]
	s_mov_b32 m0, s61
	s_nop 0
	global_load_lds_dwordx4 v132, s[6:7]
	s_waitcnt vmcnt(8)
	s_waitcnt lgkmcnt(0)
	s_barrier
	s_waitcnt lgkmcnt(0)
	v_mfma_f32_16x16x32_bf16 v[124:127], v[144:147], v[202:205], v[124:127]
	v_mfma_f32_16x16x32_bf16 v[120:123], v[172:175], v[202:205], v[120:123]
	v_mfma_f32_16x16x32_bf16 v[108:111], v[144:147], v[210:213], v[108:111]
	v_mfma_f32_16x16x32_bf16 v[104:107], v[172:175], v[210:213], v[104:107]
	v_mfma_f32_16x16x32_bf16 v[92:95], v[144:147], v[218:221], v[92:95]
	v_mfma_f32_16x16x32_bf16 v[88:91], v[172:175], v[218:221], v[88:91]
	v_mfma_f32_16x16x32_bf16 v[76:79], v[144:147], v[226:229], v[76:79]
	v_mfma_f32_16x16x32_bf16 v[72:75], v[172:175], v[226:229], v[72:75]
	v_mfma_f32_16x16x32_bf16 v[124:127], v[168:171], v[206:209], v[124:127]
	v_mfma_f32_16x16x32_bf16 v[120:123], v[176:179], v[206:209], v[120:123]
	v_mfma_f32_16x16x32_bf16 v[108:111], v[168:171], v[214:217], v[108:111]
	v_mfma_f32_16x16x32_bf16 v[104:107], v[176:179], v[214:217], v[104:107]
	v_mfma_f32_16x16x32_bf16 v[92:95], v[168:171], v[222:225], v[92:95]
	v_mfma_f32_16x16x32_bf16 v[88:91], v[176:179], v[222:225], v[88:91]
	v_mfma_f32_16x16x32_bf16 v[76:79], v[168:171], v[230:233], v[76:79]
	v_mfma_f32_16x16x32_bf16 v[72:75], v[176:179], v[230:233], v[72:75]
	v_mfma_f32_16x16x32_bf16 v[116:119], v[180:183], v[202:205], v[116:119]
	v_mfma_f32_16x16x32_bf16 v[112:115], v[188:191], v[202:205], v[112:115]
	v_mfma_f32_16x16x32_bf16 v[100:103], v[180:183], v[210:213], v[100:103]
	v_mfma_f32_16x16x32_bf16 v[96:99], v[188:191], v[210:213], v[96:99]
	v_mfma_f32_16x16x32_bf16 v[84:87], v[180:183], v[218:221], v[84:87]
	v_mfma_f32_16x16x32_bf16 v[80:83], v[188:191], v[218:221], v[80:83]
	v_mfma_f32_16x16x32_bf16 v[68:71], v[180:183], v[226:229], v[68:71]
	v_mfma_f32_16x16x32_bf16 v[64:67], v[188:191], v[226:229], v[64:67]
	v_mfma_f32_16x16x32_bf16 v[116:119], v[184:187], v[206:209], v[116:119]
	v_mfma_f32_16x16x32_bf16 v[112:115], v[198:201], v[206:209], v[112:115]
	v_mfma_f32_16x16x32_bf16 v[100:103], v[184:187], v[214:217], v[100:103]
	v_mfma_f32_16x16x32_bf16 v[96:99], v[198:201], v[214:217], v[96:99]
	v_mfma_f32_16x16x32_bf16 v[84:87], v[184:187], v[222:225], v[84:87]
	v_mfma_f32_16x16x32_bf16 v[80:83], v[198:201], v[222:225], v[80:83]
	v_mfma_f32_16x16x32_bf16 v[68:71], v[184:187], v[230:233], v[68:71]
	v_mfma_f32_16x16x32_bf16 v[64:67], v[198:201], v[230:233], v[64:67]
	s_barrier
	s_add_i32 s6, s48, s57
	s_add_u32 s98, s52, 0x80
	s_addc_u32 s99, s53, 0
	s_add_u32 s100, s54, 0x80
	s_addc_u32 s101, s55, 0
	s_mov_b32 m0, s6
	ds_read_b128 v[202:205], v155 offset:49152
	ds_read_b128 v[206:209], v155 offset:50176
	ds_read_b128 v[210:213], v155 offset:51200
	ds_read_b128 v[214:217], v155 offset:52224
	ds_read_b128 v[218:221], v155 offset:53248
	ds_read_b128 v[222:225], v155 offset:54272
	ds_read_b128 v[226:229], v155 offset:55296
	ds_read_b128 v[230:233], v155 offset:56320
	global_load_lds_dwordx4 v130, s[98:99]
	s_add_i32 m0, s6, 0x2000
	s_add_u32 s6, s52, 0xb0080
	s_addc_u32 s7, s53, 0
	s_add_i32 s48, s49, s57
	global_load_lds_dwordx4 v134, s[98:99]
	s_mov_b32 m0, s48
	s_nop 0
	global_load_lds_dwordx4 v130, s[6:7]
	s_add_i32 m0, s48, 0x2000
	s_nop 0
	global_load_lds_dwordx4 v134, s[6:7]
	s_mov_b32 m0, s76
	s_nop 0
	global_load_lds_dwordx4 v128, s[100:101]
	s_mov_b32 m0, s4
	s_nop 0
	global_load_lds_dwordx4 v132, s[100:101]
	s_waitcnt vmcnt(8)
	s_waitcnt lgkmcnt(0)
	s_barrier
	s_waitcnt lgkmcnt(0)
	v_mfma_f32_16x16x32_bf16 v[60:63], v[144:147], v[202:205], v[60:63]
	v_mfma_f32_16x16x32_bf16 v[56:59], v[172:175], v[202:205], v[56:59]
	v_mfma_f32_16x16x32_bf16 v[44:47], v[144:147], v[210:213], v[44:47]
	v_mfma_f32_16x16x32_bf16 v[40:43], v[172:175], v[210:213], v[40:43]
	v_mfma_f32_16x16x32_bf16 v[28:31], v[144:147], v[218:221], v[28:31]
	v_mfma_f32_16x16x32_bf16 v[24:27], v[172:175], v[218:221], v[24:27]
	v_mfma_f32_16x16x32_bf16 v[12:15], v[144:147], v[226:229], v[12:15]
	v_mfma_f32_16x16x32_bf16 v[8:11], v[172:175], v[226:229], v[8:11]
	v_mfma_f32_16x16x32_bf16 v[60:63], v[168:171], v[206:209], v[60:63]
	v_mfma_f32_16x16x32_bf16 v[56:59], v[176:179], v[206:209], v[56:59]
	v_mfma_f32_16x16x32_bf16 v[44:47], v[168:171], v[214:217], v[44:47]
	v_mfma_f32_16x16x32_bf16 v[40:43], v[176:179], v[214:217], v[40:43]
	v_mfma_f32_16x16x32_bf16 v[28:31], v[168:171], v[222:225], v[28:31]
	v_mfma_f32_16x16x32_bf16 v[24:27], v[176:179], v[222:225], v[24:27]
	v_mfma_f32_16x16x32_bf16 v[12:15], v[168:171], v[230:233], v[12:15]
	v_mfma_f32_16x16x32_bf16 v[8:11], v[176:179], v[230:233], v[8:11]
	v_mfma_f32_16x16x32_bf16 v[52:55], v[180:183], v[202:205], v[52:55]
	v_mfma_f32_16x16x32_bf16 v[48:51], v[188:191], v[202:205], v[48:51]
	v_mfma_f32_16x16x32_bf16 v[36:39], v[180:183], v[210:213], v[36:39]
	v_mfma_f32_16x16x32_bf16 v[32:35], v[188:191], v[210:213], v[32:35]
	v_mfma_f32_16x16x32_bf16 v[20:23], v[180:183], v[218:221], v[20:23]
	v_mfma_f32_16x16x32_bf16 v[16:19], v[188:191], v[218:221], v[16:19]
	v_mfma_f32_16x16x32_bf16 v[4:7], v[180:183], v[226:229], v[4:7]
	v_mfma_f32_16x16x32_bf16 v[0:3], v[188:191], v[226:229], v[0:3]
	v_mfma_f32_16x16x32_bf16 v[52:55], v[184:187], v[206:209], v[52:55]
	v_mfma_f32_16x16x32_bf16 v[48:51], v[198:201], v[206:209], v[48:51]
	v_mfma_f32_16x16x32_bf16 v[36:39], v[184:187], v[214:217], v[36:39]
	v_mfma_f32_16x16x32_bf16 v[32:35], v[198:201], v[214:217], v[32:35]
	v_mfma_f32_16x16x32_bf16 v[20:23], v[184:187], v[222:225], v[20:23]
	v_mfma_f32_16x16x32_bf16 v[16:19], v[198:201], v[222:225], v[16:19]
	v_mfma_f32_16x16x32_bf16 v[4:7], v[184:187], v[230:233], v[4:7]
	v_mfma_f32_16x16x32_bf16 v[0:3], v[198:201], v[230:233], v[0:3]
	s_barrier
	s_add_i32 s72, s72, 2
	s_add_u32 s33, s33, 0x100
	s_addc_u32 s77, s77, 0
	s_cmp_gt_u32 s72, 41
	s_mov_b64 s[48:49], s[50:51]
	s_cbranch_scc0 .LBB0_1935
	s_and_b64 vcc, exec, s[38:39]
	s_cbranch_vccz .LBB0_1938
	s_barrier
